# previous but without the s_setprio 1/0 pairs around the MFMA blocks of the GEMM K-loops
# baseline (speedup 1.0000x reference)
.LBB0_287:
	ds_read_b128 v[160:163], v156
	ds_read_b128 v[164:167], v156 offset:1024
	ds_read_b128 v[168:171], v156 offset:2048
	ds_read_b128 v[172:175], v156 offset:3072
	ds_read_b128 v[176:179], v157
	ds_read_b128 v[180:183], v157 offset:1024
	ds_read_b128 v[184:187], v157 offset:2048
	ds_read_b128 v[188:191], v157 offset:3072
	s_add_u32 s28, s26, 0xfff00080
	s_addc_u32 s29, s27, -1
	s_cmp_eq_u32 s58, 60
	s_cselect_b32 s31, s21, s29
	s_cselect_b32 s30, s54, s28
	s_cselect_b32 s29, s19, s57
	s_cselect_b32 s28, s55, s56
	v_lshl_add_u64 v[192:193], s[26:27], 0, v[138:139]
	s_add_i32 m0, s17, 0xc000
	ds_read_b128 v[196:199], v158
	ds_read_b128 v[200:203], v158 offset:1024
	ds_read_b128 v[204:207], v158 offset:2048
	ds_read_b128 v[208:211], v158 offset:3072
	ds_read_b128 v[212:215], v158 offset:4096
	ds_read_b128 v[216:219], v158 offset:5120
	ds_read_b128 v[220:223], v158 offset:6144
	ds_read_b128 v[224:227], v158 offset:7168
	global_load_lds_dwordx4 v[192:193], off
	v_lshl_add_u64 v[192:193], s[26:27], 0, v[140:141]
	s_add_i32 m0, s17, 0xe000
	s_nop 0
	global_load_lds_dwordx4 v[192:193], off
	s_waitcnt vmcnt(8)
	s_waitcnt lgkmcnt(0)
	s_barrier
	v_mfma_f32_16x16x32_bf16 v[126:129], v[160:163], v[196:199], v[126:129]
	v_mfma_f32_16x16x32_bf16 v[122:125], v[168:171], v[196:199], v[122:125]
	v_mfma_f32_16x16x32_bf16 v[118:121], v[160:163], v[204:207], v[118:121]
	v_mfma_f32_16x16x32_bf16 v[114:117], v[168:171], v[204:207], v[114:117]
	v_mfma_f32_16x16x32_bf16 v[102:105], v[160:163], v[212:215], v[102:105]
	v_mfma_f32_16x16x32_bf16 v[98:101], v[168:171], v[212:215], v[98:101]
	v_mfma_f32_16x16x32_bf16 v[86:89], v[160:163], v[220:223], v[86:89]
	v_mfma_f32_16x16x32_bf16 v[82:85], v[168:171], v[220:223], v[82:85]
	v_mfma_f32_16x16x32_bf16 v[126:129], v[164:167], v[200:203], v[126:129]
	v_mfma_f32_16x16x32_bf16 v[122:125], v[172:175], v[200:203], v[122:125]
	v_mfma_f32_16x16x32_bf16 v[118:121], v[164:167], v[208:211], v[118:121]
	v_mfma_f32_16x16x32_bf16 v[114:117], v[172:175], v[208:211], v[114:117]
	v_mfma_f32_16x16x32_bf16 v[102:105], v[164:167], v[216:219], v[102:105]
	v_mfma_f32_16x16x32_bf16 v[98:101], v[172:175], v[216:219], v[98:101]
	v_mfma_f32_16x16x32_bf16 v[86:89], v[164:167], v[224:227], v[86:89]
	v_mfma_f32_16x16x32_bf16 v[82:85], v[172:175], v[224:227], v[82:85]
	v_mfma_f32_16x16x32_bf16 v[110:113], v[176:179], v[196:199], v[110:113]
	v_mfma_f32_16x16x32_bf16 v[106:109], v[184:187], v[196:199], v[106:109]
	v_mfma_f32_16x16x32_bf16 v[94:97], v[176:179], v[204:207], v[94:97]
	v_mfma_f32_16x16x32_bf16 v[90:93], v[184:187], v[204:207], v[90:93]
	v_mfma_f32_16x16x32_bf16 v[78:81], v[176:179], v[212:215], v[78:81]
	v_mfma_f32_16x16x32_bf16 v[74:77], v[184:187], v[212:215], v[74:77]
	v_mfma_f32_16x16x32_bf16 v[70:73], v[176:179], v[220:223], v[70:73]
	v_mfma_f32_16x16x32_bf16 v[66:69], v[184:187], v[220:223], v[66:69]
	v_mfma_f32_16x16x32_bf16 v[110:113], v[180:183], v[200:203], v[110:113]
	v_mfma_f32_16x16x32_bf16 v[106:109], v[188:191], v[200:203], v[106:109]
	v_mfma_f32_16x16x32_bf16 v[94:97], v[180:183], v[208:211], v[94:97]
	v_mfma_f32_16x16x32_bf16 v[90:93], v[188:191], v[208:211], v[90:93]
	v_mfma_f32_16x16x32_bf16 v[78:81], v[180:183], v[216:219], v[78:81]
	v_mfma_f32_16x16x32_bf16 v[74:77], v[188:191], v[216:219], v[74:77]
	v_mfma_f32_16x16x32_bf16 v[70:73], v[180:183], v[224:227], v[70:73]
	v_mfma_f32_16x16x32_bf16 v[66:69], v[188:191], v[224:227], v[66:69]
	s_barrier
	s_add_i32 s59, s50, s41
	v_lshl_add_u64 v[192:193], s[28:29], 0, v[134:135]
	s_mov_b32 m0, s59
	ds_read_b128 v[196:199], v158 offset:16384
	ds_read_b128 v[200:203], v158 offset:17408
	ds_read_b128 v[204:207], v158 offset:18432
	ds_read_b128 v[208:211], v158 offset:19456
	ds_read_b128 v[212:215], v158 offset:20480
	ds_read_b128 v[216:219], v158 offset:21504
	ds_read_b128 v[220:223], v158 offset:22528
	ds_read_b128 v[224:227], v158 offset:23552
	global_load_lds_dwordx4 v[192:193], off
	s_add_i32 m0, s59, 0x2000
	s_add_u32 s60, s28, 0x100000
	v_lshl_add_u64 v[228:229], s[28:29], 0, v[136:137]
	s_addc_u32 s61, s29, 0
	s_add_i32 s59, s51, s41
	global_load_lds_dwordx4 v[228:229], off
	v_lshl_add_u64 v[230:231], s[60:61], 0, v[134:135]
	s_mov_b32 m0, s59
	v_lshl_add_u64 v[232:233], s[30:31], 0, v[132:133]
	global_load_lds_dwordx4 v[230:231], off
	v_lshl_add_u64 v[230:231], s[60:61], 0, v[136:137]
	s_add_i32 m0, s59, 0x2000
	s_nop 0
	global_load_lds_dwordx4 v[230:231], off
	v_lshl_add_u64 v[230:231], s[30:31], 0, v[130:131]
	s_mov_b32 m0, s17
	s_nop 0
	global_load_lds_dwordx4 v[230:231], off
	s_mov_b32 m0, s42
	s_nop 0
	global_load_lds_dwordx4 v[232:233], off
	s_waitcnt vmcnt(8)
	s_waitcnt lgkmcnt(0)
	s_barrier
	v_mfma_f32_16x16x32_bf16 v[62:65], v[160:163], v[196:199], v[62:65]
	v_mfma_f32_16x16x32_bf16 v[58:61], v[168:171], v[196:199], v[58:61]
	v_mfma_f32_16x16x32_bf16 v[54:57], v[160:163], v[204:207], v[54:57]
	v_mfma_f32_16x16x32_bf16 v[50:53], v[168:171], v[204:207], v[50:53]
	v_mfma_f32_16x16x32_bf16 v[38:41], v[160:163], v[212:215], v[38:41]
	v_mfma_f32_16x16x32_bf16 v[34:37], v[168:171], v[212:215], v[34:37]
	v_mfma_f32_16x16x32_bf16 v[22:25], v[160:163], v[220:223], v[22:25]
	v_mfma_f32_16x16x32_bf16 v[18:21], v[168:171], v[220:223], v[18:21]
	v_mfma_f32_16x16x32_bf16 v[62:65], v[164:167], v[200:203], v[62:65]
	v_mfma_f32_16x16x32_bf16 v[58:61], v[172:175], v[200:203], v[58:61]
	v_mfma_f32_16x16x32_bf16 v[54:57], v[164:167], v[208:211], v[54:57]
	v_mfma_f32_16x16x32_bf16 v[50:53], v[172:175], v[208:211], v[50:53]
	v_mfma_f32_16x16x32_bf16 v[38:41], v[164:167], v[216:219], v[38:41]
	v_mfma_f32_16x16x32_bf16 v[34:37], v[172:175], v[216:219], v[34:37]
	v_mfma_f32_16x16x32_bf16 v[22:25], v[164:167], v[224:227], v[22:25]
	v_mfma_f32_16x16x32_bf16 v[18:21], v[172:175], v[224:227], v[18:21]
	v_mfma_f32_16x16x32_bf16 v[46:49], v[176:179], v[196:199], v[46:49]
	v_mfma_f32_16x16x32_bf16 v[42:45], v[184:187], v[196:199], v[42:45]
	v_mfma_f32_16x16x32_bf16 v[30:33], v[176:179], v[204:207], v[30:33]
	v_mfma_f32_16x16x32_bf16 v[26:29], v[184:187], v[204:207], v[26:29]
	v_mfma_f32_16x16x32_bf16 v[14:17], v[176:179], v[212:215], v[14:17]
	v_mfma_f32_16x16x32_bf16 v[10:13], v[184:187], v[212:215], v[10:13]
	v_mfma_f32_16x16x32_bf16 v[6:9], v[176:179], v[220:223], v[6:9]
	v_mfma_f32_16x16x32_bf16 v[2:5], v[184:187], v[220:223], v[2:5]
	v_mfma_f32_16x16x32_bf16 v[46:49], v[180:183], v[200:203], v[46:49]
	v_mfma_f32_16x16x32_bf16 v[42:45], v[188:191], v[200:203], v[42:45]
	v_mfma_f32_16x16x32_bf16 v[30:33], v[180:183], v[208:211], v[30:33]
	v_mfma_f32_16x16x32_bf16 v[26:29], v[188:191], v[208:211], v[26:29]
	v_mfma_f32_16x16x32_bf16 v[14:17], v[180:183], v[216:219], v[14:17]
	v_mfma_f32_16x16x32_bf16 v[10:13], v[188:191], v[216:219], v[10:13]
	v_mfma_f32_16x16x32_bf16 v[6:9], v[180:183], v[224:227], v[6:9]
	v_mfma_f32_16x16x32_bf16 v[2:5], v[188:191], v[224:227], v[2:5]
	s_barrier
	s_add_i32 s59, 0, 0x18000
	v_add_u32_e32 v159, s59, v154
	s_add_i32 s60, 0, 0x1c000
	ds_read_b128 v[160:163], v159
	ds_read_b128 v[164:167], v159 offset:1024
	ds_read_b128 v[168:171], v159 offset:2048
	ds_read_b128 v[172:175], v159 offset:3072
	v_add_u32_e32 v159, s60, v154
	ds_read_b128 v[176:179], v159
	ds_read_b128 v[180:183], v159 offset:1024
	ds_read_b128 v[184:187], v159 offset:2048
	ds_read_b128 v[188:191], v159 offset:3072
	s_add_u32 s30, s30, 0x100000
	s_addc_u32 s31, s31, 0
	s_mov_b32 m0, s43
	v_lshl_add_u64 v[234:235], s[30:31], 0, v[130:131]
	ds_read_b128 v[196:199], v158 offset:32768
	ds_read_b128 v[200:203], v158 offset:33792
	ds_read_b128 v[204:207], v158 offset:34816
	ds_read_b128 v[208:211], v158 offset:35840
	ds_read_b128 v[212:215], v158 offset:36864
	ds_read_b128 v[216:219], v158 offset:37888
	ds_read_b128 v[220:223], v158 offset:38912
	ds_read_b128 v[224:227], v158 offset:39936
	global_load_lds_dwordx4 v[234:235], off
	v_lshl_add_u64 v[234:235], s[30:31], 0, v[132:133]
	s_mov_b32 m0, s45
	s_nop 0
	global_load_lds_dwordx4 v[234:235], off
	s_waitcnt vmcnt(8)
	s_waitcnt lgkmcnt(0)
	s_barrier
	v_mfma_f32_16x16x32_bf16 v[126:129], v[160:163], v[196:199], v[126:129]
	v_mfma_f32_16x16x32_bf16 v[122:125], v[168:171], v[196:199], v[122:125]
	v_mfma_f32_16x16x32_bf16 v[118:121], v[160:163], v[204:207], v[118:121]
	v_mfma_f32_16x16x32_bf16 v[114:117], v[168:171], v[204:207], v[114:117]
	v_mfma_f32_16x16x32_bf16 v[102:105], v[160:163], v[212:215], v[102:105]
	v_mfma_f32_16x16x32_bf16 v[98:101], v[168:171], v[212:215], v[98:101]
	v_mfma_f32_16x16x32_bf16 v[86:89], v[160:163], v[220:223], v[86:89]
	v_mfma_f32_16x16x32_bf16 v[82:85], v[168:171], v[220:223], v[82:85]
	v_mfma_f32_16x16x32_bf16 v[126:129], v[164:167], v[200:203], v[126:129]
	v_mfma_f32_16x16x32_bf16 v[122:125], v[172:175], v[200:203], v[122:125]
	v_mfma_f32_16x16x32_bf16 v[118:121], v[164:167], v[208:211], v[118:121]
	v_mfma_f32_16x16x32_bf16 v[114:117], v[172:175], v[208:211], v[114:117]
	v_mfma_f32_16x16x32_bf16 v[102:105], v[164:167], v[216:219], v[102:105]
	v_mfma_f32_16x16x32_bf16 v[98:101], v[172:175], v[216:219], v[98:101]
	v_mfma_f32_16x16x32_bf16 v[86:89], v[164:167], v[224:227], v[86:89]
	v_mfma_f32_16x16x32_bf16 v[82:85], v[172:175], v[224:227], v[82:85]
	v_mfma_f32_16x16x32_bf16 v[110:113], v[176:179], v[196:199], v[110:113]
	v_mfma_f32_16x16x32_bf16 v[106:109], v[184:187], v[196:199], v[106:109]
	v_mfma_f32_16x16x32_bf16 v[94:97], v[176:179], v[204:207], v[94:97]
	v_mfma_f32_16x16x32_bf16 v[90:93], v[184:187], v[204:207], v[90:93]
	v_mfma_f32_16x16x32_bf16 v[78:81], v[176:179], v[212:215], v[78:81]
	v_mfma_f32_16x16x32_bf16 v[74:77], v[184:187], v[212:215], v[74:77]
	v_mfma_f32_16x16x32_bf16 v[70:73], v[176:179], v[220:223], v[70:73]
	v_mfma_f32_16x16x32_bf16 v[66:69], v[184:187], v[220:223], v[66:69]
	v_mfma_f32_16x16x32_bf16 v[110:113], v[180:183], v[200:203], v[110:113]
	v_mfma_f32_16x16x32_bf16 v[106:109], v[188:191], v[200:203], v[106:109]
	v_mfma_f32_16x16x32_bf16 v[94:97], v[180:183], v[208:211], v[94:97]
	v_mfma_f32_16x16x32_bf16 v[90:93], v[188:191], v[208:211], v[90:93]
	v_mfma_f32_16x16x32_bf16 v[78:81], v[180:183], v[216:219], v[78:81]
	v_mfma_f32_16x16x32_bf16 v[74:77], v[188:191], v[216:219], v[74:77]
	v_mfma_f32_16x16x32_bf16 v[70:73], v[180:183], v[224:227], v[70:73]
	v_mfma_f32_16x16x32_bf16 v[66:69], v[188:191], v[224:227], v[66:69]
	s_barrier
	s_add_i32 s30, s59, s41
	v_lshl_add_u64 v[192:193], v[192:193], 0, s[12:13]
	s_mov_b32 m0, s30
	ds_read_b128 v[196:199], v158 offset:49152
	ds_read_b128 v[200:203], v158 offset:50176
	ds_read_b128 v[204:207], v158 offset:51200
	ds_read_b128 v[208:211], v158 offset:52224
	ds_read_b128 v[212:215], v158 offset:53248
	ds_read_b128 v[216:219], v158 offset:54272
	ds_read_b128 v[220:223], v158 offset:55296
	ds_read_b128 v[224:227], v158 offset:56320
	global_load_lds_dwordx4 v[192:193], off
	s_add_i32 m0, s30, 0x2000
	s_add_u32 s28, s28, 0x100080
	v_lshl_add_u64 v[192:193], v[228:229], 0, s[12:13]
	s_addc_u32 s29, s29, 0
	s_add_i32 s30, s60, s41
	global_load_lds_dwordx4 v[192:193], off
	v_lshl_add_u64 v[192:193], s[28:29], 0, v[134:135]
	s_mov_b32 m0, s30
	s_nop 0
	global_load_lds_dwordx4 v[192:193], off
	v_lshl_add_u64 v[192:193], s[28:29], 0, v[136:137]
	s_add_i32 m0, s30, 0x2000
	s_nop 0
	global_load_lds_dwordx4 v[192:193], off
	v_lshl_add_u64 v[192:193], v[230:231], 0, s[12:13]
	s_mov_b32 m0, s47
	s_nop 0
	global_load_lds_dwordx4 v[192:193], off
	v_lshl_add_u64 v[192:193], v[232:233], 0, s[12:13]
	s_mov_b32 m0, s48
	s_nop 0
	global_load_lds_dwordx4 v[192:193], off
	s_nop 0
	s_waitcnt vmcnt(8)
	s_waitcnt lgkmcnt(0)
	s_barrier
	v_mfma_f32_16x16x32_bf16 v[62:65], v[160:163], v[196:199], v[62:65]
	v_mfma_f32_16x16x32_bf16 v[58:61], v[168:171], v[196:199], v[58:61]
	v_mfma_f32_16x16x32_bf16 v[54:57], v[160:163], v[204:207], v[54:57]
	v_mfma_f32_16x16x32_bf16 v[50:53], v[168:171], v[204:207], v[50:53]
	v_mfma_f32_16x16x32_bf16 v[38:41], v[160:163], v[212:215], v[38:41]
	v_mfma_f32_16x16x32_bf16 v[34:37], v[168:171], v[212:215], v[34:37]
	v_mfma_f32_16x16x32_bf16 v[22:25], v[160:163], v[220:223], v[22:25]
	v_mfma_f32_16x16x32_bf16 v[18:21], v[168:171], v[220:223], v[18:21]
	v_mfma_f32_16x16x32_bf16 v[62:65], v[164:167], v[200:203], v[62:65]
	v_mfma_f32_16x16x32_bf16 v[58:61], v[172:175], v[200:203], v[58:61]
	v_mfma_f32_16x16x32_bf16 v[54:57], v[164:167], v[208:211], v[54:57]
	v_mfma_f32_16x16x32_bf16 v[50:53], v[172:175], v[208:211], v[50:53]
	v_mfma_f32_16x16x32_bf16 v[38:41], v[164:167], v[216:219], v[38:41]
	v_mfma_f32_16x16x32_bf16 v[34:37], v[172:175], v[216:219], v[34:37]
	v_mfma_f32_16x16x32_bf16 v[22:25], v[164:167], v[224:227], v[22:25]
	v_mfma_f32_16x16x32_bf16 v[18:21], v[172:175], v[224:227], v[18:21]
	v_mfma_f32_16x16x32_bf16 v[46:49], v[176:179], v[196:199], v[46:49]
	v_mfma_f32_16x16x32_bf16 v[42:45], v[184:187], v[196:199], v[42:45]
	v_mfma_f32_16x16x32_bf16 v[30:33], v[176:179], v[204:207], v[30:33]
	v_mfma_f32_16x16x32_bf16 v[26:29], v[184:187], v[204:207], v[26:29]
	v_mfma_f32_16x16x32_bf16 v[14:17], v[176:179], v[212:215], v[14:17]
	v_mfma_f32_16x16x32_bf16 v[10:13], v[184:187], v[212:215], v[10:13]
	v_mfma_f32_16x16x32_bf16 v[6:9], v[176:179], v[220:223], v[6:9]
	v_mfma_f32_16x16x32_bf16 v[2:5], v[184:187], v[220:223], v[2:5]
	v_mfma_f32_16x16x32_bf16 v[46:49], v[180:183], v[200:203], v[46:49]
	v_mfma_f32_16x16x32_bf16 v[42:45], v[188:191], v[200:203], v[42:45]
	v_mfma_f32_16x16x32_bf16 v[30:33], v[180:183], v[208:211], v[30:33]
	v_mfma_f32_16x16x32_bf16 v[26:29], v[188:191], v[208:211], v[26:29]
	v_mfma_f32_16x16x32_bf16 v[14:17], v[180:183], v[216:219], v[14:17]
	v_mfma_f32_16x16x32_bf16 v[10:13], v[188:191], v[216:219], v[10:13]
	v_mfma_f32_16x16x32_bf16 v[6:9], v[180:183], v[224:227], v[6:9]
	v_mfma_f32_16x16x32_bf16 v[2:5], v[188:191], v[224:227], v[2:5]
	s_barrier
	s_add_i32 s58, s58, 2
	s_add_u32 s26, s26, 0x100
	s_addc_u32 s27, s27, 0
	s_add_u32 s56, s56, 0x100
	s_addc_u32 s57, s57, 0
	s_cmp_gt_u32 s58, 61
	s_cbranch_scc0 .LBB0_287
	s_and_b64 vcc, exec, s[14:15]
	s_cbranch_vccz .LBB0_290
	s_barrier

.LBB0_311:
	ds_read_b128 v[152:155], v144
	ds_read_b128 v[156:159], v144 offset:1024
	ds_read_b128 v[160:163], v144 offset:2048
	ds_read_b128 v[164:167], v144 offset:3072
	ds_read_b128 v[168:171], v145
	ds_read_b128 v[172:175], v145 offset:1024
	ds_read_b128 v[176:179], v145 offset:2048
	ds_read_b128 v[180:183], v145 offset:3072
	s_add_u32 s42, s40, 0xfff00080
	s_addc_u32 s43, s41, -1
	s_cmp_eq_u32 s70, 60
	s_cselect_b32 s47, s27, s43
	s_cselect_b32 s46, s66, s42
	s_cselect_b32 s43, s25, s69
	s_cselect_b32 s42, s67, s68
	v_lshl_add_u64 v[192:193], s[40:41], 0, v[134:135]
	s_add_i32 m0, s29, 0xc000
	ds_read_b128 v[184:187], v151
	ds_read_b128 v[188:191], v151 offset:1024
	ds_read_b128 v[196:199], v151 offset:2048
	ds_read_b128 v[200:203], v151 offset:3072
	ds_read_b128 v[204:207], v151 offset:4096
	ds_read_b128 v[208:211], v151 offset:5120
	ds_read_b128 v[212:215], v151 offset:6144
	ds_read_b128 v[216:219], v151 offset:7168
	global_load_lds_dwordx4 v[192:193], off
	v_lshl_add_u64 v[192:193], s[40:41], 0, v[136:137]
	s_add_i32 m0, s29, 0xe000
	s_nop 0
	global_load_lds_dwordx4 v[192:193], off
	s_waitcnt vmcnt(8)
	s_waitcnt lgkmcnt(0)
	s_barrier
	v_mfma_f32_16x16x32_bf16 v[126:129], v[152:155], v[184:187], v[126:129]
	v_mfma_f32_16x16x32_bf16 v[122:125], v[160:163], v[184:187], v[122:125]
	v_mfma_f32_16x16x32_bf16 v[118:121], v[152:155], v[196:199], v[118:121]
	v_mfma_f32_16x16x32_bf16 v[110:113], v[160:163], v[196:199], v[110:113]
	v_mfma_f32_16x16x32_bf16 v[102:105], v[152:155], v[204:207], v[102:105]
	v_mfma_f32_16x16x32_bf16 v[94:97], v[160:163], v[204:207], v[94:97]
	v_mfma_f32_16x16x32_bf16 v[86:89], v[152:155], v[212:215], v[86:89]
	v_mfma_f32_16x16x32_bf16 v[78:81], v[160:163], v[212:215], v[78:81]
	v_mfma_f32_16x16x32_bf16 v[126:129], v[156:159], v[188:191], v[126:129]
	v_mfma_f32_16x16x32_bf16 v[122:125], v[164:167], v[188:191], v[122:125]
	v_mfma_f32_16x16x32_bf16 v[118:121], v[156:159], v[200:203], v[118:121]
	v_mfma_f32_16x16x32_bf16 v[110:113], v[164:167], v[200:203], v[110:113]
	v_mfma_f32_16x16x32_bf16 v[102:105], v[156:159], v[208:211], v[102:105]
	v_mfma_f32_16x16x32_bf16 v[94:97], v[164:167], v[208:211], v[94:97]
	v_mfma_f32_16x16x32_bf16 v[86:89], v[156:159], v[216:219], v[86:89]
	v_mfma_f32_16x16x32_bf16 v[78:81], v[164:167], v[216:219], v[78:81]
	v_mfma_f32_16x16x32_bf16 v[114:117], v[168:171], v[184:187], v[114:117]
	v_mfma_f32_16x16x32_bf16 v[106:109], v[176:179], v[184:187], v[106:109]
	v_mfma_f32_16x16x32_bf16 v[98:101], v[168:171], v[196:199], v[98:101]
	v_mfma_f32_16x16x32_bf16 v[90:93], v[176:179], v[196:199], v[90:93]
	v_mfma_f32_16x16x32_bf16 v[82:85], v[168:171], v[204:207], v[82:85]
	v_mfma_f32_16x16x32_bf16 v[74:77], v[176:179], v[204:207], v[74:77]
	v_mfma_f32_16x16x32_bf16 v[70:73], v[168:171], v[212:215], v[70:73]
	v_mfma_f32_16x16x32_bf16 v[66:69], v[176:179], v[212:215], v[66:69]
	v_mfma_f32_16x16x32_bf16 v[114:117], v[172:175], v[188:191], v[114:117]
	v_mfma_f32_16x16x32_bf16 v[106:109], v[180:183], v[188:191], v[106:109]
	v_mfma_f32_16x16x32_bf16 v[98:101], v[172:175], v[200:203], v[98:101]
	v_mfma_f32_16x16x32_bf16 v[90:93], v[180:183], v[200:203], v[90:93]
	v_mfma_f32_16x16x32_bf16 v[82:85], v[172:175], v[208:211], v[82:85]
	v_mfma_f32_16x16x32_bf16 v[74:77], v[180:183], v[208:211], v[74:77]
	v_mfma_f32_16x16x32_bf16 v[70:73], v[172:175], v[216:219], v[70:73]
	v_mfma_f32_16x16x32_bf16 v[66:69], v[180:183], v[216:219], v[66:69]
	s_barrier
	s_add_i32 s71, s62, s54
	v_lshl_add_u64 v[192:193], s[42:43], 0, v[130:131]
	s_mov_b32 m0, s71
	ds_read_b128 v[184:187], v151 offset:16384
	ds_read_b128 v[188:191], v151 offset:17408
	ds_read_b128 v[196:199], v151 offset:18432
	ds_read_b128 v[200:203], v151 offset:19456
	ds_read_b128 v[204:207], v151 offset:20480
	ds_read_b128 v[208:211], v151 offset:21504
	ds_read_b128 v[212:215], v151 offset:22528
	ds_read_b128 v[216:219], v151 offset:23552
	global_load_lds_dwordx4 v[192:193], off
	s_add_i32 m0, s71, 0x2000
	s_add_u32 s72, s42, 0x100000
	v_lshl_add_u64 v[220:221], s[42:43], 0, v[132:133]
	s_addc_u32 s73, s43, 0
	s_add_i32 s71, s63, s54
	global_load_lds_dwordx4 v[220:221], off
	v_lshl_add_u64 v[222:223], s[72:73], 0, v[130:131]
	s_mov_b32 m0, s71
	v_lshl_add_u64 v[224:225], s[46:47], 0, v[132:133]
	global_load_lds_dwordx4 v[222:223], off
	v_lshl_add_u64 v[222:223], s[72:73], 0, v[132:133]
	s_add_i32 m0, s71, 0x2000
	s_nop 0
	global_load_lds_dwordx4 v[222:223], off
	v_lshl_add_u64 v[222:223], s[46:47], 0, v[130:131]
	s_mov_b32 m0, s29
	s_nop 0
	global_load_lds_dwordx4 v[222:223], off
	s_mov_b32 m0, s55
	s_nop 0
	global_load_lds_dwordx4 v[224:225], off
	s_waitcnt vmcnt(8)
	s_waitcnt lgkmcnt(0)
	s_barrier
	v_mfma_f32_16x16x32_bf16 v[62:65], v[152:155], v[184:187], v[62:65]
	v_mfma_f32_16x16x32_bf16 v[58:61], v[160:163], v[184:187], v[58:61]
	v_mfma_f32_16x16x32_bf16 v[54:57], v[152:155], v[196:199], v[54:57]
	v_mfma_f32_16x16x32_bf16 v[46:49], v[160:163], v[196:199], v[46:49]
	v_mfma_f32_16x16x32_bf16 v[38:41], v[152:155], v[204:207], v[38:41]
	v_mfma_f32_16x16x32_bf16 v[30:33], v[160:163], v[204:207], v[30:33]
	v_mfma_f32_16x16x32_bf16 v[22:25], v[152:155], v[212:215], v[22:25]
	v_mfma_f32_16x16x32_bf16 v[14:17], v[160:163], v[212:215], v[14:17]
	v_mfma_f32_16x16x32_bf16 v[62:65], v[156:159], v[188:191], v[62:65]
	v_mfma_f32_16x16x32_bf16 v[58:61], v[164:167], v[188:191], v[58:61]
	v_mfma_f32_16x16x32_bf16 v[54:57], v[156:159], v[200:203], v[54:57]
	v_mfma_f32_16x16x32_bf16 v[46:49], v[164:167], v[200:203], v[46:49]
	v_mfma_f32_16x16x32_bf16 v[38:41], v[156:159], v[208:211], v[38:41]
	v_mfma_f32_16x16x32_bf16 v[30:33], v[164:167], v[208:211], v[30:33]
	v_mfma_f32_16x16x32_bf16 v[22:25], v[156:159], v[216:219], v[22:25]
	v_mfma_f32_16x16x32_bf16 v[14:17], v[164:167], v[216:219], v[14:17]
	v_mfma_f32_16x16x32_bf16 v[50:53], v[168:171], v[184:187], v[50:53]
	v_mfma_f32_16x16x32_bf16 v[42:45], v[176:179], v[184:187], v[42:45]
	v_mfma_f32_16x16x32_bf16 v[34:37], v[168:171], v[196:199], v[34:37]
	v_mfma_f32_16x16x32_bf16 v[26:29], v[176:179], v[196:199], v[26:29]
	v_mfma_f32_16x16x32_bf16 v[18:21], v[168:171], v[204:207], v[18:21]
	v_mfma_f32_16x16x32_bf16 v[10:13], v[176:179], v[204:207], v[10:13]
	v_mfma_f32_16x16x32_bf16 v[6:9], v[168:171], v[212:215], v[6:9]
	v_mfma_f32_16x16x32_bf16 v[2:5], v[176:179], v[212:215], v[2:5]
	v_mfma_f32_16x16x32_bf16 v[50:53], v[172:175], v[188:191], v[50:53]
	v_mfma_f32_16x16x32_bf16 v[42:45], v[180:183], v[188:191], v[42:45]
	v_mfma_f32_16x16x32_bf16 v[34:37], v[172:175], v[200:203], v[34:37]
	v_mfma_f32_16x16x32_bf16 v[26:29], v[180:183], v[200:203], v[26:29]
	v_mfma_f32_16x16x32_bf16 v[18:21], v[172:175], v[208:211], v[18:21]
	v_mfma_f32_16x16x32_bf16 v[10:13], v[180:183], v[208:211], v[10:13]
	v_mfma_f32_16x16x32_bf16 v[6:9], v[172:175], v[216:219], v[6:9]
	v_mfma_f32_16x16x32_bf16 v[2:5], v[180:183], v[216:219], v[2:5]
	s_barrier
	s_add_i32 s71, 0, 0x18000
	s_add_i32 s72, 0, 0x1c000
	v_add_u32_e32 v164, s71, v142
	v_add_u32_e32 v180, s72, v142
	ds_read_b128 v[152:155], v164
	ds_read_b128 v[156:159], v164 offset:1024
	ds_read_b128 v[160:163], v164 offset:2048
	ds_read_b128 v[164:167], v164 offset:3072
	ds_read_b128 v[168:171], v180
	ds_read_b128 v[172:175], v180 offset:1024
	ds_read_b128 v[176:179], v180 offset:2048
	ds_read_b128 v[180:183], v180 offset:3072
	s_add_u32 s46, s46, 0x100000
	s_addc_u32 s47, s47, 0
	s_mov_b32 m0, s56
	v_lshl_add_u64 v[226:227], s[46:47], 0, v[130:131]
	ds_read_b128 v[184:187], v151 offset:32768
	ds_read_b128 v[188:191], v151 offset:33792
	ds_read_b128 v[196:199], v151 offset:34816
	ds_read_b128 v[200:203], v151 offset:35840
	ds_read_b128 v[204:207], v151 offset:36864
	ds_read_b128 v[208:211], v151 offset:37888
	ds_read_b128 v[212:215], v151 offset:38912
	ds_read_b128 v[216:219], v151 offset:39936
	global_load_lds_dwordx4 v[226:227], off
	v_lshl_add_u64 v[226:227], s[46:47], 0, v[132:133]
	s_mov_b32 m0, s57
	s_nop 0
	global_load_lds_dwordx4 v[226:227], off
	s_waitcnt vmcnt(8)
	s_waitcnt lgkmcnt(0)
	s_barrier
	v_mfma_f32_16x16x32_bf16 v[126:129], v[152:155], v[184:187], v[126:129]
	v_mfma_f32_16x16x32_bf16 v[122:125], v[160:163], v[184:187], v[122:125]
	v_mfma_f32_16x16x32_bf16 v[118:121], v[152:155], v[196:199], v[118:121]
	v_mfma_f32_16x16x32_bf16 v[110:113], v[160:163], v[196:199], v[110:113]
	v_mfma_f32_16x16x32_bf16 v[102:105], v[152:155], v[204:207], v[102:105]
	v_mfma_f32_16x16x32_bf16 v[94:97], v[160:163], v[204:207], v[94:97]
	v_mfma_f32_16x16x32_bf16 v[86:89], v[152:155], v[212:215], v[86:89]
	v_mfma_f32_16x16x32_bf16 v[78:81], v[160:163], v[212:215], v[78:81]
	v_mfma_f32_16x16x32_bf16 v[126:129], v[156:159], v[188:191], v[126:129]
	v_mfma_f32_16x16x32_bf16 v[122:125], v[164:167], v[188:191], v[122:125]
	v_mfma_f32_16x16x32_bf16 v[118:121], v[156:159], v[200:203], v[118:121]
	v_mfma_f32_16x16x32_bf16 v[110:113], v[164:167], v[200:203], v[110:113]
	v_mfma_f32_16x16x32_bf16 v[102:105], v[156:159], v[208:211], v[102:105]
	v_mfma_f32_16x16x32_bf16 v[94:97], v[164:167], v[208:211], v[94:97]
	v_mfma_f32_16x16x32_bf16 v[86:89], v[156:159], v[216:219], v[86:89]
	v_mfma_f32_16x16x32_bf16 v[78:81], v[164:167], v[216:219], v[78:81]
	v_mfma_f32_16x16x32_bf16 v[114:117], v[168:171], v[184:187], v[114:117]
	v_mfma_f32_16x16x32_bf16 v[106:109], v[176:179], v[184:187], v[106:109]
	v_mfma_f32_16x16x32_bf16 v[98:101], v[168:171], v[196:199], v[98:101]
	v_mfma_f32_16x16x32_bf16 v[90:93], v[176:179], v[196:199], v[90:93]
	v_mfma_f32_16x16x32_bf16 v[82:85], v[168:171], v[204:207], v[82:85]
	v_mfma_f32_16x16x32_bf16 v[74:77], v[176:179], v[204:207], v[74:77]
	v_mfma_f32_16x16x32_bf16 v[70:73], v[168:171], v[212:215], v[70:73]
	v_mfma_f32_16x16x32_bf16 v[66:69], v[176:179], v[212:215], v[66:69]
	v_mfma_f32_16x16x32_bf16 v[114:117], v[172:175], v[188:191], v[114:117]
	v_mfma_f32_16x16x32_bf16 v[106:109], v[180:183], v[188:191], v[106:109]
	v_mfma_f32_16x16x32_bf16 v[98:101], v[172:175], v[200:203], v[98:101]
	v_mfma_f32_16x16x32_bf16 v[90:93], v[180:183], v[200:203], v[90:93]
	v_mfma_f32_16x16x32_bf16 v[82:85], v[172:175], v[208:211], v[82:85]
	v_mfma_f32_16x16x32_bf16 v[74:77], v[180:183], v[208:211], v[74:77]
	v_mfma_f32_16x16x32_bf16 v[70:73], v[172:175], v[216:219], v[70:73]
	v_mfma_f32_16x16x32_bf16 v[66:69], v[180:183], v[216:219], v[66:69]
	s_barrier
	s_add_i32 s46, s71, s54
	v_lshl_add_u64 v[192:193], v[192:193], 0, s[10:11]
	s_mov_b32 m0, s46
	ds_read_b128 v[184:187], v151 offset:49152
	ds_read_b128 v[188:191], v151 offset:50176
	ds_read_b128 v[196:199], v151 offset:51200
	ds_read_b128 v[200:203], v151 offset:52224
	ds_read_b128 v[204:207], v151 offset:53248
	ds_read_b128 v[208:211], v151 offset:54272
	ds_read_b128 v[212:215], v151 offset:55296
	ds_read_b128 v[216:219], v151 offset:56320
	global_load_lds_dwordx4 v[192:193], off
	s_add_i32 m0, s46, 0x2000
	s_add_u32 s42, s42, 0x100080
	v_lshl_add_u64 v[192:193], v[220:221], 0, s[10:11]
	s_addc_u32 s43, s43, 0
	s_add_i32 s46, s72, s54
	global_load_lds_dwordx4 v[192:193], off
	v_lshl_add_u64 v[192:193], s[42:43], 0, v[130:131]
	s_mov_b32 m0, s46
	s_nop 0
	global_load_lds_dwordx4 v[192:193], off
	v_lshl_add_u64 v[192:193], s[42:43], 0, v[132:133]
	s_add_i32 m0, s46, 0x2000
	s_nop 0
	global_load_lds_dwordx4 v[192:193], off
	v_lshl_add_u64 v[192:193], v[222:223], 0, s[10:11]
	s_mov_b32 m0, s59
	s_nop 0
	global_load_lds_dwordx4 v[192:193], off
	v_lshl_add_u64 v[192:193], v[224:225], 0, s[10:11]
	s_mov_b32 m0, s60
	s_nop 0
	global_load_lds_dwordx4 v[192:193], off
	s_nop 0
	s_waitcnt vmcnt(8)
	s_waitcnt lgkmcnt(0)
	s_barrier
	v_mfma_f32_16x16x32_bf16 v[62:65], v[152:155], v[184:187], v[62:65]
	v_mfma_f32_16x16x32_bf16 v[58:61], v[160:163], v[184:187], v[58:61]
	v_mfma_f32_16x16x32_bf16 v[54:57], v[152:155], v[196:199], v[54:57]
	v_mfma_f32_16x16x32_bf16 v[46:49], v[160:163], v[196:199], v[46:49]
	v_mfma_f32_16x16x32_bf16 v[38:41], v[152:155], v[204:207], v[38:41]
	v_mfma_f32_16x16x32_bf16 v[30:33], v[160:163], v[204:207], v[30:33]
	v_mfma_f32_16x16x32_bf16 v[22:25], v[152:155], v[212:215], v[22:25]
	v_mfma_f32_16x16x32_bf16 v[14:17], v[160:163], v[212:215], v[14:17]
	v_mfma_f32_16x16x32_bf16 v[62:65], v[156:159], v[188:191], v[62:65]
	v_mfma_f32_16x16x32_bf16 v[58:61], v[164:167], v[188:191], v[58:61]
	v_mfma_f32_16x16x32_bf16 v[54:57], v[156:159], v[200:203], v[54:57]
	v_mfma_f32_16x16x32_bf16 v[46:49], v[164:167], v[200:203], v[46:49]
	v_mfma_f32_16x16x32_bf16 v[38:41], v[156:159], v[208:211], v[38:41]
	v_mfma_f32_16x16x32_bf16 v[30:33], v[164:167], v[208:211], v[30:33]
	v_mfma_f32_16x16x32_bf16 v[22:25], v[156:159], v[216:219], v[22:25]
	v_mfma_f32_16x16x32_bf16 v[14:17], v[164:167], v[216:219], v[14:17]
	v_mfma_f32_16x16x32_bf16 v[50:53], v[168:171], v[184:187], v[50:53]
	v_mfma_f32_16x16x32_bf16 v[42:45], v[176:179], v[184:187], v[42:45]
	v_mfma_f32_16x16x32_bf16 v[34:37], v[168:171], v[196:199], v[34:37]
	v_mfma_f32_16x16x32_bf16 v[26:29], v[176:179], v[196:199], v[26:29]
	v_mfma_f32_16x16x32_bf16 v[18:21], v[168:171], v[204:207], v[18:21]
	v_mfma_f32_16x16x32_bf16 v[10:13], v[176:179], v[204:207], v[10:13]
	v_mfma_f32_16x16x32_bf16 v[6:9], v[168:171], v[212:215], v[6:9]
	v_mfma_f32_16x16x32_bf16 v[2:5], v[176:179], v[212:215], v[2:5]
	v_mfma_f32_16x16x32_bf16 v[50:53], v[172:175], v[188:191], v[50:53]
	v_mfma_f32_16x16x32_bf16 v[42:45], v[180:183], v[188:191], v[42:45]
	v_mfma_f32_16x16x32_bf16 v[34:37], v[172:175], v[200:203], v[34:37]
	v_mfma_f32_16x16x32_bf16 v[26:29], v[180:183], v[200:203], v[26:29]
	v_mfma_f32_16x16x32_bf16 v[18:21], v[172:175], v[208:211], v[18:21]
	v_mfma_f32_16x16x32_bf16 v[10:13], v[180:183], v[208:211], v[10:13]
	v_mfma_f32_16x16x32_bf16 v[6:9], v[172:175], v[216:219], v[6:9]
	v_mfma_f32_16x16x32_bf16 v[2:5], v[180:183], v[216:219], v[2:5]
	s_barrier
	s_add_i32 s70, s70, 2
	s_add_u32 s40, s40, 0x100
	s_addc_u32 s41, s41, 0
	s_add_u32 s68, s68, 0x100
	s_addc_u32 s69, s69, 0
	s_cmp_gt_u32 s70, 61
	s_cbranch_scc0 .LBB0_311
	s_and_b64 vcc, exec, s[12:13]
	s_cbranch_vccz .LBB0_314
	s_barrier

.LBB0_335:
	ds_read_b128 v[144:147], v140
	ds_read_b128 v[148:151], v140 offset:1024
	ds_read_b128 v[152:155], v140 offset:2048
	ds_read_b128 v[156:159], v140 offset:3072
	ds_read_b128 v[160:163], v142
	ds_read_b128 v[164:167], v142 offset:1024
	ds_read_b128 v[168:171], v142 offset:2048
	ds_read_b128 v[172:175], v142 offset:3072
	s_add_u32 s42, s40, 0xfff00080
	s_addc_u32 s43, s41, -1
	s_cmp_eq_u32 s67, 60
	s_cselect_b32 s47, s27, s43
	s_cselect_b32 s46, s63, s42
	s_cselect_b32 s43, s25, s66
	s_cselect_b32 s42, s64, s65
	v_lshl_add_u64 v[192:193], s[40:41], 0, v[134:135]
	s_add_i32 m0, s29, 0xc000
	ds_read_b128 v[176:179], v143
	ds_read_b128 v[180:183], v143 offset:1024
	ds_read_b128 v[184:187], v143 offset:2048
	ds_read_b128 v[188:191], v143 offset:3072
	ds_read_b128 v[196:199], v143 offset:4096
	ds_read_b128 v[200:203], v143 offset:5120
	ds_read_b128 v[204:207], v143 offset:6144
	ds_read_b128 v[208:211], v143 offset:7168
	global_load_lds_dwordx4 v[192:193], off
	v_lshl_add_u64 v[192:193], s[40:41], 0, v[136:137]
	s_add_i32 m0, s29, 0xe000
	s_nop 0
	global_load_lds_dwordx4 v[192:193], off
	s_waitcnt vmcnt(8)
	s_waitcnt lgkmcnt(0)
	s_barrier
	v_mfma_f32_16x16x32_bf16 v[126:129], v[144:147], v[176:179], v[126:129]
	v_mfma_f32_16x16x32_bf16 v[122:125], v[152:155], v[176:179], v[122:125]
	v_mfma_f32_16x16x32_bf16 v[118:121], v[144:147], v[184:187], v[118:121]
	v_mfma_f32_16x16x32_bf16 v[110:113], v[152:155], v[184:187], v[110:113]
	v_mfma_f32_16x16x32_bf16 v[102:105], v[144:147], v[196:199], v[102:105]
	v_mfma_f32_16x16x32_bf16 v[94:97], v[152:155], v[196:199], v[94:97]
	v_mfma_f32_16x16x32_bf16 v[86:89], v[144:147], v[204:207], v[86:89]
	v_mfma_f32_16x16x32_bf16 v[78:81], v[152:155], v[204:207], v[78:81]
	v_mfma_f32_16x16x32_bf16 v[126:129], v[148:151], v[180:183], v[126:129]
	v_mfma_f32_16x16x32_bf16 v[122:125], v[156:159], v[180:183], v[122:125]
	v_mfma_f32_16x16x32_bf16 v[118:121], v[148:151], v[188:191], v[118:121]
	v_mfma_f32_16x16x32_bf16 v[110:113], v[156:159], v[188:191], v[110:113]
	v_mfma_f32_16x16x32_bf16 v[102:105], v[148:151], v[200:203], v[102:105]
	v_mfma_f32_16x16x32_bf16 v[94:97], v[156:159], v[200:203], v[94:97]
	v_mfma_f32_16x16x32_bf16 v[86:89], v[148:151], v[208:211], v[86:89]
	v_mfma_f32_16x16x32_bf16 v[78:81], v[156:159], v[208:211], v[78:81]
	v_mfma_f32_16x16x32_bf16 v[114:117], v[160:163], v[176:179], v[114:117]
	v_mfma_f32_16x16x32_bf16 v[106:109], v[168:171], v[176:179], v[106:109]
	v_mfma_f32_16x16x32_bf16 v[98:101], v[160:163], v[184:187], v[98:101]
	v_mfma_f32_16x16x32_bf16 v[90:93], v[168:171], v[184:187], v[90:93]
	v_mfma_f32_16x16x32_bf16 v[82:85], v[160:163], v[196:199], v[82:85]
	v_mfma_f32_16x16x32_bf16 v[74:77], v[168:171], v[196:199], v[74:77]
	v_mfma_f32_16x16x32_bf16 v[70:73], v[160:163], v[204:207], v[70:73]
	v_mfma_f32_16x16x32_bf16 v[66:69], v[168:171], v[204:207], v[66:69]
	v_mfma_f32_16x16x32_bf16 v[114:117], v[164:167], v[180:183], v[114:117]
	v_mfma_f32_16x16x32_bf16 v[106:109], v[172:175], v[180:183], v[106:109]
	v_mfma_f32_16x16x32_bf16 v[98:101], v[164:167], v[188:191], v[98:101]
	v_mfma_f32_16x16x32_bf16 v[90:93], v[172:175], v[188:191], v[90:93]
	v_mfma_f32_16x16x32_bf16 v[82:85], v[164:167], v[200:203], v[82:85]
	v_mfma_f32_16x16x32_bf16 v[74:77], v[172:175], v[200:203], v[74:77]
	v_mfma_f32_16x16x32_bf16 v[70:73], v[164:167], v[208:211], v[70:73]
	v_mfma_f32_16x16x32_bf16 v[66:69], v[172:175], v[208:211], v[66:69]
	s_barrier
	s_add_i32 s68, s59, s51
	v_lshl_add_u64 v[192:193], s[42:43], 0, v[130:131]
	s_mov_b32 m0, s68
	ds_read_b128 v[176:179], v143 offset:16384
	ds_read_b128 v[180:183], v143 offset:17408
	ds_read_b128 v[184:187], v143 offset:18432
	ds_read_b128 v[188:191], v143 offset:19456
	ds_read_b128 v[196:199], v143 offset:20480
	ds_read_b128 v[200:203], v143 offset:21504
	ds_read_b128 v[204:207], v143 offset:22528
	ds_read_b128 v[208:211], v143 offset:23552
	global_load_lds_dwordx4 v[192:193], off
	s_add_i32 m0, s68, 0x2000
	s_add_u32 s68, s42, 0x100000
	v_lshl_add_u64 v[212:213], s[42:43], 0, v[132:133]
	s_addc_u32 s69, s43, 0
	s_add_i32 s70, s60, s51
	global_load_lds_dwordx4 v[212:213], off
	v_lshl_add_u64 v[214:215], s[68:69], 0, v[130:131]
	s_mov_b32 m0, s70
	v_lshl_add_u64 v[216:217], s[46:47], 0, v[132:133]
	global_load_lds_dwordx4 v[214:215], off
	v_lshl_add_u64 v[214:215], s[68:69], 0, v[132:133]
	s_add_i32 m0, s70, 0x2000
	s_nop 0
	global_load_lds_dwordx4 v[214:215], off
	v_lshl_add_u64 v[214:215], s[46:47], 0, v[130:131]
	s_mov_b32 m0, s29
	s_nop 0
	global_load_lds_dwordx4 v[214:215], off
	s_mov_b32 m0, s52
	s_nop 0
	global_load_lds_dwordx4 v[216:217], off
	s_waitcnt vmcnt(8)
	s_waitcnt lgkmcnt(0)
	s_barrier
	v_mfma_f32_16x16x32_bf16 v[62:65], v[144:147], v[176:179], v[62:65]
	v_mfma_f32_16x16x32_bf16 v[58:61], v[152:155], v[176:179], v[58:61]
	v_mfma_f32_16x16x32_bf16 v[54:57], v[144:147], v[184:187], v[54:57]
	v_mfma_f32_16x16x32_bf16 v[46:49], v[152:155], v[184:187], v[46:49]
	v_mfma_f32_16x16x32_bf16 v[38:41], v[144:147], v[196:199], v[38:41]
	v_mfma_f32_16x16x32_bf16 v[30:33], v[152:155], v[196:199], v[30:33]
	v_mfma_f32_16x16x32_bf16 v[22:25], v[144:147], v[204:207], v[22:25]
	v_mfma_f32_16x16x32_bf16 v[14:17], v[152:155], v[204:207], v[14:17]
	v_mfma_f32_16x16x32_bf16 v[62:65], v[148:151], v[180:183], v[62:65]
	v_mfma_f32_16x16x32_bf16 v[58:61], v[156:159], v[180:183], v[58:61]
	v_mfma_f32_16x16x32_bf16 v[54:57], v[148:151], v[188:191], v[54:57]
	v_mfma_f32_16x16x32_bf16 v[46:49], v[156:159], v[188:191], v[46:49]
	v_mfma_f32_16x16x32_bf16 v[38:41], v[148:151], v[200:203], v[38:41]
	v_mfma_f32_16x16x32_bf16 v[30:33], v[156:159], v[200:203], v[30:33]
	v_mfma_f32_16x16x32_bf16 v[22:25], v[148:151], v[208:211], v[22:25]
	v_mfma_f32_16x16x32_bf16 v[14:17], v[156:159], v[208:211], v[14:17]
	v_mfma_f32_16x16x32_bf16 v[50:53], v[160:163], v[176:179], v[50:53]
	v_mfma_f32_16x16x32_bf16 v[42:45], v[168:171], v[176:179], v[42:45]
	v_mfma_f32_16x16x32_bf16 v[34:37], v[160:163], v[184:187], v[34:37]
	v_mfma_f32_16x16x32_bf16 v[26:29], v[168:171], v[184:187], v[26:29]
	v_mfma_f32_16x16x32_bf16 v[18:21], v[160:163], v[196:199], v[18:21]
	v_mfma_f32_16x16x32_bf16 v[10:13], v[168:171], v[196:199], v[10:13]
	v_mfma_f32_16x16x32_bf16 v[6:9], v[160:163], v[204:207], v[6:9]
	v_mfma_f32_16x16x32_bf16 v[2:5], v[168:171], v[204:207], v[2:5]
	v_mfma_f32_16x16x32_bf16 v[50:53], v[164:167], v[180:183], v[50:53]
	v_mfma_f32_16x16x32_bf16 v[42:45], v[172:175], v[180:183], v[42:45]
	v_mfma_f32_16x16x32_bf16 v[34:37], v[164:167], v[188:191], v[34:37]
	v_mfma_f32_16x16x32_bf16 v[26:29], v[172:175], v[188:191], v[26:29]
	v_mfma_f32_16x16x32_bf16 v[18:21], v[164:167], v[200:203], v[18:21]
	v_mfma_f32_16x16x32_bf16 v[10:13], v[172:175], v[200:203], v[10:13]
	v_mfma_f32_16x16x32_bf16 v[6:9], v[164:167], v[208:211], v[6:9]
	v_mfma_f32_16x16x32_bf16 v[2:5], v[172:175], v[208:211], v[2:5]
	s_barrier
	s_add_i32 s68, 0, 0x18000
	s_add_i32 s69, 0, 0x1c000
	v_add_u32_e32 v156, s68, v139
	v_add_u32_e32 v172, s69, v139
	ds_read_b128 v[144:147], v156
	ds_read_b128 v[148:151], v156 offset:1024
	ds_read_b128 v[152:155], v156 offset:2048
	ds_read_b128 v[156:159], v156 offset:3072
	ds_read_b128 v[160:163], v172
	ds_read_b128 v[164:167], v172 offset:1024
	ds_read_b128 v[168:171], v172 offset:2048
	ds_read_b128 v[172:175], v172 offset:3072
	s_add_u32 s46, s46, 0x100000
	s_addc_u32 s47, s47, 0
	s_mov_b32 m0, s53
	v_lshl_add_u64 v[218:219], s[46:47], 0, v[130:131]
	ds_read_b128 v[176:179], v143 offset:32768
	ds_read_b128 v[180:183], v143 offset:33792
	ds_read_b128 v[184:187], v143 offset:34816
	ds_read_b128 v[188:191], v143 offset:35840
	ds_read_b128 v[196:199], v143 offset:36864
	ds_read_b128 v[200:203], v143 offset:37888
	ds_read_b128 v[204:207], v143 offset:38912
	ds_read_b128 v[208:211], v143 offset:39936
	global_load_lds_dwordx4 v[218:219], off
	v_lshl_add_u64 v[218:219], s[46:47], 0, v[132:133]
	s_mov_b32 m0, s54
	s_nop 0
	global_load_lds_dwordx4 v[218:219], off
	s_waitcnt vmcnt(8)
	s_waitcnt lgkmcnt(0)
	s_barrier
	v_mfma_f32_16x16x32_bf16 v[126:129], v[144:147], v[176:179], v[126:129]
	v_mfma_f32_16x16x32_bf16 v[122:125], v[152:155], v[176:179], v[122:125]
	v_mfma_f32_16x16x32_bf16 v[118:121], v[144:147], v[184:187], v[118:121]
	v_mfma_f32_16x16x32_bf16 v[110:113], v[152:155], v[184:187], v[110:113]
	v_mfma_f32_16x16x32_bf16 v[102:105], v[144:147], v[196:199], v[102:105]
	v_mfma_f32_16x16x32_bf16 v[94:97], v[152:155], v[196:199], v[94:97]
	v_mfma_f32_16x16x32_bf16 v[86:89], v[144:147], v[204:207], v[86:89]
	v_mfma_f32_16x16x32_bf16 v[78:81], v[152:155], v[204:207], v[78:81]
	v_mfma_f32_16x16x32_bf16 v[126:129], v[148:151], v[180:183], v[126:129]
	v_mfma_f32_16x16x32_bf16 v[122:125], v[156:159], v[180:183], v[122:125]
	v_mfma_f32_16x16x32_bf16 v[118:121], v[148:151], v[188:191], v[118:121]
	v_mfma_f32_16x16x32_bf16 v[110:113], v[156:159], v[188:191], v[110:113]
	v_mfma_f32_16x16x32_bf16 v[102:105], v[148:151], v[200:203], v[102:105]
	v_mfma_f32_16x16x32_bf16 v[94:97], v[156:159], v[200:203], v[94:97]
	v_mfma_f32_16x16x32_bf16 v[86:89], v[148:151], v[208:211], v[86:89]
	v_mfma_f32_16x16x32_bf16 v[78:81], v[156:159], v[208:211], v[78:81]
	v_mfma_f32_16x16x32_bf16 v[114:117], v[160:163], v[176:179], v[114:117]
	v_mfma_f32_16x16x32_bf16 v[106:109], v[168:171], v[176:179], v[106:109]
	v_mfma_f32_16x16x32_bf16 v[98:101], v[160:163], v[184:187], v[98:101]
	v_mfma_f32_16x16x32_bf16 v[90:93], v[168:171], v[184:187], v[90:93]
	v_mfma_f32_16x16x32_bf16 v[82:85], v[160:163], v[196:199], v[82:85]
	v_mfma_f32_16x16x32_bf16 v[74:77], v[168:171], v[196:199], v[74:77]
	v_mfma_f32_16x16x32_bf16 v[70:73], v[160:163], v[204:207], v[70:73]
	v_mfma_f32_16x16x32_bf16 v[66:69], v[168:171], v[204:207], v[66:69]
	v_mfma_f32_16x16x32_bf16 v[114:117], v[164:167], v[180:183], v[114:117]
	v_mfma_f32_16x16x32_bf16 v[106:109], v[172:175], v[180:183], v[106:109]
	v_mfma_f32_16x16x32_bf16 v[98:101], v[164:167], v[188:191], v[98:101]
	v_mfma_f32_16x16x32_bf16 v[90:93], v[172:175], v[188:191], v[90:93]
	v_mfma_f32_16x16x32_bf16 v[82:85], v[164:167], v[200:203], v[82:85]
	v_mfma_f32_16x16x32_bf16 v[74:77], v[172:175], v[200:203], v[74:77]
	v_mfma_f32_16x16x32_bf16 v[70:73], v[164:167], v[208:211], v[70:73]
	v_mfma_f32_16x16x32_bf16 v[66:69], v[172:175], v[208:211], v[66:69]
	s_barrier
	s_add_i32 s46, s68, s51
	v_lshl_add_u64 v[192:193], v[192:193], 0, s[10:11]
	s_mov_b32 m0, s46
	ds_read_b128 v[176:179], v143 offset:49152
	ds_read_b128 v[180:183], v143 offset:50176
	ds_read_b128 v[184:187], v143 offset:51200
	ds_read_b128 v[188:191], v143 offset:52224
	ds_read_b128 v[196:199], v143 offset:53248
	ds_read_b128 v[200:203], v143 offset:54272
	ds_read_b128 v[204:207], v143 offset:55296
	ds_read_b128 v[208:211], v143 offset:56320
	global_load_lds_dwordx4 v[192:193], off
	s_add_i32 m0, s46, 0x2000
	s_add_u32 s42, s42, 0x100080
	v_lshl_add_u64 v[192:193], v[212:213], 0, s[10:11]
	s_addc_u32 s43, s43, 0
	s_add_i32 s46, s69, s51
	global_load_lds_dwordx4 v[192:193], off
	v_lshl_add_u64 v[192:193], s[42:43], 0, v[130:131]
	s_mov_b32 m0, s46
	s_nop 0
	global_load_lds_dwordx4 v[192:193], off
	v_lshl_add_u64 v[192:193], s[42:43], 0, v[132:133]
	s_add_i32 m0, s46, 0x2000
	s_nop 0
	global_load_lds_dwordx4 v[192:193], off
	v_lshl_add_u64 v[192:193], v[214:215], 0, s[10:11]
	s_mov_b32 m0, s56
	s_nop 0
	global_load_lds_dwordx4 v[192:193], off
	v_lshl_add_u64 v[192:193], v[216:217], 0, s[10:11]
	s_mov_b32 m0, s57
	s_nop 0
	global_load_lds_dwordx4 v[192:193], off
	s_nop 0
	s_waitcnt vmcnt(8)
	s_waitcnt lgkmcnt(0)
	s_barrier
	v_mfma_f32_16x16x32_bf16 v[62:65], v[144:147], v[176:179], v[62:65]
	v_mfma_f32_16x16x32_bf16 v[58:61], v[152:155], v[176:179], v[58:61]
	v_mfma_f32_16x16x32_bf16 v[54:57], v[144:147], v[184:187], v[54:57]
	v_mfma_f32_16x16x32_bf16 v[46:49], v[152:155], v[184:187], v[46:49]
	v_mfma_f32_16x16x32_bf16 v[38:41], v[144:147], v[196:199], v[38:41]
	v_mfma_f32_16x16x32_bf16 v[30:33], v[152:155], v[196:199], v[30:33]
	v_mfma_f32_16x16x32_bf16 v[22:25], v[144:147], v[204:207], v[22:25]
	v_mfma_f32_16x16x32_bf16 v[14:17], v[152:155], v[204:207], v[14:17]
	v_mfma_f32_16x16x32_bf16 v[62:65], v[148:151], v[180:183], v[62:65]
	v_mfma_f32_16x16x32_bf16 v[58:61], v[156:159], v[180:183], v[58:61]
	v_mfma_f32_16x16x32_bf16 v[54:57], v[148:151], v[188:191], v[54:57]
	v_mfma_f32_16x16x32_bf16 v[46:49], v[156:159], v[188:191], v[46:49]
	v_mfma_f32_16x16x32_bf16 v[38:41], v[148:151], v[200:203], v[38:41]
	v_mfma_f32_16x16x32_bf16 v[30:33], v[156:159], v[200:203], v[30:33]
	v_mfma_f32_16x16x32_bf16 v[22:25], v[148:151], v[208:211], v[22:25]
	v_mfma_f32_16x16x32_bf16 v[14:17], v[156:159], v[208:211], v[14:17]
	v_mfma_f32_16x16x32_bf16 v[50:53], v[160:163], v[176:179], v[50:53]
	v_mfma_f32_16x16x32_bf16 v[42:45], v[168:171], v[176:179], v[42:45]
	v_mfma_f32_16x16x32_bf16 v[34:37], v[160:163], v[184:187], v[34:37]
	v_mfma_f32_16x16x32_bf16 v[26:29], v[168:171], v[184:187], v[26:29]
	v_mfma_f32_16x16x32_bf16 v[18:21], v[160:163], v[196:199], v[18:21]
	v_mfma_f32_16x16x32_bf16 v[10:13], v[168:171], v[196:199], v[10:13]
	v_mfma_f32_16x16x32_bf16 v[6:9], v[160:163], v[204:207], v[6:9]
	v_mfma_f32_16x16x32_bf16 v[2:5], v[168:171], v[204:207], v[2:5]
	v_mfma_f32_16x16x32_bf16 v[50:53], v[164:167], v[180:183], v[50:53]
	v_mfma_f32_16x16x32_bf16 v[42:45], v[172:175], v[180:183], v[42:45]
	v_mfma_f32_16x16x32_bf16 v[34:37], v[164:167], v[188:191], v[34:37]
	v_mfma_f32_16x16x32_bf16 v[26:29], v[172:175], v[188:191], v[26:29]
	v_mfma_f32_16x16x32_bf16 v[18:21], v[164:167], v[200:203], v[18:21]
	v_mfma_f32_16x16x32_bf16 v[10:13], v[172:175], v[200:203], v[10:13]
	v_mfma_f32_16x16x32_bf16 v[6:9], v[164:167], v[208:211], v[6:9]
	v_mfma_f32_16x16x32_bf16 v[2:5], v[172:175], v[208:211], v[2:5]
	s_barrier
	s_add_i32 s67, s67, 2
	s_add_u32 s40, s40, 0x100
	s_addc_u32 s41, s41, 0
	s_add_u32 s65, s65, 0x100
	s_addc_u32 s66, s66, 0
	s_cmp_gt_u32 s67, 61
	s_cbranch_scc0 .LBB0_335
	s_and_b64 vcc, exec, s[12:13]
	s_cbranch_vccz .LBB0_338
	s_barrier

.LBB0_657:
	ds_read_b128 v[158:161], v155
	ds_read_b128 v[162:165], v155 offset:1024
	ds_read_b128 v[166:169], v155 offset:2048
	ds_read_b128 v[170:173], v155 offset:3072
	ds_read_b128 v[174:177], v156
	ds_read_b128 v[178:181], v156 offset:1024
	ds_read_b128 v[182:185], v156 offset:2048
	ds_read_b128 v[186:189], v156 offset:3072
	s_add_u32 s28, s26, 0xfff00080
	s_addc_u32 s29, s27, -1
	s_cmp_eq_u32 s58, 60
	s_cselect_b32 s31, s21, s29
	s_cselect_b32 s30, s54, s28
	s_cselect_b32 s29, s19, s57
	s_cselect_b32 s28, s55, s56
	v_lshl_add_u64 v[224:225], s[26:27], 0, v[138:139]
	s_add_i32 m0, s17, 0xc000
	ds_read_b128 v[190:193], v157
	ds_read_b128 v[196:199], v157 offset:1024
	ds_read_b128 v[200:203], v157 offset:2048
	ds_read_b128 v[204:207], v157 offset:3072
	ds_read_b128 v[208:211], v157 offset:4096
	ds_read_b128 v[212:215], v157 offset:5120
	ds_read_b128 v[216:219], v157 offset:6144
	ds_read_b128 v[220:223], v157 offset:7168
	global_load_lds_dwordx4 v[224:225], off
	v_lshl_add_u64 v[224:225], s[26:27], 0, v[140:141]
	s_add_i32 m0, s17, 0xe000
	s_nop 0
	global_load_lds_dwordx4 v[224:225], off
	s_nop 0
	s_waitcnt vmcnt(8)
	s_waitcnt lgkmcnt(0)
	s_barrier
	v_mfma_f32_16x16x32_bf16 v[126:129], v[158:161], v[190:193], v[126:129]
	v_mfma_f32_16x16x32_bf16 v[122:125], v[166:169], v[190:193], v[122:125]
	v_mfma_f32_16x16x32_bf16 v[118:121], v[158:161], v[200:203], v[118:121]
	v_mfma_f32_16x16x32_bf16 v[114:117], v[166:169], v[200:203], v[114:117]
	v_mfma_f32_16x16x32_bf16 v[102:105], v[158:161], v[208:211], v[102:105]
	v_mfma_f32_16x16x32_bf16 v[98:101], v[166:169], v[208:211], v[98:101]
	v_mfma_f32_16x16x32_bf16 v[86:89], v[158:161], v[216:219], v[86:89]
	v_mfma_f32_16x16x32_bf16 v[82:85], v[166:169], v[216:219], v[82:85]
	v_mfma_f32_16x16x32_bf16 v[126:129], v[162:165], v[196:199], v[126:129]
	v_mfma_f32_16x16x32_bf16 v[122:125], v[170:173], v[196:199], v[122:125]
	v_mfma_f32_16x16x32_bf16 v[118:121], v[162:165], v[204:207], v[118:121]
	v_mfma_f32_16x16x32_bf16 v[114:117], v[170:173], v[204:207], v[114:117]
	v_mfma_f32_16x16x32_bf16 v[102:105], v[162:165], v[212:215], v[102:105]
	v_mfma_f32_16x16x32_bf16 v[98:101], v[170:173], v[212:215], v[98:101]
	v_mfma_f32_16x16x32_bf16 v[86:89], v[162:165], v[220:223], v[86:89]
	v_mfma_f32_16x16x32_bf16 v[82:85], v[170:173], v[220:223], v[82:85]
	v_mfma_f32_16x16x32_bf16 v[110:113], v[174:177], v[190:193], v[110:113]
	v_mfma_f32_16x16x32_bf16 v[106:109], v[182:185], v[190:193], v[106:109]
	v_mfma_f32_16x16x32_bf16 v[94:97], v[174:177], v[200:203], v[94:97]
	v_mfma_f32_16x16x32_bf16 v[90:93], v[182:185], v[200:203], v[90:93]
	v_mfma_f32_16x16x32_bf16 v[78:81], v[174:177], v[208:211], v[78:81]
	v_mfma_f32_16x16x32_bf16 v[74:77], v[182:185], v[208:211], v[74:77]
	v_mfma_f32_16x16x32_bf16 v[70:73], v[174:177], v[216:219], v[70:73]
	v_mfma_f32_16x16x32_bf16 v[66:69], v[182:185], v[216:219], v[66:69]
	v_mfma_f32_16x16x32_bf16 v[110:113], v[178:181], v[196:199], v[110:113]
	v_mfma_f32_16x16x32_bf16 v[106:109], v[186:189], v[196:199], v[106:109]
	v_mfma_f32_16x16x32_bf16 v[94:97], v[178:181], v[204:207], v[94:97]
	v_mfma_f32_16x16x32_bf16 v[90:93], v[186:189], v[204:207], v[90:93]
	v_mfma_f32_16x16x32_bf16 v[78:81], v[178:181], v[212:215], v[78:81]
	v_mfma_f32_16x16x32_bf16 v[74:77], v[186:189], v[212:215], v[74:77]
	v_mfma_f32_16x16x32_bf16 v[70:73], v[178:181], v[220:223], v[70:73]
	v_mfma_f32_16x16x32_bf16 v[66:69], v[186:189], v[220:223], v[66:69]
	s_barrier
	s_add_i32 s59, s50, s41
	v_lshl_add_u64 v[224:225], s[28:29], 0, v[134:135]
	s_mov_b32 m0, s59
	ds_read_b128 v[190:193], v157 offset:16384
	ds_read_b128 v[196:199], v157 offset:17408
	ds_read_b128 v[200:203], v157 offset:18432
	ds_read_b128 v[204:207], v157 offset:19456
	ds_read_b128 v[208:211], v157 offset:20480
	ds_read_b128 v[212:215], v157 offset:21504
	ds_read_b128 v[216:219], v157 offset:22528
	ds_read_b128 v[220:223], v157 offset:23552
	global_load_lds_dwordx4 v[224:225], off
	s_add_i32 m0, s59, 0x2000
	s_add_u32 s60, s28, 0x100000
	v_lshl_add_u64 v[226:227], s[28:29], 0, v[136:137]
	s_addc_u32 s61, s29, 0
	s_add_i32 s59, s51, s41
	global_load_lds_dwordx4 v[226:227], off
	v_lshl_add_u64 v[228:229], s[60:61], 0, v[134:135]
	s_mov_b32 m0, s59
	v_lshl_add_u64 v[230:231], s[30:31], 0, v[132:133]
	global_load_lds_dwordx4 v[228:229], off
	v_lshl_add_u64 v[228:229], s[60:61], 0, v[136:137]
	s_add_i32 m0, s59, 0x2000
	s_nop 0
	global_load_lds_dwordx4 v[228:229], off
	v_lshl_add_u64 v[228:229], s[30:31], 0, v[130:131]
	s_mov_b32 m0, s17
	s_nop 0
	global_load_lds_dwordx4 v[228:229], off
	s_mov_b32 m0, s42
	s_nop 0
	global_load_lds_dwordx4 v[230:231], off
	s_waitcnt vmcnt(8)
	s_waitcnt lgkmcnt(0)
	s_barrier
	v_mfma_f32_16x16x32_bf16 v[62:65], v[158:161], v[190:193], v[62:65]
	v_mfma_f32_16x16x32_bf16 v[58:61], v[166:169], v[190:193], v[58:61]
	v_mfma_f32_16x16x32_bf16 v[54:57], v[158:161], v[200:203], v[54:57]
	v_mfma_f32_16x16x32_bf16 v[50:53], v[166:169], v[200:203], v[50:53]
	v_mfma_f32_16x16x32_bf16 v[38:41], v[158:161], v[208:211], v[38:41]
	v_mfma_f32_16x16x32_bf16 v[34:37], v[166:169], v[208:211], v[34:37]
	v_mfma_f32_16x16x32_bf16 v[22:25], v[158:161], v[216:219], v[22:25]
	v_mfma_f32_16x16x32_bf16 v[18:21], v[166:169], v[216:219], v[18:21]
	v_mfma_f32_16x16x32_bf16 v[62:65], v[162:165], v[196:199], v[62:65]
	v_mfma_f32_16x16x32_bf16 v[58:61], v[170:173], v[196:199], v[58:61]
	v_mfma_f32_16x16x32_bf16 v[54:57], v[162:165], v[204:207], v[54:57]
	v_mfma_f32_16x16x32_bf16 v[50:53], v[170:173], v[204:207], v[50:53]
	v_mfma_f32_16x16x32_bf16 v[38:41], v[162:165], v[212:215], v[38:41]
	v_mfma_f32_16x16x32_bf16 v[34:37], v[170:173], v[212:215], v[34:37]
	v_mfma_f32_16x16x32_bf16 v[22:25], v[162:165], v[220:223], v[22:25]
	v_mfma_f32_16x16x32_bf16 v[18:21], v[170:173], v[220:223], v[18:21]
	v_mfma_f32_16x16x32_bf16 v[46:49], v[174:177], v[190:193], v[46:49]
	v_mfma_f32_16x16x32_bf16 v[42:45], v[182:185], v[190:193], v[42:45]
	v_mfma_f32_16x16x32_bf16 v[30:33], v[174:177], v[200:203], v[30:33]
	v_mfma_f32_16x16x32_bf16 v[26:29], v[182:185], v[200:203], v[26:29]
	v_mfma_f32_16x16x32_bf16 v[14:17], v[174:177], v[208:211], v[14:17]
	v_mfma_f32_16x16x32_bf16 v[10:13], v[182:185], v[208:211], v[10:13]
	v_mfma_f32_16x16x32_bf16 v[6:9], v[174:177], v[216:219], v[6:9]
	v_mfma_f32_16x16x32_bf16 v[2:5], v[182:185], v[216:219], v[2:5]
	v_mfma_f32_16x16x32_bf16 v[46:49], v[178:181], v[196:199], v[46:49]
	v_mfma_f32_16x16x32_bf16 v[42:45], v[186:189], v[196:199], v[42:45]
	v_mfma_f32_16x16x32_bf16 v[30:33], v[178:181], v[204:207], v[30:33]
	v_mfma_f32_16x16x32_bf16 v[26:29], v[186:189], v[204:207], v[26:29]
	v_mfma_f32_16x16x32_bf16 v[14:17], v[178:181], v[212:215], v[14:17]
	v_mfma_f32_16x16x32_bf16 v[10:13], v[186:189], v[212:215], v[10:13]
	v_mfma_f32_16x16x32_bf16 v[6:9], v[178:181], v[220:223], v[6:9]
	v_mfma_f32_16x16x32_bf16 v[2:5], v[186:189], v[220:223], v[2:5]
	s_barrier
	s_add_i32 s59, 0, 0x18000
	s_add_i32 s60, 0, 0x1c000
	v_add_u32_e32 v170, s59, v153
	v_add_u32_e32 v186, s60, v153
	ds_read_b128 v[158:161], v170
	ds_read_b128 v[162:165], v170 offset:1024
	ds_read_b128 v[166:169], v170 offset:2048
	ds_read_b128 v[170:173], v170 offset:3072
	ds_read_b128 v[174:177], v186
	ds_read_b128 v[178:181], v186 offset:1024
	ds_read_b128 v[182:185], v186 offset:2048
	ds_read_b128 v[186:189], v186 offset:3072
	s_add_u32 s30, s30, 0x100000
	s_addc_u32 s31, s31, 0
	s_mov_b32 m0, s43
	v_lshl_add_u64 v[232:233], s[30:31], 0, v[130:131]
	ds_read_b128 v[190:193], v157 offset:32768
	ds_read_b128 v[196:199], v157 offset:33792
	ds_read_b128 v[200:203], v157 offset:34816
	ds_read_b128 v[204:207], v157 offset:35840
	ds_read_b128 v[208:211], v157 offset:36864
	ds_read_b128 v[212:215], v157 offset:37888
	ds_read_b128 v[216:219], v157 offset:38912
	ds_read_b128 v[220:223], v157 offset:39936
	global_load_lds_dwordx4 v[232:233], off
	v_lshl_add_u64 v[232:233], s[30:31], 0, v[132:133]
	s_mov_b32 m0, s45
	s_nop 0
	global_load_lds_dwordx4 v[232:233], off
	s_waitcnt vmcnt(8)
	s_waitcnt lgkmcnt(0)
	s_barrier
	v_mfma_f32_16x16x32_bf16 v[126:129], v[158:161], v[190:193], v[126:129]
	v_mfma_f32_16x16x32_bf16 v[122:125], v[166:169], v[190:193], v[122:125]
	v_mfma_f32_16x16x32_bf16 v[118:121], v[158:161], v[200:203], v[118:121]
	v_mfma_f32_16x16x32_bf16 v[114:117], v[166:169], v[200:203], v[114:117]
	v_mfma_f32_16x16x32_bf16 v[102:105], v[158:161], v[208:211], v[102:105]
	v_mfma_f32_16x16x32_bf16 v[98:101], v[166:169], v[208:211], v[98:101]
	v_mfma_f32_16x16x32_bf16 v[86:89], v[158:161], v[216:219], v[86:89]
	v_mfma_f32_16x16x32_bf16 v[82:85], v[166:169], v[216:219], v[82:85]
	v_mfma_f32_16x16x32_bf16 v[126:129], v[162:165], v[196:199], v[126:129]
	v_mfma_f32_16x16x32_bf16 v[122:125], v[170:173], v[196:199], v[122:125]
	v_mfma_f32_16x16x32_bf16 v[118:121], v[162:165], v[204:207], v[118:121]
	v_mfma_f32_16x16x32_bf16 v[114:117], v[170:173], v[204:207], v[114:117]
	v_mfma_f32_16x16x32_bf16 v[102:105], v[162:165], v[212:215], v[102:105]
	v_mfma_f32_16x16x32_bf16 v[98:101], v[170:173], v[212:215], v[98:101]
	v_mfma_f32_16x16x32_bf16 v[86:89], v[162:165], v[220:223], v[86:89]
	v_mfma_f32_16x16x32_bf16 v[82:85], v[170:173], v[220:223], v[82:85]
	v_mfma_f32_16x16x32_bf16 v[110:113], v[174:177], v[190:193], v[110:113]
	v_mfma_f32_16x16x32_bf16 v[106:109], v[182:185], v[190:193], v[106:109]
	v_mfma_f32_16x16x32_bf16 v[94:97], v[174:177], v[200:203], v[94:97]
	v_mfma_f32_16x16x32_bf16 v[90:93], v[182:185], v[200:203], v[90:93]
	v_mfma_f32_16x16x32_bf16 v[78:81], v[174:177], v[208:211], v[78:81]
	v_mfma_f32_16x16x32_bf16 v[74:77], v[182:185], v[208:211], v[74:77]
	v_mfma_f32_16x16x32_bf16 v[70:73], v[174:177], v[216:219], v[70:73]
	v_mfma_f32_16x16x32_bf16 v[66:69], v[182:185], v[216:219], v[66:69]
	v_mfma_f32_16x16x32_bf16 v[110:113], v[178:181], v[196:199], v[110:113]
	v_mfma_f32_16x16x32_bf16 v[106:109], v[186:189], v[196:199], v[106:109]
	v_mfma_f32_16x16x32_bf16 v[94:97], v[178:181], v[204:207], v[94:97]
	v_mfma_f32_16x16x32_bf16 v[90:93], v[186:189], v[204:207], v[90:93]
	v_mfma_f32_16x16x32_bf16 v[78:81], v[178:181], v[212:215], v[78:81]
	v_mfma_f32_16x16x32_bf16 v[74:77], v[186:189], v[212:215], v[74:77]
	v_mfma_f32_16x16x32_bf16 v[70:73], v[178:181], v[220:223], v[70:73]
	v_mfma_f32_16x16x32_bf16 v[66:69], v[186:189], v[220:223], v[66:69]
	s_barrier
	s_add_i32 s30, s59, s41
	v_lshl_add_u64 v[224:225], v[224:225], 0, s[12:13]
	s_mov_b32 m0, s30
	ds_read_b128 v[190:193], v157 offset:49152
	ds_read_b128 v[196:199], v157 offset:50176
	ds_read_b128 v[200:203], v157 offset:51200
	ds_read_b128 v[204:207], v157 offset:52224
	ds_read_b128 v[208:211], v157 offset:53248
	ds_read_b128 v[212:215], v157 offset:54272
	ds_read_b128 v[216:219], v157 offset:55296
	ds_read_b128 v[220:223], v157 offset:56320
	global_load_lds_dwordx4 v[224:225], off
	s_add_i32 m0, s30, 0x2000
	s_add_u32 s28, s28, 0x100080
	v_lshl_add_u64 v[224:225], v[226:227], 0, s[12:13]
	s_addc_u32 s29, s29, 0
	s_add_i32 s30, s60, s41
	global_load_lds_dwordx4 v[224:225], off
	v_lshl_add_u64 v[224:225], s[28:29], 0, v[134:135]
	s_mov_b32 m0, s30
	s_nop 0
	global_load_lds_dwordx4 v[224:225], off
	v_lshl_add_u64 v[224:225], s[28:29], 0, v[136:137]
	s_add_i32 m0, s30, 0x2000
	s_nop 0
	global_load_lds_dwordx4 v[224:225], off
	v_lshl_add_u64 v[224:225], v[228:229], 0, s[12:13]
	s_mov_b32 m0, s47
	s_nop 0
	global_load_lds_dwordx4 v[224:225], off
	v_lshl_add_u64 v[224:225], v[230:231], 0, s[12:13]
	s_mov_b32 m0, s48
	s_nop 0
	global_load_lds_dwordx4 v[224:225], off
	s_nop 0
	s_waitcnt vmcnt(8)
	s_waitcnt lgkmcnt(0)
	s_barrier
	v_mfma_f32_16x16x32_bf16 v[62:65], v[158:161], v[190:193], v[62:65]
	v_mfma_f32_16x16x32_bf16 v[58:61], v[166:169], v[190:193], v[58:61]
	v_mfma_f32_16x16x32_bf16 v[54:57], v[158:161], v[200:203], v[54:57]
	v_mfma_f32_16x16x32_bf16 v[50:53], v[166:169], v[200:203], v[50:53]
	v_mfma_f32_16x16x32_bf16 v[38:41], v[158:161], v[208:211], v[38:41]
	v_mfma_f32_16x16x32_bf16 v[34:37], v[166:169], v[208:211], v[34:37]
	v_mfma_f32_16x16x32_bf16 v[22:25], v[158:161], v[216:219], v[22:25]
	v_mfma_f32_16x16x32_bf16 v[18:21], v[166:169], v[216:219], v[18:21]
	v_mfma_f32_16x16x32_bf16 v[62:65], v[162:165], v[196:199], v[62:65]
	v_mfma_f32_16x16x32_bf16 v[58:61], v[170:173], v[196:199], v[58:61]
	v_mfma_f32_16x16x32_bf16 v[54:57], v[162:165], v[204:207], v[54:57]
	v_mfma_f32_16x16x32_bf16 v[50:53], v[170:173], v[204:207], v[50:53]
	v_mfma_f32_16x16x32_bf16 v[38:41], v[162:165], v[212:215], v[38:41]
	v_mfma_f32_16x16x32_bf16 v[34:37], v[170:173], v[212:215], v[34:37]
	v_mfma_f32_16x16x32_bf16 v[22:25], v[162:165], v[220:223], v[22:25]
	v_mfma_f32_16x16x32_bf16 v[18:21], v[170:173], v[220:223], v[18:21]
	v_mfma_f32_16x16x32_bf16 v[46:49], v[174:177], v[190:193], v[46:49]
	v_mfma_f32_16x16x32_bf16 v[42:45], v[182:185], v[190:193], v[42:45]
	v_mfma_f32_16x16x32_bf16 v[30:33], v[174:177], v[200:203], v[30:33]
	v_mfma_f32_16x16x32_bf16 v[26:29], v[182:185], v[200:203], v[26:29]
	v_mfma_f32_16x16x32_bf16 v[14:17], v[174:177], v[208:211], v[14:17]
	v_mfma_f32_16x16x32_bf16 v[10:13], v[182:185], v[208:211], v[10:13]
	v_mfma_f32_16x16x32_bf16 v[6:9], v[174:177], v[216:219], v[6:9]
	v_mfma_f32_16x16x32_bf16 v[2:5], v[182:185], v[216:219], v[2:5]
	v_mfma_f32_16x16x32_bf16 v[46:49], v[178:181], v[196:199], v[46:49]
	v_mfma_f32_16x16x32_bf16 v[42:45], v[186:189], v[196:199], v[42:45]
	v_mfma_f32_16x16x32_bf16 v[30:33], v[178:181], v[204:207], v[30:33]
	v_mfma_f32_16x16x32_bf16 v[26:29], v[186:189], v[204:207], v[26:29]
	v_mfma_f32_16x16x32_bf16 v[14:17], v[178:181], v[212:215], v[14:17]
	v_mfma_f32_16x16x32_bf16 v[10:13], v[186:189], v[212:215], v[10:13]
	v_mfma_f32_16x16x32_bf16 v[6:9], v[178:181], v[220:223], v[6:9]
	v_mfma_f32_16x16x32_bf16 v[2:5], v[186:189], v[220:223], v[2:5]
	s_barrier
	s_add_i32 s58, s58, 2
	s_add_u32 s26, s26, 0x100
	s_addc_u32 s27, s27, 0
	s_add_u32 s56, s56, 0x100
	s_addc_u32 s57, s57, 0
	s_cmp_gt_u32 s58, 61
	s_cbranch_scc0 .LBB0_657
	s_and_b64 vcc, exec, s[14:15]
	s_cbranch_vccz .LBB0_660
	s_barrier

.LBB0_681:
	ds_read_b128 v[152:155], v144
	ds_read_b128 v[156:159], v144 offset:1024
	ds_read_b128 v[160:163], v144 offset:2048
	ds_read_b128 v[164:167], v144 offset:3072
	ds_read_b128 v[168:171], v145
	ds_read_b128 v[172:175], v145 offset:1024
	ds_read_b128 v[176:179], v145 offset:2048
	ds_read_b128 v[180:183], v145 offset:3072
	s_add_u32 s42, s40, 0xfff00080
	s_addc_u32 s43, s41, -1
	s_cmp_eq_u32 s70, 60
	s_cselect_b32 s47, s27, s43
	s_cselect_b32 s46, s66, s42
	s_cselect_b32 s43, s25, s69
	s_cselect_b32 s42, s67, s68
	v_lshl_add_u64 v[192:193], s[40:41], 0, v[134:135]
	s_add_i32 m0, s29, 0xc000
	ds_read_b128 v[184:187], v150
	ds_read_b128 v[188:191], v150 offset:1024
	ds_read_b128 v[196:199], v150 offset:2048
	ds_read_b128 v[200:203], v150 offset:3072
	ds_read_b128 v[204:207], v150 offset:4096
	ds_read_b128 v[208:211], v150 offset:5120
	ds_read_b128 v[212:215], v150 offset:6144
	ds_read_b128 v[216:219], v150 offset:7168
	global_load_lds_dwordx4 v[192:193], off
	v_lshl_add_u64 v[192:193], s[40:41], 0, v[136:137]
	s_add_i32 m0, s29, 0xe000
	s_nop 0
	global_load_lds_dwordx4 v[192:193], off
	s_nop 0
	s_waitcnt vmcnt(8)
	s_waitcnt lgkmcnt(0)
	s_barrier
	v_mfma_f32_16x16x32_bf16 v[126:129], v[152:155], v[184:187], v[126:129]
	v_mfma_f32_16x16x32_bf16 v[122:125], v[160:163], v[184:187], v[122:125]
	v_mfma_f32_16x16x32_bf16 v[118:121], v[152:155], v[196:199], v[118:121]
	v_mfma_f32_16x16x32_bf16 v[110:113], v[160:163], v[196:199], v[110:113]
	v_mfma_f32_16x16x32_bf16 v[102:105], v[152:155], v[204:207], v[102:105]
	v_mfma_f32_16x16x32_bf16 v[94:97], v[160:163], v[204:207], v[94:97]
	v_mfma_f32_16x16x32_bf16 v[86:89], v[152:155], v[212:215], v[86:89]
	v_mfma_f32_16x16x32_bf16 v[78:81], v[160:163], v[212:215], v[78:81]
	v_mfma_f32_16x16x32_bf16 v[126:129], v[156:159], v[188:191], v[126:129]
	v_mfma_f32_16x16x32_bf16 v[122:125], v[164:167], v[188:191], v[122:125]
	v_mfma_f32_16x16x32_bf16 v[118:121], v[156:159], v[200:203], v[118:121]
	v_mfma_f32_16x16x32_bf16 v[110:113], v[164:167], v[200:203], v[110:113]
	v_mfma_f32_16x16x32_bf16 v[102:105], v[156:159], v[208:211], v[102:105]
	v_mfma_f32_16x16x32_bf16 v[94:97], v[164:167], v[208:211], v[94:97]
	v_mfma_f32_16x16x32_bf16 v[86:89], v[156:159], v[216:219], v[86:89]
	v_mfma_f32_16x16x32_bf16 v[78:81], v[164:167], v[216:219], v[78:81]
	v_mfma_f32_16x16x32_bf16 v[114:117], v[168:171], v[184:187], v[114:117]
	v_mfma_f32_16x16x32_bf16 v[106:109], v[176:179], v[184:187], v[106:109]
	v_mfma_f32_16x16x32_bf16 v[98:101], v[168:171], v[196:199], v[98:101]
	v_mfma_f32_16x16x32_bf16 v[90:93], v[176:179], v[196:199], v[90:93]
	v_mfma_f32_16x16x32_bf16 v[82:85], v[168:171], v[204:207], v[82:85]
	v_mfma_f32_16x16x32_bf16 v[74:77], v[176:179], v[204:207], v[74:77]
	v_mfma_f32_16x16x32_bf16 v[70:73], v[168:171], v[212:215], v[70:73]
	v_mfma_f32_16x16x32_bf16 v[66:69], v[176:179], v[212:215], v[66:69]
	v_mfma_f32_16x16x32_bf16 v[114:117], v[172:175], v[188:191], v[114:117]
	v_mfma_f32_16x16x32_bf16 v[106:109], v[180:183], v[188:191], v[106:109]
	v_mfma_f32_16x16x32_bf16 v[98:101], v[172:175], v[200:203], v[98:101]
	v_mfma_f32_16x16x32_bf16 v[90:93], v[180:183], v[200:203], v[90:93]
	v_mfma_f32_16x16x32_bf16 v[82:85], v[172:175], v[208:211], v[82:85]
	v_mfma_f32_16x16x32_bf16 v[74:77], v[180:183], v[208:211], v[74:77]
	v_mfma_f32_16x16x32_bf16 v[70:73], v[172:175], v[216:219], v[70:73]
	v_mfma_f32_16x16x32_bf16 v[66:69], v[180:183], v[216:219], v[66:69]
	s_barrier
	s_add_i32 s71, s62, s54
	v_lshl_add_u64 v[192:193], s[42:43], 0, v[130:131]
	s_mov_b32 m0, s71
	ds_read_b128 v[184:187], v150 offset:16384
	ds_read_b128 v[188:191], v150 offset:17408
	ds_read_b128 v[196:199], v150 offset:18432
	ds_read_b128 v[200:203], v150 offset:19456
	ds_read_b128 v[204:207], v150 offset:20480
	ds_read_b128 v[208:211], v150 offset:21504
	ds_read_b128 v[212:215], v150 offset:22528
	ds_read_b128 v[216:219], v150 offset:23552
	global_load_lds_dwordx4 v[192:193], off
	s_add_i32 m0, s71, 0x2000
	s_add_u32 s72, s42, 0x100000
	v_lshl_add_u64 v[220:221], s[42:43], 0, v[132:133]
	s_addc_u32 s73, s43, 0
	s_add_i32 s71, s63, s54
	global_load_lds_dwordx4 v[220:221], off
	v_lshl_add_u64 v[222:223], s[72:73], 0, v[130:131]
	s_mov_b32 m0, s71
	v_lshl_add_u64 v[224:225], s[46:47], 0, v[132:133]
	global_load_lds_dwordx4 v[222:223], off
	v_lshl_add_u64 v[222:223], s[72:73], 0, v[132:133]
	s_add_i32 m0, s71, 0x2000
	s_nop 0
	global_load_lds_dwordx4 v[222:223], off
	v_lshl_add_u64 v[222:223], s[46:47], 0, v[130:131]
	s_mov_b32 m0, s29
	s_nop 0
	global_load_lds_dwordx4 v[222:223], off
	s_mov_b32 m0, s55
	s_nop 0
	global_load_lds_dwordx4 v[224:225], off
	s_waitcnt vmcnt(8)
	s_waitcnt lgkmcnt(0)
	s_barrier
	v_mfma_f32_16x16x32_bf16 v[62:65], v[152:155], v[184:187], v[62:65]
	v_mfma_f32_16x16x32_bf16 v[58:61], v[160:163], v[184:187], v[58:61]
	v_mfma_f32_16x16x32_bf16 v[54:57], v[152:155], v[196:199], v[54:57]
	v_mfma_f32_16x16x32_bf16 v[46:49], v[160:163], v[196:199], v[46:49]
	v_mfma_f32_16x16x32_bf16 v[38:41], v[152:155], v[204:207], v[38:41]
	v_mfma_f32_16x16x32_bf16 v[30:33], v[160:163], v[204:207], v[30:33]
	v_mfma_f32_16x16x32_bf16 v[22:25], v[152:155], v[212:215], v[22:25]
	v_mfma_f32_16x16x32_bf16 v[14:17], v[160:163], v[212:215], v[14:17]
	v_mfma_f32_16x16x32_bf16 v[62:65], v[156:159], v[188:191], v[62:65]
	v_mfma_f32_16x16x32_bf16 v[58:61], v[164:167], v[188:191], v[58:61]
	v_mfma_f32_16x16x32_bf16 v[54:57], v[156:159], v[200:203], v[54:57]
	v_mfma_f32_16x16x32_bf16 v[46:49], v[164:167], v[200:203], v[46:49]
	v_mfma_f32_16x16x32_bf16 v[38:41], v[156:159], v[208:211], v[38:41]
	v_mfma_f32_16x16x32_bf16 v[30:33], v[164:167], v[208:211], v[30:33]
	v_mfma_f32_16x16x32_bf16 v[22:25], v[156:159], v[216:219], v[22:25]
	v_mfma_f32_16x16x32_bf16 v[14:17], v[164:167], v[216:219], v[14:17]
	v_mfma_f32_16x16x32_bf16 v[50:53], v[168:171], v[184:187], v[50:53]
	v_mfma_f32_16x16x32_bf16 v[42:45], v[176:179], v[184:187], v[42:45]
	v_mfma_f32_16x16x32_bf16 v[34:37], v[168:171], v[196:199], v[34:37]
	v_mfma_f32_16x16x32_bf16 v[26:29], v[176:179], v[196:199], v[26:29]
	v_mfma_f32_16x16x32_bf16 v[18:21], v[168:171], v[204:207], v[18:21]
	v_mfma_f32_16x16x32_bf16 v[10:13], v[176:179], v[204:207], v[10:13]
	v_mfma_f32_16x16x32_bf16 v[6:9], v[168:171], v[212:215], v[6:9]
	v_mfma_f32_16x16x32_bf16 v[2:5], v[176:179], v[212:215], v[2:5]
	v_mfma_f32_16x16x32_bf16 v[50:53], v[172:175], v[188:191], v[50:53]
	v_mfma_f32_16x16x32_bf16 v[42:45], v[180:183], v[188:191], v[42:45]
	v_mfma_f32_16x16x32_bf16 v[34:37], v[172:175], v[200:203], v[34:37]
	v_mfma_f32_16x16x32_bf16 v[26:29], v[180:183], v[200:203], v[26:29]
	v_mfma_f32_16x16x32_bf16 v[18:21], v[172:175], v[208:211], v[18:21]
	v_mfma_f32_16x16x32_bf16 v[10:13], v[180:183], v[208:211], v[10:13]
	v_mfma_f32_16x16x32_bf16 v[6:9], v[172:175], v[216:219], v[6:9]
	v_mfma_f32_16x16x32_bf16 v[2:5], v[180:183], v[216:219], v[2:5]
	s_barrier
	s_add_i32 s71, 0, 0x18000
	v_add_u32_e32 v151, s71, v142
	s_add_i32 s72, 0, 0x1c000
	ds_read_b128 v[152:155], v151
	ds_read_b128 v[156:159], v151 offset:1024
	ds_read_b128 v[160:163], v151 offset:2048
	ds_read_b128 v[164:167], v151 offset:3072
	v_add_u32_e32 v151, s72, v142
	ds_read_b128 v[168:171], v151
	ds_read_b128 v[172:175], v151 offset:1024
	ds_read_b128 v[176:179], v151 offset:2048
	ds_read_b128 v[180:183], v151 offset:3072
	s_add_u32 s46, s46, 0x100000
	s_addc_u32 s47, s47, 0
	s_mov_b32 m0, s56
	v_lshl_add_u64 v[226:227], s[46:47], 0, v[130:131]
	ds_read_b128 v[184:187], v150 offset:32768
	ds_read_b128 v[188:191], v150 offset:33792
	ds_read_b128 v[196:199], v150 offset:34816
	ds_read_b128 v[200:203], v150 offset:35840
	ds_read_b128 v[204:207], v150 offset:36864
	ds_read_b128 v[208:211], v150 offset:37888
	ds_read_b128 v[212:215], v150 offset:38912
	ds_read_b128 v[216:219], v150 offset:39936
	global_load_lds_dwordx4 v[226:227], off
	v_lshl_add_u64 v[226:227], s[46:47], 0, v[132:133]
	s_mov_b32 m0, s57
	s_nop 0
	global_load_lds_dwordx4 v[226:227], off
	s_waitcnt vmcnt(8)
	s_waitcnt lgkmcnt(0)
	s_barrier
	v_mfma_f32_16x16x32_bf16 v[126:129], v[152:155], v[184:187], v[126:129]
	v_mfma_f32_16x16x32_bf16 v[122:125], v[160:163], v[184:187], v[122:125]
	v_mfma_f32_16x16x32_bf16 v[118:121], v[152:155], v[196:199], v[118:121]
	v_mfma_f32_16x16x32_bf16 v[110:113], v[160:163], v[196:199], v[110:113]
	v_mfma_f32_16x16x32_bf16 v[102:105], v[152:155], v[204:207], v[102:105]
	v_mfma_f32_16x16x32_bf16 v[94:97], v[160:163], v[204:207], v[94:97]
	v_mfma_f32_16x16x32_bf16 v[86:89], v[152:155], v[212:215], v[86:89]
	v_mfma_f32_16x16x32_bf16 v[78:81], v[160:163], v[212:215], v[78:81]
	v_mfma_f32_16x16x32_bf16 v[126:129], v[156:159], v[188:191], v[126:129]
	v_mfma_f32_16x16x32_bf16 v[122:125], v[164:167], v[188:191], v[122:125]
	v_mfma_f32_16x16x32_bf16 v[118:121], v[156:159], v[200:203], v[118:121]
	v_mfma_f32_16x16x32_bf16 v[110:113], v[164:167], v[200:203], v[110:113]
	v_mfma_f32_16x16x32_bf16 v[102:105], v[156:159], v[208:211], v[102:105]
	v_mfma_f32_16x16x32_bf16 v[94:97], v[164:167], v[208:211], v[94:97]
	v_mfma_f32_16x16x32_bf16 v[86:89], v[156:159], v[216:219], v[86:89]
	v_mfma_f32_16x16x32_bf16 v[78:81], v[164:167], v[216:219], v[78:81]
	v_mfma_f32_16x16x32_bf16 v[114:117], v[168:171], v[184:187], v[114:117]
	v_mfma_f32_16x16x32_bf16 v[106:109], v[176:179], v[184:187], v[106:109]
	v_mfma_f32_16x16x32_bf16 v[98:101], v[168:171], v[196:199], v[98:101]
	v_mfma_f32_16x16x32_bf16 v[90:93], v[176:179], v[196:199], v[90:93]
	v_mfma_f32_16x16x32_bf16 v[82:85], v[168:171], v[204:207], v[82:85]
	v_mfma_f32_16x16x32_bf16 v[74:77], v[176:179], v[204:207], v[74:77]
	v_mfma_f32_16x16x32_bf16 v[70:73], v[168:171], v[212:215], v[70:73]
	v_mfma_f32_16x16x32_bf16 v[66:69], v[176:179], v[212:215], v[66:69]
	v_mfma_f32_16x16x32_bf16 v[114:117], v[172:175], v[188:191], v[114:117]
	v_mfma_f32_16x16x32_bf16 v[106:109], v[180:183], v[188:191], v[106:109]
	v_mfma_f32_16x16x32_bf16 v[98:101], v[172:175], v[200:203], v[98:101]
	v_mfma_f32_16x16x32_bf16 v[90:93], v[180:183], v[200:203], v[90:93]
	v_mfma_f32_16x16x32_bf16 v[82:85], v[172:175], v[208:211], v[82:85]
	v_mfma_f32_16x16x32_bf16 v[74:77], v[180:183], v[208:211], v[74:77]
	v_mfma_f32_16x16x32_bf16 v[70:73], v[172:175], v[216:219], v[70:73]
	v_mfma_f32_16x16x32_bf16 v[66:69], v[180:183], v[216:219], v[66:69]
	s_barrier
	s_add_i32 s46, s71, s54
	v_lshl_add_u64 v[192:193], v[192:193], 0, s[10:11]
	s_mov_b32 m0, s46
	ds_read_b128 v[184:187], v150 offset:49152
	ds_read_b128 v[188:191], v150 offset:50176
	ds_read_b128 v[196:199], v150 offset:51200
	ds_read_b128 v[200:203], v150 offset:52224
	ds_read_b128 v[204:207], v150 offset:53248
	ds_read_b128 v[208:211], v150 offset:54272
	ds_read_b128 v[212:215], v150 offset:55296
	ds_read_b128 v[216:219], v150 offset:56320
	global_load_lds_dwordx4 v[192:193], off
	s_add_i32 m0, s46, 0x2000
	s_add_u32 s42, s42, 0x100080
	v_lshl_add_u64 v[192:193], v[220:221], 0, s[10:11]
	s_addc_u32 s43, s43, 0
	s_add_i32 s46, s72, s54
	global_load_lds_dwordx4 v[192:193], off
	v_lshl_add_u64 v[192:193], s[42:43], 0, v[130:131]
	s_mov_b32 m0, s46
	s_nop 0
	global_load_lds_dwordx4 v[192:193], off
	v_lshl_add_u64 v[192:193], s[42:43], 0, v[132:133]
	s_add_i32 m0, s46, 0x2000
	s_nop 0
	global_load_lds_dwordx4 v[192:193], off
	v_lshl_add_u64 v[192:193], v[222:223], 0, s[10:11]
	s_mov_b32 m0, s59
	s_nop 0
	global_load_lds_dwordx4 v[192:193], off
	v_lshl_add_u64 v[192:193], v[224:225], 0, s[10:11]
	s_mov_b32 m0, s60
	s_nop 0
	global_load_lds_dwordx4 v[192:193], off
	s_nop 0
	s_waitcnt vmcnt(8)
	s_waitcnt lgkmcnt(0)
	s_barrier
	v_mfma_f32_16x16x32_bf16 v[62:65], v[152:155], v[184:187], v[62:65]
	v_mfma_f32_16x16x32_bf16 v[58:61], v[160:163], v[184:187], v[58:61]
	v_mfma_f32_16x16x32_bf16 v[54:57], v[152:155], v[196:199], v[54:57]
	v_mfma_f32_16x16x32_bf16 v[46:49], v[160:163], v[196:199], v[46:49]
	v_mfma_f32_16x16x32_bf16 v[38:41], v[152:155], v[204:207], v[38:41]
	v_mfma_f32_16x16x32_bf16 v[30:33], v[160:163], v[204:207], v[30:33]
	v_mfma_f32_16x16x32_bf16 v[22:25], v[152:155], v[212:215], v[22:25]
	v_mfma_f32_16x16x32_bf16 v[14:17], v[160:163], v[212:215], v[14:17]
	v_mfma_f32_16x16x32_bf16 v[62:65], v[156:159], v[188:191], v[62:65]
	v_mfma_f32_16x16x32_bf16 v[58:61], v[164:167], v[188:191], v[58:61]
	v_mfma_f32_16x16x32_bf16 v[54:57], v[156:159], v[200:203], v[54:57]
	v_mfma_f32_16x16x32_bf16 v[46:49], v[164:167], v[200:203], v[46:49]
	v_mfma_f32_16x16x32_bf16 v[38:41], v[156:159], v[208:211], v[38:41]
	v_mfma_f32_16x16x32_bf16 v[30:33], v[164:167], v[208:211], v[30:33]
	v_mfma_f32_16x16x32_bf16 v[22:25], v[156:159], v[216:219], v[22:25]
	v_mfma_f32_16x16x32_bf16 v[14:17], v[164:167], v[216:219], v[14:17]
	v_mfma_f32_16x16x32_bf16 v[50:53], v[168:171], v[184:187], v[50:53]
	v_mfma_f32_16x16x32_bf16 v[42:45], v[176:179], v[184:187], v[42:45]
	v_mfma_f32_16x16x32_bf16 v[34:37], v[168:171], v[196:199], v[34:37]
	v_mfma_f32_16x16x32_bf16 v[26:29], v[176:179], v[196:199], v[26:29]
	v_mfma_f32_16x16x32_bf16 v[18:21], v[168:171], v[204:207], v[18:21]
	v_mfma_f32_16x16x32_bf16 v[10:13], v[176:179], v[204:207], v[10:13]
	v_mfma_f32_16x16x32_bf16 v[6:9], v[168:171], v[212:215], v[6:9]
	v_mfma_f32_16x16x32_bf16 v[2:5], v[176:179], v[212:215], v[2:5]
	v_mfma_f32_16x16x32_bf16 v[50:53], v[172:175], v[188:191], v[50:53]
	v_mfma_f32_16x16x32_bf16 v[42:45], v[180:183], v[188:191], v[42:45]
	v_mfma_f32_16x16x32_bf16 v[34:37], v[172:175], v[200:203], v[34:37]
	v_mfma_f32_16x16x32_bf16 v[26:29], v[180:183], v[200:203], v[26:29]
	v_mfma_f32_16x16x32_bf16 v[18:21], v[172:175], v[208:211], v[18:21]
	v_mfma_f32_16x16x32_bf16 v[10:13], v[180:183], v[208:211], v[10:13]
	v_mfma_f32_16x16x32_bf16 v[6:9], v[172:175], v[216:219], v[6:9]
	v_mfma_f32_16x16x32_bf16 v[2:5], v[180:183], v[216:219], v[2:5]
	s_barrier
	s_add_i32 s70, s70, 2
	s_add_u32 s40, s40, 0x100
	s_addc_u32 s41, s41, 0
	s_add_u32 s68, s68, 0x100
	s_addc_u32 s69, s69, 0
	s_cmp_gt_u32 s70, 61
	s_cbranch_scc0 .LBB0_681
	s_and_b64 vcc, exec, s[12:13]
	s_cbranch_vccz .LBB0_684
	s_barrier

.LBB0_705:
	ds_read_b128 v[144:147], v139
	ds_read_b128 v[148:151], v139 offset:1024
	ds_read_b128 v[152:155], v139 offset:2048
	ds_read_b128 v[156:159], v139 offset:3072
	ds_read_b128 v[160:163], v140
	ds_read_b128 v[164:167], v140 offset:1024
	ds_read_b128 v[168:171], v140 offset:2048
	ds_read_b128 v[172:175], v140 offset:3072
	s_add_u32 s42, s40, 0xfff00080
	s_addc_u32 s43, s41, -1
	s_cmp_eq_u32 s67, 60
	s_cselect_b32 s47, s27, s43
	s_cselect_b32 s46, s63, s42
	s_cselect_b32 s43, s25, s66
	s_cselect_b32 s42, s64, s65
	v_lshl_add_u64 v[192:193], s[40:41], 0, v[134:135]
	s_add_i32 m0, s29, 0xc000
	ds_read_b128 v[176:179], v142
	ds_read_b128 v[180:183], v142 offset:1024
	ds_read_b128 v[184:187], v142 offset:2048
	ds_read_b128 v[188:191], v142 offset:3072
	ds_read_b128 v[196:199], v142 offset:4096
	ds_read_b128 v[200:203], v142 offset:5120
	ds_read_b128 v[204:207], v142 offset:6144
	ds_read_b128 v[208:211], v142 offset:7168
	global_load_lds_dwordx4 v[192:193], off
	v_lshl_add_u64 v[192:193], s[40:41], 0, v[136:137]
	s_add_i32 m0, s29, 0xe000
	s_nop 0
	global_load_lds_dwordx4 v[192:193], off
	s_nop 0
	s_waitcnt vmcnt(8)
	s_waitcnt lgkmcnt(0)
	s_barrier
	v_mfma_f32_16x16x32_bf16 v[126:129], v[144:147], v[176:179], v[126:129]
	v_mfma_f32_16x16x32_bf16 v[122:125], v[152:155], v[176:179], v[122:125]
	v_mfma_f32_16x16x32_bf16 v[118:121], v[144:147], v[184:187], v[118:121]
	v_mfma_f32_16x16x32_bf16 v[110:113], v[152:155], v[184:187], v[110:113]
	v_mfma_f32_16x16x32_bf16 v[102:105], v[144:147], v[196:199], v[102:105]
	v_mfma_f32_16x16x32_bf16 v[94:97], v[152:155], v[196:199], v[94:97]
	v_mfma_f32_16x16x32_bf16 v[86:89], v[144:147], v[204:207], v[86:89]
	v_mfma_f32_16x16x32_bf16 v[78:81], v[152:155], v[204:207], v[78:81]
	v_mfma_f32_16x16x32_bf16 v[126:129], v[148:151], v[180:183], v[126:129]
	v_mfma_f32_16x16x32_bf16 v[122:125], v[156:159], v[180:183], v[122:125]
	v_mfma_f32_16x16x32_bf16 v[118:121], v[148:151], v[188:191], v[118:121]
	v_mfma_f32_16x16x32_bf16 v[110:113], v[156:159], v[188:191], v[110:113]
	v_mfma_f32_16x16x32_bf16 v[102:105], v[148:151], v[200:203], v[102:105]
	v_mfma_f32_16x16x32_bf16 v[94:97], v[156:159], v[200:203], v[94:97]
	v_mfma_f32_16x16x32_bf16 v[86:89], v[148:151], v[208:211], v[86:89]
	v_mfma_f32_16x16x32_bf16 v[78:81], v[156:159], v[208:211], v[78:81]
	v_mfma_f32_16x16x32_bf16 v[114:117], v[160:163], v[176:179], v[114:117]
	v_mfma_f32_16x16x32_bf16 v[106:109], v[168:171], v[176:179], v[106:109]
	v_mfma_f32_16x16x32_bf16 v[98:101], v[160:163], v[184:187], v[98:101]
	v_mfma_f32_16x16x32_bf16 v[90:93], v[168:171], v[184:187], v[90:93]
	v_mfma_f32_16x16x32_bf16 v[82:85], v[160:163], v[196:199], v[82:85]
	v_mfma_f32_16x16x32_bf16 v[74:77], v[168:171], v[196:199], v[74:77]
	v_mfma_f32_16x16x32_bf16 v[70:73], v[160:163], v[204:207], v[70:73]
	v_mfma_f32_16x16x32_bf16 v[66:69], v[168:171], v[204:207], v[66:69]
	v_mfma_f32_16x16x32_bf16 v[114:117], v[164:167], v[180:183], v[114:117]
	v_mfma_f32_16x16x32_bf16 v[106:109], v[172:175], v[180:183], v[106:109]
	v_mfma_f32_16x16x32_bf16 v[98:101], v[164:167], v[188:191], v[98:101]
	v_mfma_f32_16x16x32_bf16 v[90:93], v[172:175], v[188:191], v[90:93]
	v_mfma_f32_16x16x32_bf16 v[82:85], v[164:167], v[200:203], v[82:85]
	v_mfma_f32_16x16x32_bf16 v[74:77], v[172:175], v[200:203], v[74:77]
	v_mfma_f32_16x16x32_bf16 v[70:73], v[164:167], v[208:211], v[70:73]
	v_mfma_f32_16x16x32_bf16 v[66:69], v[172:175], v[208:211], v[66:69]
	s_barrier
	s_add_i32 s68, s59, s51
	v_lshl_add_u64 v[192:193], s[42:43], 0, v[130:131]
	s_mov_b32 m0, s68
	ds_read_b128 v[176:179], v142 offset:16384
	ds_read_b128 v[180:183], v142 offset:17408
	ds_read_b128 v[184:187], v142 offset:18432
	ds_read_b128 v[188:191], v142 offset:19456
	ds_read_b128 v[196:199], v142 offset:20480
	ds_read_b128 v[200:203], v142 offset:21504
	ds_read_b128 v[204:207], v142 offset:22528
	ds_read_b128 v[208:211], v142 offset:23552
	global_load_lds_dwordx4 v[192:193], off
	s_add_i32 m0, s68, 0x2000
	s_add_u32 s68, s42, 0x100000
	v_lshl_add_u64 v[212:213], s[42:43], 0, v[132:133]
	s_addc_u32 s69, s43, 0
	s_add_i32 s70, s60, s51
	global_load_lds_dwordx4 v[212:213], off
	v_lshl_add_u64 v[214:215], s[68:69], 0, v[130:131]
	s_mov_b32 m0, s70
	v_lshl_add_u64 v[216:217], s[46:47], 0, v[132:133]
	global_load_lds_dwordx4 v[214:215], off
	v_lshl_add_u64 v[214:215], s[68:69], 0, v[132:133]
	s_add_i32 m0, s70, 0x2000
	s_nop 0
	global_load_lds_dwordx4 v[214:215], off
	v_lshl_add_u64 v[214:215], s[46:47], 0, v[130:131]
	s_mov_b32 m0, s29
	s_nop 0
	global_load_lds_dwordx4 v[214:215], off
	s_mov_b32 m0, s52
	s_nop 0
	global_load_lds_dwordx4 v[216:217], off
	s_waitcnt vmcnt(8)
	s_waitcnt lgkmcnt(0)
	s_barrier
	v_mfma_f32_16x16x32_bf16 v[62:65], v[144:147], v[176:179], v[62:65]
	v_mfma_f32_16x16x32_bf16 v[58:61], v[152:155], v[176:179], v[58:61]
	v_mfma_f32_16x16x32_bf16 v[54:57], v[144:147], v[184:187], v[54:57]
	v_mfma_f32_16x16x32_bf16 v[46:49], v[152:155], v[184:187], v[46:49]
	v_mfma_f32_16x16x32_bf16 v[38:41], v[144:147], v[196:199], v[38:41]
	v_mfma_f32_16x16x32_bf16 v[30:33], v[152:155], v[196:199], v[30:33]
	v_mfma_f32_16x16x32_bf16 v[22:25], v[144:147], v[204:207], v[22:25]
	v_mfma_f32_16x16x32_bf16 v[14:17], v[152:155], v[204:207], v[14:17]
	v_mfma_f32_16x16x32_bf16 v[62:65], v[148:151], v[180:183], v[62:65]
	v_mfma_f32_16x16x32_bf16 v[58:61], v[156:159], v[180:183], v[58:61]
	v_mfma_f32_16x16x32_bf16 v[54:57], v[148:151], v[188:191], v[54:57]
	v_mfma_f32_16x16x32_bf16 v[46:49], v[156:159], v[188:191], v[46:49]
	v_mfma_f32_16x16x32_bf16 v[38:41], v[148:151], v[200:203], v[38:41]
	v_mfma_f32_16x16x32_bf16 v[30:33], v[156:159], v[200:203], v[30:33]
	v_mfma_f32_16x16x32_bf16 v[22:25], v[148:151], v[208:211], v[22:25]
	v_mfma_f32_16x16x32_bf16 v[14:17], v[156:159], v[208:211], v[14:17]
	v_mfma_f32_16x16x32_bf16 v[50:53], v[160:163], v[176:179], v[50:53]
	v_mfma_f32_16x16x32_bf16 v[42:45], v[168:171], v[176:179], v[42:45]
	v_mfma_f32_16x16x32_bf16 v[34:37], v[160:163], v[184:187], v[34:37]
	v_mfma_f32_16x16x32_bf16 v[26:29], v[168:171], v[184:187], v[26:29]
	v_mfma_f32_16x16x32_bf16 v[18:21], v[160:163], v[196:199], v[18:21]
	v_mfma_f32_16x16x32_bf16 v[10:13], v[168:171], v[196:199], v[10:13]
	v_mfma_f32_16x16x32_bf16 v[6:9], v[160:163], v[204:207], v[6:9]
	v_mfma_f32_16x16x32_bf16 v[2:5], v[168:171], v[204:207], v[2:5]
	v_mfma_f32_16x16x32_bf16 v[50:53], v[164:167], v[180:183], v[50:53]
	v_mfma_f32_16x16x32_bf16 v[42:45], v[172:175], v[180:183], v[42:45]
	v_mfma_f32_16x16x32_bf16 v[34:37], v[164:167], v[188:191], v[34:37]
	v_mfma_f32_16x16x32_bf16 v[26:29], v[172:175], v[188:191], v[26:29]
	v_mfma_f32_16x16x32_bf16 v[18:21], v[164:167], v[200:203], v[18:21]
	v_mfma_f32_16x16x32_bf16 v[10:13], v[172:175], v[200:203], v[10:13]
	v_mfma_f32_16x16x32_bf16 v[6:9], v[164:167], v[208:211], v[6:9]
	v_mfma_f32_16x16x32_bf16 v[2:5], v[172:175], v[208:211], v[2:5]
	s_barrier
	s_add_i32 s68, 0, 0x18000
	v_add_u32_e32 v143, s68, v1
	s_add_i32 s69, 0, 0x1c000
	ds_read_b128 v[144:147], v143
	ds_read_b128 v[148:151], v143 offset:1024
	ds_read_b128 v[152:155], v143 offset:2048
	ds_read_b128 v[156:159], v143 offset:3072
	v_add_u32_e32 v143, s69, v1
	ds_read_b128 v[160:163], v143
	ds_read_b128 v[164:167], v143 offset:1024
	ds_read_b128 v[168:171], v143 offset:2048
	ds_read_b128 v[172:175], v143 offset:3072
	s_add_u32 s46, s46, 0x100000
	s_addc_u32 s47, s47, 0
	s_mov_b32 m0, s53
	v_lshl_add_u64 v[218:219], s[46:47], 0, v[130:131]
	ds_read_b128 v[176:179], v142 offset:32768
	ds_read_b128 v[180:183], v142 offset:33792
	ds_read_b128 v[184:187], v142 offset:34816
	ds_read_b128 v[188:191], v142 offset:35840
	ds_read_b128 v[196:199], v142 offset:36864
	ds_read_b128 v[200:203], v142 offset:37888
	ds_read_b128 v[204:207], v142 offset:38912
	ds_read_b128 v[208:211], v142 offset:39936
	global_load_lds_dwordx4 v[218:219], off
	v_lshl_add_u64 v[218:219], s[46:47], 0, v[132:133]
	s_mov_b32 m0, s54
	s_nop 0
	global_load_lds_dwordx4 v[218:219], off
	s_waitcnt vmcnt(8)
	s_waitcnt lgkmcnt(0)
	s_barrier
	v_mfma_f32_16x16x32_bf16 v[126:129], v[144:147], v[176:179], v[126:129]
	v_mfma_f32_16x16x32_bf16 v[122:125], v[152:155], v[176:179], v[122:125]
	v_mfma_f32_16x16x32_bf16 v[118:121], v[144:147], v[184:187], v[118:121]
	v_mfma_f32_16x16x32_bf16 v[110:113], v[152:155], v[184:187], v[110:113]
	v_mfma_f32_16x16x32_bf16 v[102:105], v[144:147], v[196:199], v[102:105]
	v_mfma_f32_16x16x32_bf16 v[94:97], v[152:155], v[196:199], v[94:97]
	v_mfma_f32_16x16x32_bf16 v[86:89], v[144:147], v[204:207], v[86:89]
	v_mfma_f32_16x16x32_bf16 v[78:81], v[152:155], v[204:207], v[78:81]
	v_mfma_f32_16x16x32_bf16 v[126:129], v[148:151], v[180:183], v[126:129]
	v_mfma_f32_16x16x32_bf16 v[122:125], v[156:159], v[180:183], v[122:125]
	v_mfma_f32_16x16x32_bf16 v[118:121], v[148:151], v[188:191], v[118:121]
	v_mfma_f32_16x16x32_bf16 v[110:113], v[156:159], v[188:191], v[110:113]
	v_mfma_f32_16x16x32_bf16 v[102:105], v[148:151], v[200:203], v[102:105]
	v_mfma_f32_16x16x32_bf16 v[94:97], v[156:159], v[200:203], v[94:97]
	v_mfma_f32_16x16x32_bf16 v[86:89], v[148:151], v[208:211], v[86:89]
	v_mfma_f32_16x16x32_bf16 v[78:81], v[156:159], v[208:211], v[78:81]
	v_mfma_f32_16x16x32_bf16 v[114:117], v[160:163], v[176:179], v[114:117]
	v_mfma_f32_16x16x32_bf16 v[106:109], v[168:171], v[176:179], v[106:109]
	v_mfma_f32_16x16x32_bf16 v[98:101], v[160:163], v[184:187], v[98:101]
	v_mfma_f32_16x16x32_bf16 v[90:93], v[168:171], v[184:187], v[90:93]
	v_mfma_f32_16x16x32_bf16 v[82:85], v[160:163], v[196:199], v[82:85]
	v_mfma_f32_16x16x32_bf16 v[74:77], v[168:171], v[196:199], v[74:77]
	v_mfma_f32_16x16x32_bf16 v[70:73], v[160:163], v[204:207], v[70:73]
	v_mfma_f32_16x16x32_bf16 v[66:69], v[168:171], v[204:207], v[66:69]
	v_mfma_f32_16x16x32_bf16 v[114:117], v[164:167], v[180:183], v[114:117]
	v_mfma_f32_16x16x32_bf16 v[106:109], v[172:175], v[180:183], v[106:109]
	v_mfma_f32_16x16x32_bf16 v[98:101], v[164:167], v[188:191], v[98:101]
	v_mfma_f32_16x16x32_bf16 v[90:93], v[172:175], v[188:191], v[90:93]
	v_mfma_f32_16x16x32_bf16 v[82:85], v[164:167], v[200:203], v[82:85]
	v_mfma_f32_16x16x32_bf16 v[74:77], v[172:175], v[200:203], v[74:77]
	v_mfma_f32_16x16x32_bf16 v[70:73], v[164:167], v[208:211], v[70:73]
	v_mfma_f32_16x16x32_bf16 v[66:69], v[172:175], v[208:211], v[66:69]
	s_barrier
	s_add_i32 s46, s68, s51
	v_lshl_add_u64 v[192:193], v[192:193], 0, s[10:11]
	s_mov_b32 m0, s46
	ds_read_b128 v[176:179], v142 offset:49152
	ds_read_b128 v[180:183], v142 offset:50176
	ds_read_b128 v[184:187], v142 offset:51200
	ds_read_b128 v[188:191], v142 offset:52224
	ds_read_b128 v[196:199], v142 offset:53248
	ds_read_b128 v[200:203], v142 offset:54272
	ds_read_b128 v[204:207], v142 offset:55296
	ds_read_b128 v[208:211], v142 offset:56320
	global_load_lds_dwordx4 v[192:193], off
	s_add_i32 m0, s46, 0x2000
	s_add_u32 s42, s42, 0x100080
	v_lshl_add_u64 v[192:193], v[212:213], 0, s[10:11]
	s_addc_u32 s43, s43, 0
	s_add_i32 s46, s69, s51
	global_load_lds_dwordx4 v[192:193], off
	v_lshl_add_u64 v[192:193], s[42:43], 0, v[130:131]
	s_mov_b32 m0, s46
	s_nop 0
	global_load_lds_dwordx4 v[192:193], off
	v_lshl_add_u64 v[192:193], s[42:43], 0, v[132:133]
	s_add_i32 m0, s46, 0x2000
	s_nop 0
	global_load_lds_dwordx4 v[192:193], off
	v_lshl_add_u64 v[192:193], v[214:215], 0, s[10:11]
	s_mov_b32 m0, s56
	s_nop 0
	global_load_lds_dwordx4 v[192:193], off
	v_lshl_add_u64 v[192:193], v[216:217], 0, s[10:11]
	s_mov_b32 m0, s57
	s_nop 0
	global_load_lds_dwordx4 v[192:193], off
	s_nop 0
	s_waitcnt vmcnt(8)
	s_waitcnt lgkmcnt(0)
	s_barrier
	v_mfma_f32_16x16x32_bf16 v[62:65], v[144:147], v[176:179], v[62:65]
	v_mfma_f32_16x16x32_bf16 v[58:61], v[152:155], v[176:179], v[58:61]
	v_mfma_f32_16x16x32_bf16 v[54:57], v[144:147], v[184:187], v[54:57]
	v_mfma_f32_16x16x32_bf16 v[46:49], v[152:155], v[184:187], v[46:49]
	v_mfma_f32_16x16x32_bf16 v[38:41], v[144:147], v[196:199], v[38:41]
	v_mfma_f32_16x16x32_bf16 v[30:33], v[152:155], v[196:199], v[30:33]
	v_mfma_f32_16x16x32_bf16 v[22:25], v[144:147], v[204:207], v[22:25]
	v_mfma_f32_16x16x32_bf16 v[14:17], v[152:155], v[204:207], v[14:17]
	v_mfma_f32_16x16x32_bf16 v[62:65], v[148:151], v[180:183], v[62:65]
	v_mfma_f32_16x16x32_bf16 v[58:61], v[156:159], v[180:183], v[58:61]
	v_mfma_f32_16x16x32_bf16 v[54:57], v[148:151], v[188:191], v[54:57]
	v_mfma_f32_16x16x32_bf16 v[46:49], v[156:159], v[188:191], v[46:49]
	v_mfma_f32_16x16x32_bf16 v[38:41], v[148:151], v[200:203], v[38:41]
	v_mfma_f32_16x16x32_bf16 v[30:33], v[156:159], v[200:203], v[30:33]
	v_mfma_f32_16x16x32_bf16 v[22:25], v[148:151], v[208:211], v[22:25]
	v_mfma_f32_16x16x32_bf16 v[14:17], v[156:159], v[208:211], v[14:17]
	v_mfma_f32_16x16x32_bf16 v[50:53], v[160:163], v[176:179], v[50:53]
	v_mfma_f32_16x16x32_bf16 v[42:45], v[168:171], v[176:179], v[42:45]
	v_mfma_f32_16x16x32_bf16 v[34:37], v[160:163], v[184:187], v[34:37]
	v_mfma_f32_16x16x32_bf16 v[26:29], v[168:171], v[184:187], v[26:29]
	v_mfma_f32_16x16x32_bf16 v[18:21], v[160:163], v[196:199], v[18:21]
	v_mfma_f32_16x16x32_bf16 v[10:13], v[168:171], v[196:199], v[10:13]
	v_mfma_f32_16x16x32_bf16 v[6:9], v[160:163], v[204:207], v[6:9]
	v_mfma_f32_16x16x32_bf16 v[2:5], v[168:171], v[204:207], v[2:5]
	v_mfma_f32_16x16x32_bf16 v[50:53], v[164:167], v[180:183], v[50:53]
	v_mfma_f32_16x16x32_bf16 v[42:45], v[172:175], v[180:183], v[42:45]
	v_mfma_f32_16x16x32_bf16 v[34:37], v[164:167], v[188:191], v[34:37]
	v_mfma_f32_16x16x32_bf16 v[26:29], v[172:175], v[188:191], v[26:29]
	v_mfma_f32_16x16x32_bf16 v[18:21], v[164:167], v[200:203], v[18:21]
	v_mfma_f32_16x16x32_bf16 v[10:13], v[172:175], v[200:203], v[10:13]
	v_mfma_f32_16x16x32_bf16 v[6:9], v[164:167], v[208:211], v[6:9]
	v_mfma_f32_16x16x32_bf16 v[2:5], v[172:175], v[208:211], v[2:5]
	s_barrier
	s_add_i32 s67, s67, 2
	s_add_u32 s40, s40, 0x100
	s_addc_u32 s41, s41, 0
	s_add_u32 s65, s65, 0x100
	s_addc_u32 s66, s66, 0
	s_cmp_gt_u32 s67, 61
	s_cbranch_scc0 .LBB0_705
	s_and_b64 vcc, exec, s[12:13]
	s_cbranch_vccz .LBB0_708
	s_barrier

.LBB0_967:
	ds_read_b128 v[146:149], v152
	ds_read_b128 v[156:159], v152 offset:1024
	ds_read_b128 v[160:163], v152 offset:2048
	ds_read_b128 v[164:167], v152 offset:3072
	ds_read_b128 v[168:171], v153
	ds_read_b128 v[172:175], v153 offset:1024
	ds_read_b128 v[176:179], v153 offset:2048
	ds_read_b128 v[180:183], v153 offset:3072
	s_add_u32 s30, s28, 0xfff80080
	s_addc_u32 s31, s29, -1
	s_cmp_eq_u32 s57, 28
	s_cselect_b32 s35, s21, s31
	s_cselect_b32 s34, s53, s30
	s_cselect_b32 s31, s19, s56
	s_cselect_b32 s30, s54, s55
	v_lshl_add_u64 v[192:193], s[28:29], 0, v[138:139]
	s_add_i32 m0, s27, 0xc000
	ds_read_b128 v[184:187], v154
	ds_read_b128 v[188:191], v154 offset:1024
	ds_read_b128 v[196:199], v154 offset:2048
	ds_read_b128 v[200:203], v154 offset:3072
	ds_read_b128 v[206:209], v154 offset:4096
	ds_read_b128 v[210:213], v154 offset:5120
	ds_read_b128 v[214:217], v154 offset:6144
	ds_read_b128 v[218:221], v154 offset:7168
	global_load_lds_dwordx4 v[192:193], off
	v_lshl_add_u64 v[192:193], s[28:29], 0, v[140:141]
	s_add_i32 m0, s27, 0xe000
	s_nop 0
	global_load_lds_dwordx4 v[192:193], off
	s_nop 0
	s_waitcnt vmcnt(8)
	s_waitcnt lgkmcnt(0)
	s_barrier
	v_mfma_f32_16x16x32_bf16 v[126:129], v[146:149], v[184:187], v[126:129]
	v_mfma_f32_16x16x32_bf16 v[122:125], v[160:163], v[184:187], v[122:125]
	v_mfma_f32_16x16x32_bf16 v[110:113], v[146:149], v[196:199], v[110:113]
	v_mfma_f32_16x16x32_bf16 v[106:109], v[160:163], v[196:199], v[106:109]
	v_mfma_f32_16x16x32_bf16 v[98:101], v[146:149], v[206:209], v[98:101]
	v_mfma_f32_16x16x32_bf16 v[90:93], v[160:163], v[206:209], v[90:93]
	v_mfma_f32_16x16x32_bf16 v[78:81], v[146:149], v[214:217], v[78:81]
	v_mfma_f32_16x16x32_bf16 v[74:77], v[160:163], v[214:217], v[74:77]
	v_mfma_f32_16x16x32_bf16 v[126:129], v[156:159], v[188:191], v[126:129]
	v_mfma_f32_16x16x32_bf16 v[122:125], v[164:167], v[188:191], v[122:125]
	v_mfma_f32_16x16x32_bf16 v[110:113], v[156:159], v[200:203], v[110:113]
	v_mfma_f32_16x16x32_bf16 v[106:109], v[164:167], v[200:203], v[106:109]
	v_mfma_f32_16x16x32_bf16 v[98:101], v[156:159], v[210:213], v[98:101]
	v_mfma_f32_16x16x32_bf16 v[90:93], v[164:167], v[210:213], v[90:93]
	v_mfma_f32_16x16x32_bf16 v[78:81], v[156:159], v[218:221], v[78:81]
	v_mfma_f32_16x16x32_bf16 v[74:77], v[164:167], v[218:221], v[74:77]
	v_mfma_f32_16x16x32_bf16 v[118:121], v[168:171], v[184:187], v[118:121]
	v_mfma_f32_16x16x32_bf16 v[114:117], v[176:179], v[184:187], v[114:117]
	v_mfma_f32_16x16x32_bf16 v[102:105], v[168:171], v[196:199], v[102:105]
	v_mfma_f32_16x16x32_bf16 v[94:97], v[176:179], v[196:199], v[94:97]
	v_mfma_f32_16x16x32_bf16 v[86:89], v[168:171], v[206:209], v[86:89]
	v_mfma_f32_16x16x32_bf16 v[82:85], v[176:179], v[206:209], v[82:85]
	v_mfma_f32_16x16x32_bf16 v[70:73], v[168:171], v[214:217], v[70:73]
	v_mfma_f32_16x16x32_bf16 v[66:69], v[176:179], v[214:217], v[66:69]
	v_mfma_f32_16x16x32_bf16 v[118:121], v[172:175], v[188:191], v[118:121]
	v_mfma_f32_16x16x32_bf16 v[114:117], v[180:183], v[188:191], v[114:117]
	v_mfma_f32_16x16x32_bf16 v[102:105], v[172:175], v[200:203], v[102:105]
	v_mfma_f32_16x16x32_bf16 v[94:97], v[180:183], v[200:203], v[94:97]
	v_mfma_f32_16x16x32_bf16 v[86:89], v[172:175], v[210:213], v[86:89]
	v_mfma_f32_16x16x32_bf16 v[82:85], v[180:183], v[210:213], v[82:85]
	v_mfma_f32_16x16x32_bf16 v[70:73], v[172:175], v[218:221], v[70:73]
	v_mfma_f32_16x16x32_bf16 v[66:69], v[180:183], v[218:221], v[66:69]
	s_barrier
	s_add_i32 s58, s50, s40
	v_lshl_add_u64 v[192:193], s[30:31], 0, v[134:135]
	s_mov_b32 m0, s58
	ds_read_b128 v[184:187], v154 offset:16384
	ds_read_b128 v[188:191], v154 offset:17408
	ds_read_b128 v[196:199], v154 offset:18432
	ds_read_b128 v[200:203], v154 offset:19456
	ds_read_b128 v[206:209], v154 offset:20480
	ds_read_b128 v[210:213], v154 offset:21504
	ds_read_b128 v[214:217], v154 offset:22528
	ds_read_b128 v[218:221], v154 offset:23552
	global_load_lds_dwordx4 v[192:193], off
	s_add_i32 m0, s58, 0x2000
	s_add_u32 s58, s30, 0x80000
	v_lshl_add_u64 v[222:223], s[30:31], 0, v[130:131]
	s_addc_u32 s59, s31, 0
	s_add_i32 s60, s51, s40
	global_load_lds_dwordx4 v[222:223], off
	v_lshl_add_u64 v[224:225], s[58:59], 0, v[134:135]
	s_mov_b32 m0, s60
	v_lshl_add_u64 v[226:227], s[34:35], 0, v[132:133]
	global_load_lds_dwordx4 v[224:225], off
	v_lshl_add_u64 v[224:225], s[58:59], 0, v[130:131]
	s_add_i32 m0, s60, 0x2000
	s_nop 0
	global_load_lds_dwordx4 v[224:225], off
	v_lshl_add_u64 v[224:225], s[34:35], 0, v[136:137]
	s_mov_b32 m0, s27
	s_nop 0
	global_load_lds_dwordx4 v[224:225], off
	s_mov_b32 m0, s42
	s_nop 0
	global_load_lds_dwordx4 v[226:227], off
	s_waitcnt vmcnt(8)
	s_waitcnt lgkmcnt(0)
	s_barrier
	v_mfma_f32_16x16x32_bf16 v[62:65], v[146:149], v[184:187], v[62:65]
	v_mfma_f32_16x16x32_bf16 v[58:61], v[160:163], v[184:187], v[58:61]
	v_mfma_f32_16x16x32_bf16 v[46:49], v[146:149], v[196:199], v[46:49]
	v_mfma_f32_16x16x32_bf16 v[42:45], v[160:163], v[196:199], v[42:45]
	v_mfma_f32_16x16x32_bf16 v[30:33], v[146:149], v[206:209], v[30:33]
	v_mfma_f32_16x16x32_bf16 v[26:29], v[160:163], v[206:209], v[26:29]
	v_mfma_f32_16x16x32_bf16 v[14:17], v[146:149], v[214:217], v[14:17]
	v_mfma_f32_16x16x32_bf16 v[10:13], v[160:163], v[214:217], v[10:13]
	v_mfma_f32_16x16x32_bf16 v[62:65], v[156:159], v[188:191], v[62:65]
	v_mfma_f32_16x16x32_bf16 v[58:61], v[164:167], v[188:191], v[58:61]
	v_mfma_f32_16x16x32_bf16 v[46:49], v[156:159], v[200:203], v[46:49]
	v_mfma_f32_16x16x32_bf16 v[42:45], v[164:167], v[200:203], v[42:45]
	v_mfma_f32_16x16x32_bf16 v[30:33], v[156:159], v[210:213], v[30:33]
	v_mfma_f32_16x16x32_bf16 v[26:29], v[164:167], v[210:213], v[26:29]
	v_mfma_f32_16x16x32_bf16 v[14:17], v[156:159], v[218:221], v[14:17]
	v_mfma_f32_16x16x32_bf16 v[10:13], v[164:167], v[218:221], v[10:13]
	v_mfma_f32_16x16x32_bf16 v[54:57], v[168:171], v[184:187], v[54:57]
	v_mfma_f32_16x16x32_bf16 v[50:53], v[176:179], v[184:187], v[50:53]
	v_mfma_f32_16x16x32_bf16 v[38:41], v[168:171], v[196:199], v[38:41]
	v_mfma_f32_16x16x32_bf16 v[34:37], v[176:179], v[196:199], v[34:37]
	v_mfma_f32_16x16x32_bf16 v[22:25], v[168:171], v[206:209], v[22:25]
	v_mfma_f32_16x16x32_bf16 v[18:21], v[176:179], v[206:209], v[18:21]
	v_mfma_f32_16x16x32_bf16 v[6:9], v[168:171], v[214:217], v[6:9]
	v_mfma_f32_16x16x32_bf16 v[2:5], v[176:179], v[214:217], v[2:5]
	v_mfma_f32_16x16x32_bf16 v[54:57], v[172:175], v[188:191], v[54:57]
	v_mfma_f32_16x16x32_bf16 v[50:53], v[180:183], v[188:191], v[50:53]
	v_mfma_f32_16x16x32_bf16 v[38:41], v[172:175], v[200:203], v[38:41]
	v_mfma_f32_16x16x32_bf16 v[34:37], v[180:183], v[200:203], v[34:37]
	v_mfma_f32_16x16x32_bf16 v[22:25], v[172:175], v[210:213], v[22:25]
	v_mfma_f32_16x16x32_bf16 v[18:21], v[180:183], v[210:213], v[18:21]
	v_mfma_f32_16x16x32_bf16 v[6:9], v[172:175], v[218:221], v[6:9]
	v_mfma_f32_16x16x32_bf16 v[2:5], v[180:183], v[218:221], v[2:5]
	s_barrier
	s_add_i32 s58, 0, 0x18000
	v_add_u32_e32 v155, s58, v150
	s_add_i32 s59, 0, 0x1c000
	ds_read_b128 v[146:149], v155
	ds_read_b128 v[156:159], v155 offset:1024
	ds_read_b128 v[160:163], v155 offset:2048
	ds_read_b128 v[164:167], v155 offset:3072
	v_add_u32_e32 v155, s59, v150
	ds_read_b128 v[168:171], v155
	ds_read_b128 v[172:175], v155 offset:1024
	ds_read_b128 v[176:179], v155 offset:2048
	ds_read_b128 v[180:183], v155 offset:3072
	s_add_u32 s34, s34, 0x80000
	s_addc_u32 s35, s35, 0
	s_mov_b32 m0, s43
	v_lshl_add_u64 v[228:229], s[34:35], 0, v[136:137]
	ds_read_b128 v[184:187], v154 offset:32768
	ds_read_b128 v[188:191], v154 offset:33792
	ds_read_b128 v[196:199], v154 offset:34816
	ds_read_b128 v[200:203], v154 offset:35840
	ds_read_b128 v[206:209], v154 offset:36864
	ds_read_b128 v[210:213], v154 offset:37888
	ds_read_b128 v[214:217], v154 offset:38912
	ds_read_b128 v[218:221], v154 offset:39936
	global_load_lds_dwordx4 v[228:229], off
	v_lshl_add_u64 v[228:229], s[34:35], 0, v[132:133]
	s_mov_b32 m0, s45
	s_nop 0
	global_load_lds_dwordx4 v[228:229], off
	s_waitcnt vmcnt(8)
	s_waitcnt lgkmcnt(0)
	s_barrier
	v_mfma_f32_16x16x32_bf16 v[126:129], v[146:149], v[184:187], v[126:129]
	v_mfma_f32_16x16x32_bf16 v[122:125], v[160:163], v[184:187], v[122:125]
	v_mfma_f32_16x16x32_bf16 v[110:113], v[146:149], v[196:199], v[110:113]
	v_mfma_f32_16x16x32_bf16 v[106:109], v[160:163], v[196:199], v[106:109]
	v_mfma_f32_16x16x32_bf16 v[98:101], v[146:149], v[206:209], v[98:101]
	v_mfma_f32_16x16x32_bf16 v[90:93], v[160:163], v[206:209], v[90:93]
	v_mfma_f32_16x16x32_bf16 v[78:81], v[146:149], v[214:217], v[78:81]
	v_mfma_f32_16x16x32_bf16 v[74:77], v[160:163], v[214:217], v[74:77]
	v_mfma_f32_16x16x32_bf16 v[126:129], v[156:159], v[188:191], v[126:129]
	v_mfma_f32_16x16x32_bf16 v[122:125], v[164:167], v[188:191], v[122:125]
	v_mfma_f32_16x16x32_bf16 v[110:113], v[156:159], v[200:203], v[110:113]
	v_mfma_f32_16x16x32_bf16 v[106:109], v[164:167], v[200:203], v[106:109]
	v_mfma_f32_16x16x32_bf16 v[98:101], v[156:159], v[210:213], v[98:101]
	v_mfma_f32_16x16x32_bf16 v[90:93], v[164:167], v[210:213], v[90:93]
	v_mfma_f32_16x16x32_bf16 v[78:81], v[156:159], v[218:221], v[78:81]
	v_mfma_f32_16x16x32_bf16 v[74:77], v[164:167], v[218:221], v[74:77]
	v_mfma_f32_16x16x32_bf16 v[118:121], v[168:171], v[184:187], v[118:121]
	v_mfma_f32_16x16x32_bf16 v[114:117], v[176:179], v[184:187], v[114:117]
	v_mfma_f32_16x16x32_bf16 v[102:105], v[168:171], v[196:199], v[102:105]
	v_mfma_f32_16x16x32_bf16 v[94:97], v[176:179], v[196:199], v[94:97]
	v_mfma_f32_16x16x32_bf16 v[86:89], v[168:171], v[206:209], v[86:89]
	v_mfma_f32_16x16x32_bf16 v[82:85], v[176:179], v[206:209], v[82:85]
	v_mfma_f32_16x16x32_bf16 v[70:73], v[168:171], v[214:217], v[70:73]
	v_mfma_f32_16x16x32_bf16 v[66:69], v[176:179], v[214:217], v[66:69]
	v_mfma_f32_16x16x32_bf16 v[118:121], v[172:175], v[188:191], v[118:121]
	v_mfma_f32_16x16x32_bf16 v[114:117], v[180:183], v[188:191], v[114:117]
	v_mfma_f32_16x16x32_bf16 v[102:105], v[172:175], v[200:203], v[102:105]
	v_mfma_f32_16x16x32_bf16 v[94:97], v[180:183], v[200:203], v[94:97]
	v_mfma_f32_16x16x32_bf16 v[86:89], v[172:175], v[210:213], v[86:89]
	v_mfma_f32_16x16x32_bf16 v[82:85], v[180:183], v[210:213], v[82:85]
	v_mfma_f32_16x16x32_bf16 v[70:73], v[172:175], v[218:221], v[70:73]
	v_mfma_f32_16x16x32_bf16 v[66:69], v[180:183], v[218:221], v[66:69]
	s_barrier
	s_add_i32 s34, s58, s40
	v_lshl_add_u64 v[192:193], v[192:193], 0, s[14:15]
	s_mov_b32 m0, s34
	ds_read_b128 v[184:187], v154 offset:49152
	ds_read_b128 v[188:191], v154 offset:50176
	ds_read_b128 v[196:199], v154 offset:51200
	ds_read_b128 v[200:203], v154 offset:52224
	ds_read_b128 v[206:209], v154 offset:53248
	ds_read_b128 v[210:213], v154 offset:54272
	ds_read_b128 v[214:217], v154 offset:55296
	ds_read_b128 v[218:221], v154 offset:56320
	global_load_lds_dwordx4 v[192:193], off
	s_add_i32 m0, s34, 0x2000
	s_add_u32 s30, s30, 0x80080
	v_lshl_add_u64 v[192:193], v[222:223], 0, s[14:15]
	s_addc_u32 s31, s31, 0
	s_add_i32 s34, s59, s40
	global_load_lds_dwordx4 v[192:193], off
	v_lshl_add_u64 v[192:193], s[30:31], 0, v[134:135]
	s_mov_b32 m0, s34
	s_nop 0
	global_load_lds_dwordx4 v[192:193], off
	v_lshl_add_u64 v[192:193], s[30:31], 0, v[130:131]
	s_add_i32 m0, s34, 0x2000
	s_nop 0
	global_load_lds_dwordx4 v[192:193], off
	v_lshl_add_u64 v[192:193], v[224:225], 0, s[14:15]
	s_mov_b32 m0, s47
	s_nop 0
	global_load_lds_dwordx4 v[192:193], off
	v_lshl_add_u64 v[192:193], v[226:227], 0, s[14:15]
	s_mov_b32 m0, s48
	s_nop 0
	global_load_lds_dwordx4 v[192:193], off
	s_nop 0
	s_waitcnt vmcnt(8)
	s_waitcnt lgkmcnt(0)
	s_barrier
	v_mfma_f32_16x16x32_bf16 v[62:65], v[146:149], v[184:187], v[62:65]
	v_mfma_f32_16x16x32_bf16 v[58:61], v[160:163], v[184:187], v[58:61]
	v_mfma_f32_16x16x32_bf16 v[46:49], v[146:149], v[196:199], v[46:49]
	v_mfma_f32_16x16x32_bf16 v[42:45], v[160:163], v[196:199], v[42:45]
	v_mfma_f32_16x16x32_bf16 v[30:33], v[146:149], v[206:209], v[30:33]
	v_mfma_f32_16x16x32_bf16 v[26:29], v[160:163], v[206:209], v[26:29]
	v_mfma_f32_16x16x32_bf16 v[14:17], v[146:149], v[214:217], v[14:17]
	v_mfma_f32_16x16x32_bf16 v[10:13], v[160:163], v[214:217], v[10:13]
	v_mfma_f32_16x16x32_bf16 v[62:65], v[156:159], v[188:191], v[62:65]
	v_mfma_f32_16x16x32_bf16 v[58:61], v[164:167], v[188:191], v[58:61]
	v_mfma_f32_16x16x32_bf16 v[46:49], v[156:159], v[200:203], v[46:49]
	v_mfma_f32_16x16x32_bf16 v[42:45], v[164:167], v[200:203], v[42:45]
	v_mfma_f32_16x16x32_bf16 v[30:33], v[156:159], v[210:213], v[30:33]
	v_mfma_f32_16x16x32_bf16 v[26:29], v[164:167], v[210:213], v[26:29]
	v_mfma_f32_16x16x32_bf16 v[14:17], v[156:159], v[218:221], v[14:17]
	v_mfma_f32_16x16x32_bf16 v[10:13], v[164:167], v[218:221], v[10:13]
	v_mfma_f32_16x16x32_bf16 v[54:57], v[168:171], v[184:187], v[54:57]
	v_mfma_f32_16x16x32_bf16 v[50:53], v[176:179], v[184:187], v[50:53]
	v_mfma_f32_16x16x32_bf16 v[38:41], v[168:171], v[196:199], v[38:41]
	v_mfma_f32_16x16x32_bf16 v[34:37], v[176:179], v[196:199], v[34:37]
	v_mfma_f32_16x16x32_bf16 v[22:25], v[168:171], v[206:209], v[22:25]
	v_mfma_f32_16x16x32_bf16 v[18:21], v[176:179], v[206:209], v[18:21]
	v_mfma_f32_16x16x32_bf16 v[6:9], v[168:171], v[214:217], v[6:9]
	v_mfma_f32_16x16x32_bf16 v[2:5], v[176:179], v[214:217], v[2:5]
	v_mfma_f32_16x16x32_bf16 v[54:57], v[172:175], v[188:191], v[54:57]
	v_mfma_f32_16x16x32_bf16 v[50:53], v[180:183], v[188:191], v[50:53]
	v_mfma_f32_16x16x32_bf16 v[38:41], v[172:175], v[200:203], v[38:41]
	v_mfma_f32_16x16x32_bf16 v[34:37], v[180:183], v[200:203], v[34:37]
	v_mfma_f32_16x16x32_bf16 v[22:25], v[172:175], v[210:213], v[22:25]
	v_mfma_f32_16x16x32_bf16 v[18:21], v[180:183], v[210:213], v[18:21]
	v_mfma_f32_16x16x32_bf16 v[6:9], v[172:175], v[218:221], v[6:9]
	v_mfma_f32_16x16x32_bf16 v[2:5], v[180:183], v[218:221], v[2:5]
	s_barrier
	s_add_i32 s57, s57, 2
	s_add_u32 s28, s28, 0x100
	s_addc_u32 s29, s29, 0
	s_add_u32 s55, s55, 0x100
	s_addc_u32 s56, s56, 0
	s_cmp_gt_u32 s57, 29
	s_cbranch_scc0 .LBB0_967
	s_and_b64 vcc, exec, s[16:17]
	s_cbranch_vccz .LBB0_970
	s_barrier

.LBB0_1057:
	ds_read_b128 v[150:153], v158
	ds_read_b128 v[162:165], v158 offset:1024
	ds_read_b128 v[166:169], v158 offset:2048
	ds_read_b128 v[170:173], v158 offset:3072
	ds_read_b128 v[174:177], v159
	ds_read_b128 v[178:181], v159 offset:1024
	ds_read_b128 v[182:185], v159 offset:2048
	ds_read_b128 v[186:189], v159 offset:3072
	s_add_i32 s84, s48, 2
	s_add_u32 s49, s62, 0xfff00080
	s_addc_u32 s64, s63, -1
	s_cmp_eq_u32 s51, s48
	s_cselect_b32 s48, s56, s53
	s_cselect_b32 s65, s9, s64
	s_cselect_b32 s64, s8, s49
	s_cselect_b32 s49, s57, s55
	v_lshl_add_u64 v[154:155], s[62:63], 0, v[138:139]
	s_add_i32 m0, s59, 0xc000
	ds_read_b128 v[190:193], v160
	ds_read_b128 v[196:199], v160 offset:1024
	ds_read_b128 v[200:203], v160 offset:2048
	ds_read_b128 v[206:209], v160 offset:3072
	ds_read_b128 v[210:213], v160 offset:4096
	ds_read_b128 v[214:217], v160 offset:5120
	ds_read_b128 v[218:221], v160 offset:6144
	ds_read_b128 v[222:225], v160 offset:7168
	global_load_lds_dwordx4 v[154:155], off
	v_lshl_add_u64 v[154:155], s[62:63], 0, v[140:141]
	s_add_i32 m0, s59, 0xe000
	s_nop 0
	global_load_lds_dwordx4 v[154:155], off
	s_nop 0
	s_waitcnt vmcnt(8)
	s_waitcnt lgkmcnt(0)
	s_barrier
	v_mfma_f32_16x16x32_bf16 v[126:129], v[150:153], v[190:193], v[126:129]
	v_mfma_f32_16x16x32_bf16 v[122:125], v[166:169], v[190:193], v[122:125]
	v_mfma_f32_16x16x32_bf16 v[110:113], v[150:153], v[200:203], v[110:113]
	v_mfma_f32_16x16x32_bf16 v[106:109], v[166:169], v[200:203], v[106:109]
	v_mfma_f32_16x16x32_bf16 v[94:97], v[150:153], v[210:213], v[94:97]
	v_mfma_f32_16x16x32_bf16 v[90:93], v[166:169], v[210:213], v[90:93]
	v_mfma_f32_16x16x32_bf16 v[78:81], v[150:153], v[218:221], v[78:81]
	v_mfma_f32_16x16x32_bf16 v[74:77], v[166:169], v[218:221], v[74:77]
	v_mfma_f32_16x16x32_bf16 v[126:129], v[162:165], v[196:199], v[126:129]
	v_mfma_f32_16x16x32_bf16 v[122:125], v[170:173], v[196:199], v[122:125]
	v_mfma_f32_16x16x32_bf16 v[110:113], v[162:165], v[206:209], v[110:113]
	v_mfma_f32_16x16x32_bf16 v[106:109], v[170:173], v[206:209], v[106:109]
	v_mfma_f32_16x16x32_bf16 v[94:97], v[162:165], v[214:217], v[94:97]
	v_mfma_f32_16x16x32_bf16 v[90:93], v[170:173], v[214:217], v[90:93]
	v_mfma_f32_16x16x32_bf16 v[78:81], v[162:165], v[222:225], v[78:81]
	v_mfma_f32_16x16x32_bf16 v[74:77], v[170:173], v[222:225], v[74:77]
	v_mfma_f32_16x16x32_bf16 v[118:121], v[174:177], v[190:193], v[118:121]
	v_mfma_f32_16x16x32_bf16 v[114:117], v[182:185], v[190:193], v[114:117]
	v_mfma_f32_16x16x32_bf16 v[102:105], v[174:177], v[200:203], v[102:105]
	v_mfma_f32_16x16x32_bf16 v[98:101], v[182:185], v[200:203], v[98:101]
	v_mfma_f32_16x16x32_bf16 v[86:89], v[174:177], v[210:213], v[86:89]
	v_mfma_f32_16x16x32_bf16 v[82:85], v[182:185], v[210:213], v[82:85]
	v_mfma_f32_16x16x32_bf16 v[70:73], v[174:177], v[218:221], v[70:73]
	v_mfma_f32_16x16x32_bf16 v[66:69], v[182:185], v[218:221], v[66:69]
	v_mfma_f32_16x16x32_bf16 v[118:121], v[178:181], v[196:199], v[118:121]
	v_mfma_f32_16x16x32_bf16 v[114:117], v[186:189], v[196:199], v[114:117]
	v_mfma_f32_16x16x32_bf16 v[102:105], v[178:181], v[206:209], v[102:105]
	v_mfma_f32_16x16x32_bf16 v[98:101], v[186:189], v[206:209], v[98:101]
	v_mfma_f32_16x16x32_bf16 v[86:89], v[178:181], v[214:217], v[86:89]
	v_mfma_f32_16x16x32_bf16 v[82:85], v[186:189], v[214:217], v[82:85]
	v_mfma_f32_16x16x32_bf16 v[70:73], v[178:181], v[222:225], v[70:73]
	v_mfma_f32_16x16x32_bf16 v[66:69], v[186:189], v[222:225], v[66:69]
	s_barrier
	s_add_i32 s85, s75, s66
	v_lshl_add_u64 v[154:155], s[48:49], 0, v[132:133]
	s_mov_b32 m0, s85
	ds_read_b128 v[190:193], v160 offset:16384
	ds_read_b128 v[196:199], v160 offset:17408
	ds_read_b128 v[200:203], v160 offset:18432
	ds_read_b128 v[206:209], v160 offset:19456
	ds_read_b128 v[210:213], v160 offset:20480
	ds_read_b128 v[214:217], v160 offset:21504
	ds_read_b128 v[218:221], v160 offset:22528
	ds_read_b128 v[222:225], v160 offset:23552
	global_load_lds_dwordx4 v[154:155], off
	s_add_i32 m0, s85, 0x2000
	s_add_u32 s86, s48, 0x100000
	v_lshl_add_u64 v[226:227], s[48:49], 0, v[136:137]
	s_addc_u32 s87, s49, 0
	s_add_i32 s85, s76, s66
	global_load_lds_dwordx4 v[226:227], off
	v_lshl_add_u64 v[228:229], s[86:87], 0, v[132:133]
	s_mov_b32 m0, s85
	v_lshl_add_u64 v[230:231], s[64:65], 0, v[134:135]
	global_load_lds_dwordx4 v[228:229], off
	v_lshl_add_u64 v[228:229], s[86:87], 0, v[136:137]
	s_add_i32 m0, s85, 0x2000
	s_nop 0
	global_load_lds_dwordx4 v[228:229], off
	v_lshl_add_u64 v[228:229], s[64:65], 0, v[130:131]
	s_mov_b32 m0, s59
	s_nop 0
	global_load_lds_dwordx4 v[228:229], off
	s_mov_b32 m0, s61
	s_nop 0
	global_load_lds_dwordx4 v[230:231], off
	s_waitcnt vmcnt(8)
	s_waitcnt lgkmcnt(0)
	s_barrier
	v_mfma_f32_16x16x32_bf16 v[62:65], v[150:153], v[190:193], v[62:65]
	v_mfma_f32_16x16x32_bf16 v[58:61], v[166:169], v[190:193], v[58:61]
	v_mfma_f32_16x16x32_bf16 v[46:49], v[150:153], v[200:203], v[46:49]
	v_mfma_f32_16x16x32_bf16 v[42:45], v[166:169], v[200:203], v[42:45]
	v_mfma_f32_16x16x32_bf16 v[30:33], v[150:153], v[210:213], v[30:33]
	v_mfma_f32_16x16x32_bf16 v[26:29], v[166:169], v[210:213], v[26:29]
	v_mfma_f32_16x16x32_bf16 v[14:17], v[150:153], v[218:221], v[14:17]
	v_mfma_f32_16x16x32_bf16 v[10:13], v[166:169], v[218:221], v[10:13]
	v_mfma_f32_16x16x32_bf16 v[62:65], v[162:165], v[196:199], v[62:65]
	v_mfma_f32_16x16x32_bf16 v[58:61], v[170:173], v[196:199], v[58:61]
	v_mfma_f32_16x16x32_bf16 v[46:49], v[162:165], v[206:209], v[46:49]
	v_mfma_f32_16x16x32_bf16 v[42:45], v[170:173], v[206:209], v[42:45]
	v_mfma_f32_16x16x32_bf16 v[30:33], v[162:165], v[214:217], v[30:33]
	v_mfma_f32_16x16x32_bf16 v[26:29], v[170:173], v[214:217], v[26:29]
	v_mfma_f32_16x16x32_bf16 v[14:17], v[162:165], v[222:225], v[14:17]
	v_mfma_f32_16x16x32_bf16 v[10:13], v[170:173], v[222:225], v[10:13]
	v_mfma_f32_16x16x32_bf16 v[54:57], v[174:177], v[190:193], v[54:57]
	v_mfma_f32_16x16x32_bf16 v[50:53], v[182:185], v[190:193], v[50:53]
	v_mfma_f32_16x16x32_bf16 v[38:41], v[174:177], v[200:203], v[38:41]
	v_mfma_f32_16x16x32_bf16 v[34:37], v[182:185], v[200:203], v[34:37]
	v_mfma_f32_16x16x32_bf16 v[22:25], v[174:177], v[210:213], v[22:25]
	v_mfma_f32_16x16x32_bf16 v[18:21], v[182:185], v[210:213], v[18:21]
	v_mfma_f32_16x16x32_bf16 v[6:9], v[174:177], v[218:221], v[6:9]
	v_mfma_f32_16x16x32_bf16 v[2:5], v[182:185], v[218:221], v[2:5]
	v_mfma_f32_16x16x32_bf16 v[54:57], v[178:181], v[196:199], v[54:57]
	v_mfma_f32_16x16x32_bf16 v[50:53], v[186:189], v[196:199], v[50:53]
	v_mfma_f32_16x16x32_bf16 v[38:41], v[178:181], v[206:209], v[38:41]
	v_mfma_f32_16x16x32_bf16 v[34:37], v[186:189], v[206:209], v[34:37]
	v_mfma_f32_16x16x32_bf16 v[22:25], v[178:181], v[214:217], v[22:25]
	v_mfma_f32_16x16x32_bf16 v[18:21], v[186:189], v[214:217], v[18:21]
	v_mfma_f32_16x16x32_bf16 v[6:9], v[178:181], v[222:225], v[6:9]
	v_mfma_f32_16x16x32_bf16 v[2:5], v[186:189], v[222:225], v[2:5]
	s_barrier
	s_add_i32 s85, 0, 0x18000
	v_add_u32_e32 v161, s85, v156
	s_add_i32 s86, 0, 0x1c000
	ds_read_b128 v[150:153], v161
	ds_read_b128 v[162:165], v161 offset:1024
	ds_read_b128 v[166:169], v161 offset:2048
	ds_read_b128 v[170:173], v161 offset:3072
	v_add_u32_e32 v161, s86, v156
	ds_read_b128 v[174:177], v161
	ds_read_b128 v[178:181], v161 offset:1024
	ds_read_b128 v[182:185], v161 offset:2048
	ds_read_b128 v[186:189], v161 offset:3072
	s_add_u32 s64, s64, 0x100000
	s_addc_u32 s65, s65, 0
	s_mov_b32 m0, s67
	v_lshl_add_u64 v[232:233], s[64:65], 0, v[130:131]
	ds_read_b128 v[190:193], v160 offset:32768
	ds_read_b128 v[196:199], v160 offset:33792
	ds_read_b128 v[200:203], v160 offset:34816
	ds_read_b128 v[206:209], v160 offset:35840
	ds_read_b128 v[210:213], v160 offset:36864
	ds_read_b128 v[214:217], v160 offset:37888
	ds_read_b128 v[218:221], v160 offset:38912
	ds_read_b128 v[222:225], v160 offset:39936
	global_load_lds_dwordx4 v[232:233], off
	v_lshl_add_u64 v[232:233], s[64:65], 0, v[134:135]
	s_mov_b32 m0, s68
	s_nop 0
	global_load_lds_dwordx4 v[232:233], off
	s_waitcnt vmcnt(8)
	s_waitcnt lgkmcnt(0)
	s_barrier
	v_mfma_f32_16x16x32_bf16 v[126:129], v[150:153], v[190:193], v[126:129]
	v_mfma_f32_16x16x32_bf16 v[122:125], v[166:169], v[190:193], v[122:125]
	v_mfma_f32_16x16x32_bf16 v[110:113], v[150:153], v[200:203], v[110:113]
	v_mfma_f32_16x16x32_bf16 v[106:109], v[166:169], v[200:203], v[106:109]
	v_mfma_f32_16x16x32_bf16 v[94:97], v[150:153], v[210:213], v[94:97]
	v_mfma_f32_16x16x32_bf16 v[90:93], v[166:169], v[210:213], v[90:93]
	v_mfma_f32_16x16x32_bf16 v[78:81], v[150:153], v[218:221], v[78:81]
	v_mfma_f32_16x16x32_bf16 v[74:77], v[166:169], v[218:221], v[74:77]
	v_mfma_f32_16x16x32_bf16 v[126:129], v[162:165], v[196:199], v[126:129]
	v_mfma_f32_16x16x32_bf16 v[122:125], v[170:173], v[196:199], v[122:125]
	v_mfma_f32_16x16x32_bf16 v[110:113], v[162:165], v[206:209], v[110:113]
	v_mfma_f32_16x16x32_bf16 v[106:109], v[170:173], v[206:209], v[106:109]
	v_mfma_f32_16x16x32_bf16 v[94:97], v[162:165], v[214:217], v[94:97]
	v_mfma_f32_16x16x32_bf16 v[90:93], v[170:173], v[214:217], v[90:93]
	v_mfma_f32_16x16x32_bf16 v[78:81], v[162:165], v[222:225], v[78:81]
	v_mfma_f32_16x16x32_bf16 v[74:77], v[170:173], v[222:225], v[74:77]
	v_mfma_f32_16x16x32_bf16 v[118:121], v[174:177], v[190:193], v[118:121]
	v_mfma_f32_16x16x32_bf16 v[114:117], v[182:185], v[190:193], v[114:117]
	v_mfma_f32_16x16x32_bf16 v[102:105], v[174:177], v[200:203], v[102:105]
	v_mfma_f32_16x16x32_bf16 v[98:101], v[182:185], v[200:203], v[98:101]
	v_mfma_f32_16x16x32_bf16 v[86:89], v[174:177], v[210:213], v[86:89]
	v_mfma_f32_16x16x32_bf16 v[82:85], v[182:185], v[210:213], v[82:85]
	v_mfma_f32_16x16x32_bf16 v[70:73], v[174:177], v[218:221], v[70:73]
	v_mfma_f32_16x16x32_bf16 v[66:69], v[182:185], v[218:221], v[66:69]
	v_mfma_f32_16x16x32_bf16 v[118:121], v[178:181], v[196:199], v[118:121]
	v_mfma_f32_16x16x32_bf16 v[114:117], v[186:189], v[196:199], v[114:117]
	v_mfma_f32_16x16x32_bf16 v[102:105], v[178:181], v[206:209], v[102:105]
	v_mfma_f32_16x16x32_bf16 v[98:101], v[186:189], v[206:209], v[98:101]
	v_mfma_f32_16x16x32_bf16 v[86:89], v[178:181], v[214:217], v[86:89]
	v_mfma_f32_16x16x32_bf16 v[82:85], v[186:189], v[214:217], v[82:85]
	v_mfma_f32_16x16x32_bf16 v[70:73], v[178:181], v[222:225], v[70:73]
	v_mfma_f32_16x16x32_bf16 v[66:69], v[186:189], v[222:225], v[66:69]
	s_barrier
	s_add_i32 s64, s85, s66
	v_lshl_add_u64 v[154:155], v[154:155], 0, s[20:21]
	s_mov_b32 m0, s64
	ds_read_b128 v[190:193], v160 offset:49152
	ds_read_b128 v[196:199], v160 offset:50176
	ds_read_b128 v[200:203], v160 offset:51200
	ds_read_b128 v[206:209], v160 offset:52224
	ds_read_b128 v[210:213], v160 offset:53248
	ds_read_b128 v[214:217], v160 offset:54272
	ds_read_b128 v[218:221], v160 offset:55296
	ds_read_b128 v[222:225], v160 offset:56320
	global_load_lds_dwordx4 v[154:155], off
	s_add_i32 m0, s64, 0x2000
	s_add_u32 s48, s48, 0x100080
	v_lshl_add_u64 v[154:155], v[226:227], 0, s[20:21]
	s_addc_u32 s49, s49, 0
	s_add_i32 s64, s86, s66
	global_load_lds_dwordx4 v[154:155], off
	v_lshl_add_u64 v[154:155], s[48:49], 0, v[132:133]
	s_mov_b32 m0, s64
	s_nop 0
	global_load_lds_dwordx4 v[154:155], off
	v_lshl_add_u64 v[154:155], s[48:49], 0, v[136:137]
	s_add_i32 m0, s64, 0x2000
	s_nop 0
	global_load_lds_dwordx4 v[154:155], off
	v_lshl_add_u64 v[154:155], v[228:229], 0, s[20:21]
	s_mov_b32 m0, s72
	s_nop 0
	global_load_lds_dwordx4 v[154:155], off
	v_lshl_add_u64 v[154:155], v[230:231], 0, s[20:21]
	s_mov_b32 m0, s73
	s_nop 0
	global_load_lds_dwordx4 v[154:155], off
	s_nop 0
	s_waitcnt vmcnt(8)
	s_waitcnt lgkmcnt(0)
	s_barrier
	v_mfma_f32_16x16x32_bf16 v[62:65], v[150:153], v[190:193], v[62:65]
	v_mfma_f32_16x16x32_bf16 v[58:61], v[166:169], v[190:193], v[58:61]
	v_mfma_f32_16x16x32_bf16 v[46:49], v[150:153], v[200:203], v[46:49]
	v_mfma_f32_16x16x32_bf16 v[42:45], v[166:169], v[200:203], v[42:45]
	v_mfma_f32_16x16x32_bf16 v[30:33], v[150:153], v[210:213], v[30:33]
	v_mfma_f32_16x16x32_bf16 v[26:29], v[166:169], v[210:213], v[26:29]
	v_mfma_f32_16x16x32_bf16 v[14:17], v[150:153], v[218:221], v[14:17]
	v_mfma_f32_16x16x32_bf16 v[10:13], v[166:169], v[218:221], v[10:13]
	v_mfma_f32_16x16x32_bf16 v[62:65], v[162:165], v[196:199], v[62:65]
	v_mfma_f32_16x16x32_bf16 v[58:61], v[170:173], v[196:199], v[58:61]
	v_mfma_f32_16x16x32_bf16 v[46:49], v[162:165], v[206:209], v[46:49]
	v_mfma_f32_16x16x32_bf16 v[42:45], v[170:173], v[206:209], v[42:45]
	v_mfma_f32_16x16x32_bf16 v[30:33], v[162:165], v[214:217], v[30:33]
	v_mfma_f32_16x16x32_bf16 v[26:29], v[170:173], v[214:217], v[26:29]
	v_mfma_f32_16x16x32_bf16 v[14:17], v[162:165], v[222:225], v[14:17]
	v_mfma_f32_16x16x32_bf16 v[10:13], v[170:173], v[222:225], v[10:13]
	v_mfma_f32_16x16x32_bf16 v[54:57], v[174:177], v[190:193], v[54:57]
	v_mfma_f32_16x16x32_bf16 v[50:53], v[182:185], v[190:193], v[50:53]
	v_mfma_f32_16x16x32_bf16 v[38:41], v[174:177], v[200:203], v[38:41]
	v_mfma_f32_16x16x32_bf16 v[34:37], v[182:185], v[200:203], v[34:37]
	v_mfma_f32_16x16x32_bf16 v[22:25], v[174:177], v[210:213], v[22:25]
	v_mfma_f32_16x16x32_bf16 v[18:21], v[182:185], v[210:213], v[18:21]
	v_mfma_f32_16x16x32_bf16 v[6:9], v[174:177], v[218:221], v[6:9]
	v_mfma_f32_16x16x32_bf16 v[2:5], v[182:185], v[218:221], v[2:5]
	v_mfma_f32_16x16x32_bf16 v[54:57], v[178:181], v[196:199], v[54:57]
	v_mfma_f32_16x16x32_bf16 v[50:53], v[186:189], v[196:199], v[50:53]
	v_mfma_f32_16x16x32_bf16 v[38:41], v[178:181], v[206:209], v[38:41]
	v_mfma_f32_16x16x32_bf16 v[34:37], v[186:189], v[206:209], v[34:37]
	v_mfma_f32_16x16x32_bf16 v[22:25], v[178:181], v[214:217], v[22:25]
	v_mfma_f32_16x16x32_bf16 v[18:21], v[186:189], v[214:217], v[18:21]
	v_mfma_f32_16x16x32_bf16 v[6:9], v[178:181], v[222:225], v[6:9]
	v_mfma_f32_16x16x32_bf16 v[2:5], v[186:189], v[222:225], v[2:5]
	s_barrier
	s_add_u32 s62, s62, 0x100
	s_addc_u32 s63, s63, 0
	s_add_u32 s53, s53, 0x100
	s_addc_u32 s55, s55, 0
	s_cmp_ge_i32 s84, s83
	s_mov_b32 s48, s84
	s_cbranch_scc0 .LBB0_1057
	s_and_b64 vcc, exec, s[22:23]
	s_cbranch_vccz .LBB0_1060
	s_barrier

.LBB0_1197:
	ds_read_b128 v[162:165], v141
	ds_read_b128 v[166:169], v141 offset:1024
	ds_read_b128 v[170:173], v141 offset:2048
	ds_read_b128 v[174:177], v141 offset:3072
	ds_read_b128 v[178:181], v145
	ds_read_b128 v[182:185], v145 offset:1024
	ds_read_b128 v[186:189], v145 offset:2048
	ds_read_b128 v[190:193], v145 offset:3072
	s_add_i32 s65, s34, 2
	s_add_u32 s35, s30, 0xfff00080
	s_addc_u32 s40, s31, -1
	s_cmp_eq_u32 s62, s34
	s_cselect_b32 s34, s61, s63
	s_cselect_b32 s41, s21, s40
	s_cselect_b32 s40, s25, s35
	s_cselect_b32 s35, s23, s64
	v_lshl_add_u64 v[158:159], s[30:31], 0, v[148:149]
	s_add_i32 m0, s8, 0xc000
	ds_read_b128 v[196:199], v160
	ds_read_b128 v[200:203], v160 offset:1024
	ds_read_b128 v[206:209], v160 offset:2048
	ds_read_b128 v[210:213], v160 offset:3072
	ds_read_b128 v[214:217], v160 offset:4096
	ds_read_b128 v[218:221], v160 offset:5120
	ds_read_b128 v[222:225], v160 offset:6144
	ds_read_b128 v[226:229], v160 offset:7168
	global_load_lds_dwordx4 v[158:159], off
	v_lshl_add_u64 v[158:159], s[30:31], 0, v[150:151]
	s_add_i32 m0, s8, 0xe000
	s_nop 0
	global_load_lds_dwordx4 v[158:159], off
	s_nop 0
	s_waitcnt vmcnt(8)
	s_waitcnt lgkmcnt(0)
	s_barrier
	v_mfma_f32_16x16x32_bf16 v[126:129], v[162:165], v[196:199], v[126:129]
	v_mfma_f32_16x16x32_bf16 v[122:125], v[170:173], v[196:199], v[122:125]
	v_mfma_f32_16x16x32_bf16 v[118:121], v[162:165], v[206:209], v[118:121]
	v_mfma_f32_16x16x32_bf16 v[114:117], v[170:173], v[206:209], v[114:117]
	v_mfma_f32_16x16x32_bf16 v[102:105], v[162:165], v[214:217], v[102:105]
	v_mfma_f32_16x16x32_bf16 v[98:101], v[170:173], v[214:217], v[98:101]
	v_mfma_f32_16x16x32_bf16 v[42:45], v[162:165], v[222:225], v[42:45]
	v_mfma_f32_16x16x32_bf16 v[34:37], v[170:173], v[222:225], v[34:37]
	v_mfma_f32_16x16x32_bf16 v[126:129], v[166:169], v[200:203], v[126:129]
	v_mfma_f32_16x16x32_bf16 v[122:125], v[174:177], v[200:203], v[122:125]
	v_mfma_f32_16x16x32_bf16 v[118:121], v[166:169], v[210:213], v[118:121]
	v_mfma_f32_16x16x32_bf16 v[114:117], v[174:177], v[210:213], v[114:117]
	v_mfma_f32_16x16x32_bf16 v[102:105], v[166:169], v[218:221], v[102:105]
	v_mfma_f32_16x16x32_bf16 v[98:101], v[174:177], v[218:221], v[98:101]
	v_mfma_f32_16x16x32_bf16 v[42:45], v[166:169], v[226:229], v[42:45]
	v_mfma_f32_16x16x32_bf16 v[34:37], v[174:177], v[226:229], v[34:37]
	v_mfma_f32_16x16x32_bf16 v[110:113], v[178:181], v[196:199], v[110:113]
	v_mfma_f32_16x16x32_bf16 v[106:109], v[186:189], v[196:199], v[106:109]
	v_mfma_f32_16x16x32_bf16 v[94:97], v[178:181], v[206:209], v[94:97]
	v_mfma_f32_16x16x32_bf16 v[90:93], v[186:189], v[206:209], v[90:93]
	v_mfma_f32_16x16x32_bf16 v[86:89], v[178:181], v[214:217], v[86:89]
	v_mfma_f32_16x16x32_bf16 v[82:85], v[186:189], v[214:217], v[82:85]
	v_mfma_f32_16x16x32_bf16 v[30:33], v[178:181], v[222:225], v[30:33]
	v_mfma_f32_16x16x32_bf16 v[26:29], v[186:189], v[222:225], v[26:29]
	v_mfma_f32_16x16x32_bf16 v[110:113], v[182:185], v[200:203], v[110:113]
	v_mfma_f32_16x16x32_bf16 v[106:109], v[190:193], v[200:203], v[106:109]
	v_mfma_f32_16x16x32_bf16 v[94:97], v[182:185], v[210:213], v[94:97]
	v_mfma_f32_16x16x32_bf16 v[90:93], v[190:193], v[210:213], v[90:93]
	v_mfma_f32_16x16x32_bf16 v[86:89], v[182:185], v[218:221], v[86:89]
	v_mfma_f32_16x16x32_bf16 v[82:85], v[190:193], v[218:221], v[82:85]
	v_mfma_f32_16x16x32_bf16 v[30:33], v[182:185], v[226:229], v[30:33]
	v_mfma_f32_16x16x32_bf16 v[26:29], v[190:193], v[226:229], v[26:29]
	s_barrier
	s_add_i32 s66, s56, s42
	v_lshl_add_u64 v[158:159], s[34:35], 0, v[134:135]
	s_mov_b32 m0, s66
	ds_read_b128 v[196:199], v160 offset:16384
	ds_read_b128 v[200:203], v160 offset:17408
	ds_read_b128 v[206:209], v160 offset:18432
	ds_read_b128 v[210:213], v160 offset:19456
	ds_read_b128 v[214:217], v160 offset:20480
	ds_read_b128 v[218:221], v160 offset:21504
	ds_read_b128 v[222:225], v160 offset:22528
	ds_read_b128 v[226:229], v160 offset:23552
	global_load_lds_dwordx4 v[158:159], off
	s_add_i32 m0, s66, 0x2000
	s_add_u32 s66, s34, 0x100000
	v_lshl_add_u64 v[230:231], s[34:35], 0, v[132:133]
	s_addc_u32 s67, s35, 0
	s_add_i32 s68, s57, s42
	global_load_lds_dwordx4 v[230:231], off
	v_lshl_add_u64 v[232:233], s[66:67], 0, v[134:135]
	s_mov_b32 m0, s68
	v_lshl_add_u64 v[234:235], s[40:41], 0, v[132:133]
	global_load_lds_dwordx4 v[232:233], off
	v_lshl_add_u64 v[232:233], s[66:67], 0, v[132:133]
	s_add_i32 m0, s68, 0x2000
	s_nop 0
	global_load_lds_dwordx4 v[232:233], off
	v_lshl_add_u64 v[232:233], s[40:41], 0, v[134:135]
	s_mov_b32 m0, s8
	s_nop 0
	global_load_lds_dwordx4 v[232:233], off
	s_mov_b32 m0, s15
	s_nop 0
	global_load_lds_dwordx4 v[234:235], off
	s_waitcnt vmcnt(8)
	s_waitcnt lgkmcnt(0)
	s_barrier
	v_mfma_f32_16x16x32_bf16 v[78:81], v[162:165], v[196:199], v[78:81]
	v_mfma_f32_16x16x32_bf16 v[74:77], v[170:173], v[196:199], v[74:77]
	v_mfma_f32_16x16x32_bf16 v[70:73], v[162:165], v[206:209], v[70:73]
	v_mfma_f32_16x16x32_bf16 v[66:69], v[170:173], v[206:209], v[66:69]
	v_mfma_f32_16x16x32_bf16 v[54:57], v[162:165], v[214:217], v[54:57]
	v_mfma_f32_16x16x32_bf16 v[50:53], v[170:173], v[214:217], v[50:53]
	v_mfma_f32_16x16x32_bf16 v[14:17], v[162:165], v[222:225], v[14:17]
	v_mfma_f32_16x16x32_bf16 v[10:13], v[170:173], v[222:225], v[10:13]
	v_mfma_f32_16x16x32_bf16 v[78:81], v[166:169], v[200:203], v[78:81]
	v_mfma_f32_16x16x32_bf16 v[74:77], v[174:177], v[200:203], v[74:77]
	v_mfma_f32_16x16x32_bf16 v[70:73], v[166:169], v[210:213], v[70:73]
	v_mfma_f32_16x16x32_bf16 v[66:69], v[174:177], v[210:213], v[66:69]
	v_mfma_f32_16x16x32_bf16 v[54:57], v[166:169], v[218:221], v[54:57]
	v_mfma_f32_16x16x32_bf16 v[50:53], v[174:177], v[218:221], v[50:53]
	v_mfma_f32_16x16x32_bf16 v[14:17], v[166:169], v[226:229], v[14:17]
	v_mfma_f32_16x16x32_bf16 v[10:13], v[174:177], v[226:229], v[10:13]
	v_mfma_f32_16x16x32_bf16 v[62:65], v[178:181], v[196:199], v[62:65]
	v_mfma_f32_16x16x32_bf16 v[58:61], v[186:189], v[196:199], v[58:61]
	v_mfma_f32_16x16x32_bf16 v[46:49], v[178:181], v[206:209], v[46:49]
	v_mfma_f32_16x16x32_bf16 v[38:41], v[186:189], v[206:209], v[38:41]
	v_mfma_f32_16x16x32_bf16 v[22:25], v[178:181], v[214:217], v[22:25]
	v_mfma_f32_16x16x32_bf16 v[18:21], v[186:189], v[214:217], v[18:21]
	v_mfma_f32_16x16x32_bf16 v[6:9], v[178:181], v[222:225], v[6:9]
	v_mfma_f32_16x16x32_bf16 v[2:5], v[186:189], v[222:225], v[2:5]
	v_mfma_f32_16x16x32_bf16 v[62:65], v[182:185], v[200:203], v[62:65]
	v_mfma_f32_16x16x32_bf16 v[58:61], v[190:193], v[200:203], v[58:61]
	v_mfma_f32_16x16x32_bf16 v[46:49], v[182:185], v[210:213], v[46:49]
	v_mfma_f32_16x16x32_bf16 v[38:41], v[190:193], v[210:213], v[38:41]
	v_mfma_f32_16x16x32_bf16 v[22:25], v[182:185], v[218:221], v[22:25]
	v_mfma_f32_16x16x32_bf16 v[18:21], v[190:193], v[218:221], v[18:21]
	v_mfma_f32_16x16x32_bf16 v[6:9], v[182:185], v[226:229], v[6:9]
	v_mfma_f32_16x16x32_bf16 v[2:5], v[190:193], v[226:229], v[2:5]
	s_barrier
	s_add_i32 s66, 0, 0x18000
	v_add_u32_e32 v161, s66, v1
	s_add_i32 s67, 0, 0x1c000
	ds_read_b128 v[162:165], v161
	ds_read_b128 v[166:169], v161 offset:1024
	ds_read_b128 v[170:173], v161 offset:2048
	ds_read_b128 v[174:177], v161 offset:3072
	v_add_u32_e32 v161, s67, v1
	ds_read_b128 v[178:181], v161
	ds_read_b128 v[182:185], v161 offset:1024
	ds_read_b128 v[186:189], v161 offset:2048
	ds_read_b128 v[190:193], v161 offset:3072
	s_add_u32 s40, s40, 0x100000
	s_addc_u32 s41, s41, 0
	s_mov_b32 m0, s46
	v_lshl_add_u64 v[236:237], s[40:41], 0, v[134:135]
	ds_read_b128 v[196:199], v160 offset:32768
	ds_read_b128 v[200:203], v160 offset:33792
	ds_read_b128 v[206:209], v160 offset:34816
	ds_read_b128 v[210:213], v160 offset:35840
	ds_read_b128 v[214:217], v160 offset:36864
	ds_read_b128 v[218:221], v160 offset:37888
	ds_read_b128 v[222:225], v160 offset:38912
	ds_read_b128 v[226:229], v160 offset:39936
	global_load_lds_dwordx4 v[236:237], off
	v_lshl_add_u64 v[236:237], s[40:41], 0, v[132:133]
	s_mov_b32 m0, s47
	s_nop 0
	global_load_lds_dwordx4 v[236:237], off
	s_waitcnt vmcnt(8)
	s_waitcnt lgkmcnt(0)
	s_barrier
	v_mfma_f32_16x16x32_bf16 v[126:129], v[162:165], v[196:199], v[126:129]
	v_mfma_f32_16x16x32_bf16 v[122:125], v[170:173], v[196:199], v[122:125]
	v_mfma_f32_16x16x32_bf16 v[118:121], v[162:165], v[206:209], v[118:121]
	v_mfma_f32_16x16x32_bf16 v[114:117], v[170:173], v[206:209], v[114:117]
	v_mfma_f32_16x16x32_bf16 v[102:105], v[162:165], v[214:217], v[102:105]
	v_mfma_f32_16x16x32_bf16 v[98:101], v[170:173], v[214:217], v[98:101]
	v_mfma_f32_16x16x32_bf16 v[42:45], v[162:165], v[222:225], v[42:45]
	v_mfma_f32_16x16x32_bf16 v[34:37], v[170:173], v[222:225], v[34:37]
	v_mfma_f32_16x16x32_bf16 v[126:129], v[166:169], v[200:203], v[126:129]
	v_mfma_f32_16x16x32_bf16 v[122:125], v[174:177], v[200:203], v[122:125]
	v_mfma_f32_16x16x32_bf16 v[118:121], v[166:169], v[210:213], v[118:121]
	v_mfma_f32_16x16x32_bf16 v[114:117], v[174:177], v[210:213], v[114:117]
	v_mfma_f32_16x16x32_bf16 v[102:105], v[166:169], v[218:221], v[102:105]
	v_mfma_f32_16x16x32_bf16 v[98:101], v[174:177], v[218:221], v[98:101]
	v_mfma_f32_16x16x32_bf16 v[42:45], v[166:169], v[226:229], v[42:45]
	v_mfma_f32_16x16x32_bf16 v[34:37], v[174:177], v[226:229], v[34:37]
	v_mfma_f32_16x16x32_bf16 v[110:113], v[178:181], v[196:199], v[110:113]
	v_mfma_f32_16x16x32_bf16 v[106:109], v[186:189], v[196:199], v[106:109]
	v_mfma_f32_16x16x32_bf16 v[94:97], v[178:181], v[206:209], v[94:97]
	v_mfma_f32_16x16x32_bf16 v[90:93], v[186:189], v[206:209], v[90:93]
	v_mfma_f32_16x16x32_bf16 v[86:89], v[178:181], v[214:217], v[86:89]
	v_mfma_f32_16x16x32_bf16 v[82:85], v[186:189], v[214:217], v[82:85]
	v_mfma_f32_16x16x32_bf16 v[30:33], v[178:181], v[222:225], v[30:33]
	v_mfma_f32_16x16x32_bf16 v[26:29], v[186:189], v[222:225], v[26:29]
	v_mfma_f32_16x16x32_bf16 v[110:113], v[182:185], v[200:203], v[110:113]
	v_mfma_f32_16x16x32_bf16 v[106:109], v[190:193], v[200:203], v[106:109]
	v_mfma_f32_16x16x32_bf16 v[94:97], v[182:185], v[210:213], v[94:97]
	v_mfma_f32_16x16x32_bf16 v[90:93], v[190:193], v[210:213], v[90:93]
	v_mfma_f32_16x16x32_bf16 v[86:89], v[182:185], v[218:221], v[86:89]
	v_mfma_f32_16x16x32_bf16 v[82:85], v[190:193], v[218:221], v[82:85]
	v_mfma_f32_16x16x32_bf16 v[30:33], v[182:185], v[226:229], v[30:33]
	v_mfma_f32_16x16x32_bf16 v[26:29], v[190:193], v[226:229], v[26:29]
	s_barrier
	s_add_i32 s40, s66, s42
	v_lshl_add_u64 v[158:159], v[158:159], 0, s[12:13]
	s_mov_b32 m0, s40
	ds_read_b128 v[196:199], v160 offset:49152
	ds_read_b128 v[200:203], v160 offset:50176
	ds_read_b128 v[206:209], v160 offset:51200
	ds_read_b128 v[210:213], v160 offset:52224
	ds_read_b128 v[214:217], v160 offset:53248
	ds_read_b128 v[218:221], v160 offset:54272
	ds_read_b128 v[222:225], v160 offset:55296
	ds_read_b128 v[226:229], v160 offset:56320
	global_load_lds_dwordx4 v[158:159], off
	s_add_i32 m0, s40, 0x2000
	s_add_u32 s34, s34, 0x100080
	v_lshl_add_u64 v[158:159], v[230:231], 0, s[12:13]
	s_addc_u32 s35, s35, 0
	s_add_i32 s40, s67, s42
	global_load_lds_dwordx4 v[158:159], off
	v_lshl_add_u64 v[158:159], s[34:35], 0, v[134:135]
	s_mov_b32 m0, s40
	s_nop 0
	global_load_lds_dwordx4 v[158:159], off
	v_lshl_add_u64 v[158:159], s[34:35], 0, v[132:133]
	s_add_i32 m0, s40, 0x2000
	s_nop 0
	global_load_lds_dwordx4 v[158:159], off
	v_lshl_add_u64 v[158:159], v[232:233], 0, s[12:13]
	s_mov_b32 m0, s52
	s_nop 0
	global_load_lds_dwordx4 v[158:159], off
	v_lshl_add_u64 v[158:159], v[234:235], 0, s[12:13]
	s_mov_b32 m0, s53
	s_nop 0
	global_load_lds_dwordx4 v[158:159], off
	s_nop 0
	s_waitcnt vmcnt(8)
	s_waitcnt lgkmcnt(0)
	s_barrier
	v_mfma_f32_16x16x32_bf16 v[78:81], v[162:165], v[196:199], v[78:81]
	v_mfma_f32_16x16x32_bf16 v[74:77], v[170:173], v[196:199], v[74:77]
	v_mfma_f32_16x16x32_bf16 v[70:73], v[162:165], v[206:209], v[70:73]
	v_mfma_f32_16x16x32_bf16 v[66:69], v[170:173], v[206:209], v[66:69]
	v_mfma_f32_16x16x32_bf16 v[54:57], v[162:165], v[214:217], v[54:57]
	v_mfma_f32_16x16x32_bf16 v[50:53], v[170:173], v[214:217], v[50:53]
	v_mfma_f32_16x16x32_bf16 v[14:17], v[162:165], v[222:225], v[14:17]
	v_mfma_f32_16x16x32_bf16 v[10:13], v[170:173], v[222:225], v[10:13]
	v_mfma_f32_16x16x32_bf16 v[78:81], v[166:169], v[200:203], v[78:81]
	v_mfma_f32_16x16x32_bf16 v[74:77], v[174:177], v[200:203], v[74:77]
	v_mfma_f32_16x16x32_bf16 v[70:73], v[166:169], v[210:213], v[70:73]
	v_mfma_f32_16x16x32_bf16 v[66:69], v[174:177], v[210:213], v[66:69]
	v_mfma_f32_16x16x32_bf16 v[54:57], v[166:169], v[218:221], v[54:57]
	v_mfma_f32_16x16x32_bf16 v[50:53], v[174:177], v[218:221], v[50:53]
	v_mfma_f32_16x16x32_bf16 v[14:17], v[166:169], v[226:229], v[14:17]
	v_mfma_f32_16x16x32_bf16 v[10:13], v[174:177], v[226:229], v[10:13]
	v_mfma_f32_16x16x32_bf16 v[62:65], v[178:181], v[196:199], v[62:65]
	v_mfma_f32_16x16x32_bf16 v[58:61], v[186:189], v[196:199], v[58:61]
	v_mfma_f32_16x16x32_bf16 v[46:49], v[178:181], v[206:209], v[46:49]
	v_mfma_f32_16x16x32_bf16 v[38:41], v[186:189], v[206:209], v[38:41]
	v_mfma_f32_16x16x32_bf16 v[22:25], v[178:181], v[214:217], v[22:25]
	v_mfma_f32_16x16x32_bf16 v[18:21], v[186:189], v[214:217], v[18:21]
	v_mfma_f32_16x16x32_bf16 v[6:9], v[178:181], v[222:225], v[6:9]
	v_mfma_f32_16x16x32_bf16 v[2:5], v[186:189], v[222:225], v[2:5]
	v_mfma_f32_16x16x32_bf16 v[62:65], v[182:185], v[200:203], v[62:65]
	v_mfma_f32_16x16x32_bf16 v[58:61], v[190:193], v[200:203], v[58:61]
	v_mfma_f32_16x16x32_bf16 v[46:49], v[182:185], v[210:213], v[46:49]
	v_mfma_f32_16x16x32_bf16 v[38:41], v[190:193], v[210:213], v[38:41]
	v_mfma_f32_16x16x32_bf16 v[22:25], v[182:185], v[218:221], v[22:25]
	v_mfma_f32_16x16x32_bf16 v[18:21], v[190:193], v[218:221], v[18:21]
	v_mfma_f32_16x16x32_bf16 v[6:9], v[182:185], v[226:229], v[6:9]
	v_mfma_f32_16x16x32_bf16 v[2:5], v[190:193], v[226:229], v[2:5]
	s_barrier
	s_add_u32 s30, s30, 0x100
	s_addc_u32 s31, s31, 0
	s_add_u32 s63, s63, 0x100
	s_addc_u32 s64, s64, 0
	s_cmp_ge_i32 s65, s60
	s_mov_b32 s34, s65
	s_cbranch_scc0 .LBB0_1197
	s_and_b64 vcc, exec, s[18:19]
	s_cbranch_vccz .LBB0_1200
	s_barrier

.LBB0_1391:
	ds_read_b128 v[152:155], v159
	ds_read_b128 v[162:165], v159 offset:1024
	ds_read_b128 v[166:169], v159 offset:2048
	ds_read_b128 v[170:173], v159 offset:3072
	ds_read_b128 v[174:177], v160
	ds_read_b128 v[178:181], v160 offset:1024
	ds_read_b128 v[182:185], v160 offset:2048
	ds_read_b128 v[186:189], v160 offset:3072
	s_add_i32 s82, s48, 2
	s_add_u32 s49, s60, 0xfffe0080
	s_addc_u32 s62, s61, -1
	s_cmp_eq_u32 s47, s48
	s_cselect_b32 s48, s54, s51
	s_cselect_b32 s63, s9, s62
	s_cselect_b32 s62, s8, s49
	s_cselect_b32 s49, s55, s53
	v_lshl_add_u64 v[156:157], s[60:61], 0, v[140:141]
	s_add_i32 m0, s57, 0xc000
	ds_read_b128 v[190:193], v161
	ds_read_b128 v[196:199], v161 offset:1024
	ds_read_b128 v[200:203], v161 offset:2048
	ds_read_b128 v[206:209], v161 offset:3072
	ds_read_b128 v[210:213], v161 offset:4096
	ds_read_b128 v[214:217], v161 offset:5120
	ds_read_b128 v[218:221], v161 offset:6144
	ds_read_b128 v[222:225], v161 offset:7168
	global_load_lds_dwordx4 v[156:157], off
	v_lshl_add_u64 v[156:157], s[60:61], 0, v[142:143]
	s_add_i32 m0, s57, 0xe000
	s_nop 0
	global_load_lds_dwordx4 v[156:157], off
	s_nop 0
	s_waitcnt vmcnt(8)
	s_waitcnt lgkmcnt(0)
	s_barrier
	v_mfma_f32_16x16x32_bf16 v[126:129], v[152:155], v[190:193], v[126:129]
	v_mfma_f32_16x16x32_bf16 v[122:125], v[166:169], v[190:193], v[122:125]
	v_mfma_f32_16x16x32_bf16 v[110:113], v[152:155], v[200:203], v[110:113]
	v_mfma_f32_16x16x32_bf16 v[106:109], v[166:169], v[200:203], v[106:109]
	v_mfma_f32_16x16x32_bf16 v[94:97], v[152:155], v[210:213], v[94:97]
	v_mfma_f32_16x16x32_bf16 v[90:93], v[166:169], v[210:213], v[90:93]
	v_mfma_f32_16x16x32_bf16 v[78:81], v[152:155], v[218:221], v[78:81]
	v_mfma_f32_16x16x32_bf16 v[74:77], v[166:169], v[218:221], v[74:77]
	v_mfma_f32_16x16x32_bf16 v[126:129], v[162:165], v[196:199], v[126:129]
	v_mfma_f32_16x16x32_bf16 v[122:125], v[170:173], v[196:199], v[122:125]
	v_mfma_f32_16x16x32_bf16 v[110:113], v[162:165], v[206:209], v[110:113]
	v_mfma_f32_16x16x32_bf16 v[106:109], v[170:173], v[206:209], v[106:109]
	v_mfma_f32_16x16x32_bf16 v[94:97], v[162:165], v[214:217], v[94:97]
	v_mfma_f32_16x16x32_bf16 v[90:93], v[170:173], v[214:217], v[90:93]
	v_mfma_f32_16x16x32_bf16 v[78:81], v[162:165], v[222:225], v[78:81]
	v_mfma_f32_16x16x32_bf16 v[74:77], v[170:173], v[222:225], v[74:77]
	v_mfma_f32_16x16x32_bf16 v[118:121], v[174:177], v[190:193], v[118:121]
	v_mfma_f32_16x16x32_bf16 v[114:117], v[182:185], v[190:193], v[114:117]
	v_mfma_f32_16x16x32_bf16 v[102:105], v[174:177], v[200:203], v[102:105]
	v_mfma_f32_16x16x32_bf16 v[98:101], v[182:185], v[200:203], v[98:101]
	v_mfma_f32_16x16x32_bf16 v[86:89], v[174:177], v[210:213], v[86:89]
	v_mfma_f32_16x16x32_bf16 v[82:85], v[182:185], v[210:213], v[82:85]
	v_mfma_f32_16x16x32_bf16 v[70:73], v[174:177], v[218:221], v[70:73]
	v_mfma_f32_16x16x32_bf16 v[66:69], v[182:185], v[218:221], v[66:69]
	v_mfma_f32_16x16x32_bf16 v[118:121], v[178:181], v[196:199], v[118:121]
	v_mfma_f32_16x16x32_bf16 v[114:117], v[186:189], v[196:199], v[114:117]
	v_mfma_f32_16x16x32_bf16 v[102:105], v[178:181], v[206:209], v[102:105]
	v_mfma_f32_16x16x32_bf16 v[98:101], v[186:189], v[206:209], v[98:101]
	v_mfma_f32_16x16x32_bf16 v[86:89], v[178:181], v[214:217], v[86:89]
	v_mfma_f32_16x16x32_bf16 v[82:85], v[186:189], v[214:217], v[82:85]
	v_mfma_f32_16x16x32_bf16 v[70:73], v[178:181], v[222:225], v[70:73]
	v_mfma_f32_16x16x32_bf16 v[66:69], v[186:189], v[222:225], v[66:69]
	s_barrier
	s_add_i32 s83, s73, s64
	v_lshl_add_u64 v[156:157], s[48:49], 0, v[134:135]
	s_mov_b32 m0, s83
	ds_read_b128 v[190:193], v161 offset:16384
	ds_read_b128 v[196:199], v161 offset:17408
	ds_read_b128 v[200:203], v161 offset:18432
	ds_read_b128 v[206:209], v161 offset:19456
	ds_read_b128 v[210:213], v161 offset:20480
	ds_read_b128 v[214:217], v161 offset:21504
	ds_read_b128 v[218:221], v161 offset:22528
	ds_read_b128 v[222:225], v161 offset:23552
	global_load_lds_dwordx4 v[156:157], off
	s_add_i32 m0, s83, 0x2000
	s_add_u32 s84, s48, 0x20000
	v_lshl_add_u64 v[226:227], s[48:49], 0, v[138:139]
	s_addc_u32 s85, s49, 0
	s_add_i32 s83, s74, s64
	global_load_lds_dwordx4 v[226:227], off
	v_lshl_add_u64 v[228:229], s[84:85], 0, v[134:135]
	s_mov_b32 m0, s83
	v_lshl_add_u64 v[230:231], s[62:63], 0, v[136:137]
	global_load_lds_dwordx4 v[228:229], off
	v_lshl_add_u64 v[228:229], s[84:85], 0, v[138:139]
	s_add_i32 m0, s83, 0x2000
	s_nop 0
	global_load_lds_dwordx4 v[228:229], off
	v_lshl_add_u64 v[228:229], s[62:63], 0, v[132:133]
	s_mov_b32 m0, s57
	s_nop 0
	global_load_lds_dwordx4 v[228:229], off
	s_mov_b32 m0, s59
	s_nop 0
	global_load_lds_dwordx4 v[230:231], off
	s_waitcnt vmcnt(8)
	s_waitcnt lgkmcnt(0)
	s_barrier
	v_mfma_f32_16x16x32_bf16 v[62:65], v[152:155], v[190:193], v[62:65]
	v_mfma_f32_16x16x32_bf16 v[58:61], v[166:169], v[190:193], v[58:61]
	v_mfma_f32_16x16x32_bf16 v[46:49], v[152:155], v[200:203], v[46:49]
	v_mfma_f32_16x16x32_bf16 v[42:45], v[166:169], v[200:203], v[42:45]
	v_mfma_f32_16x16x32_bf16 v[30:33], v[152:155], v[210:213], v[30:33]
	v_mfma_f32_16x16x32_bf16 v[26:29], v[166:169], v[210:213], v[26:29]
	v_mfma_f32_16x16x32_bf16 v[14:17], v[152:155], v[218:221], v[14:17]
	v_mfma_f32_16x16x32_bf16 v[10:13], v[166:169], v[218:221], v[10:13]
	v_mfma_f32_16x16x32_bf16 v[62:65], v[162:165], v[196:199], v[62:65]
	v_mfma_f32_16x16x32_bf16 v[58:61], v[170:173], v[196:199], v[58:61]
	v_mfma_f32_16x16x32_bf16 v[46:49], v[162:165], v[206:209], v[46:49]
	v_mfma_f32_16x16x32_bf16 v[42:45], v[170:173], v[206:209], v[42:45]
	v_mfma_f32_16x16x32_bf16 v[30:33], v[162:165], v[214:217], v[30:33]
	v_mfma_f32_16x16x32_bf16 v[26:29], v[170:173], v[214:217], v[26:29]
	v_mfma_f32_16x16x32_bf16 v[14:17], v[162:165], v[222:225], v[14:17]
	v_mfma_f32_16x16x32_bf16 v[10:13], v[170:173], v[222:225], v[10:13]
	v_mfma_f32_16x16x32_bf16 v[54:57], v[174:177], v[190:193], v[54:57]
	v_mfma_f32_16x16x32_bf16 v[50:53], v[182:185], v[190:193], v[50:53]
	v_mfma_f32_16x16x32_bf16 v[38:41], v[174:177], v[200:203], v[38:41]
	v_mfma_f32_16x16x32_bf16 v[34:37], v[182:185], v[200:203], v[34:37]
	v_mfma_f32_16x16x32_bf16 v[22:25], v[174:177], v[210:213], v[22:25]
	v_mfma_f32_16x16x32_bf16 v[18:21], v[182:185], v[210:213], v[18:21]
	v_mfma_f32_16x16x32_bf16 v[6:9], v[174:177], v[218:221], v[6:9]
	v_mfma_f32_16x16x32_bf16 v[2:5], v[182:185], v[218:221], v[2:5]
	v_mfma_f32_16x16x32_bf16 v[54:57], v[178:181], v[196:199], v[54:57]
	v_mfma_f32_16x16x32_bf16 v[50:53], v[186:189], v[196:199], v[50:53]
	v_mfma_f32_16x16x32_bf16 v[38:41], v[178:181], v[206:209], v[38:41]
	v_mfma_f32_16x16x32_bf16 v[34:37], v[186:189], v[206:209], v[34:37]
	v_mfma_f32_16x16x32_bf16 v[22:25], v[178:181], v[214:217], v[22:25]
	v_mfma_f32_16x16x32_bf16 v[18:21], v[186:189], v[214:217], v[18:21]
	v_mfma_f32_16x16x32_bf16 v[6:9], v[178:181], v[222:225], v[6:9]
	v_mfma_f32_16x16x32_bf16 v[2:5], v[186:189], v[222:225], v[2:5]
	s_barrier
	s_add_i32 s83, 0, 0x18000
	s_add_i32 s84, 0, 0x1c000
	v_add_u32_e32 v170, s83, v131
	v_add_u32_e32 v186, s84, v131
	ds_read_b128 v[152:155], v170
	ds_read_b128 v[162:165], v170 offset:1024
	ds_read_b128 v[166:169], v170 offset:2048
	ds_read_b128 v[170:173], v170 offset:3072
	ds_read_b128 v[174:177], v186
	ds_read_b128 v[178:181], v186 offset:1024
	ds_read_b128 v[182:185], v186 offset:2048
	ds_read_b128 v[186:189], v186 offset:3072
	s_add_u32 s62, s62, 0x20000
	s_addc_u32 s63, s63, 0
	s_mov_b32 m0, s65
	v_lshl_add_u64 v[232:233], s[62:63], 0, v[132:133]
	ds_read_b128 v[190:193], v161 offset:32768
	ds_read_b128 v[196:199], v161 offset:33792
	ds_read_b128 v[200:203], v161 offset:34816
	ds_read_b128 v[206:209], v161 offset:35840
	ds_read_b128 v[210:213], v161 offset:36864
	ds_read_b128 v[214:217], v161 offset:37888
	ds_read_b128 v[218:221], v161 offset:38912
	ds_read_b128 v[222:225], v161 offset:39936
	global_load_lds_dwordx4 v[232:233], off
	v_lshl_add_u64 v[232:233], s[62:63], 0, v[136:137]
	s_mov_b32 m0, s66
	s_nop 0
	global_load_lds_dwordx4 v[232:233], off
	s_waitcnt vmcnt(8)
	s_waitcnt lgkmcnt(0)
	s_barrier
	v_mfma_f32_16x16x32_bf16 v[126:129], v[152:155], v[190:193], v[126:129]
	v_mfma_f32_16x16x32_bf16 v[122:125], v[166:169], v[190:193], v[122:125]
	v_mfma_f32_16x16x32_bf16 v[110:113], v[152:155], v[200:203], v[110:113]
	v_mfma_f32_16x16x32_bf16 v[106:109], v[166:169], v[200:203], v[106:109]
	v_mfma_f32_16x16x32_bf16 v[94:97], v[152:155], v[210:213], v[94:97]
	v_mfma_f32_16x16x32_bf16 v[90:93], v[166:169], v[210:213], v[90:93]
	v_mfma_f32_16x16x32_bf16 v[78:81], v[152:155], v[218:221], v[78:81]
	v_mfma_f32_16x16x32_bf16 v[74:77], v[166:169], v[218:221], v[74:77]
	v_mfma_f32_16x16x32_bf16 v[126:129], v[162:165], v[196:199], v[126:129]
	v_mfma_f32_16x16x32_bf16 v[122:125], v[170:173], v[196:199], v[122:125]
	v_mfma_f32_16x16x32_bf16 v[110:113], v[162:165], v[206:209], v[110:113]
	v_mfma_f32_16x16x32_bf16 v[106:109], v[170:173], v[206:209], v[106:109]
	v_mfma_f32_16x16x32_bf16 v[94:97], v[162:165], v[214:217], v[94:97]
	v_mfma_f32_16x16x32_bf16 v[90:93], v[170:173], v[214:217], v[90:93]
	v_mfma_f32_16x16x32_bf16 v[78:81], v[162:165], v[222:225], v[78:81]
	v_mfma_f32_16x16x32_bf16 v[74:77], v[170:173], v[222:225], v[74:77]
	v_mfma_f32_16x16x32_bf16 v[118:121], v[174:177], v[190:193], v[118:121]
	v_mfma_f32_16x16x32_bf16 v[114:117], v[182:185], v[190:193], v[114:117]
	v_mfma_f32_16x16x32_bf16 v[102:105], v[174:177], v[200:203], v[102:105]
	v_mfma_f32_16x16x32_bf16 v[98:101], v[182:185], v[200:203], v[98:101]
	v_mfma_f32_16x16x32_bf16 v[86:89], v[174:177], v[210:213], v[86:89]
	v_mfma_f32_16x16x32_bf16 v[82:85], v[182:185], v[210:213], v[82:85]
	v_mfma_f32_16x16x32_bf16 v[70:73], v[174:177], v[218:221], v[70:73]
	v_mfma_f32_16x16x32_bf16 v[66:69], v[182:185], v[218:221], v[66:69]
	v_mfma_f32_16x16x32_bf16 v[118:121], v[178:181], v[196:199], v[118:121]
	v_mfma_f32_16x16x32_bf16 v[114:117], v[186:189], v[196:199], v[114:117]
	v_mfma_f32_16x16x32_bf16 v[102:105], v[178:181], v[206:209], v[102:105]
	v_mfma_f32_16x16x32_bf16 v[98:101], v[186:189], v[206:209], v[98:101]
	v_mfma_f32_16x16x32_bf16 v[86:89], v[178:181], v[214:217], v[86:89]
	v_mfma_f32_16x16x32_bf16 v[82:85], v[186:189], v[214:217], v[82:85]
	v_mfma_f32_16x16x32_bf16 v[70:73], v[178:181], v[222:225], v[70:73]
	v_mfma_f32_16x16x32_bf16 v[66:69], v[186:189], v[222:225], v[66:69]
	s_barrier
	s_add_i32 s62, s83, s64
	v_lshl_add_u64 v[156:157], v[156:157], 0, s[18:19]
	s_mov_b32 m0, s62
	ds_read_b128 v[190:193], v161 offset:49152
	ds_read_b128 v[196:199], v161 offset:50176
	ds_read_b128 v[200:203], v161 offset:51200
	ds_read_b128 v[206:209], v161 offset:52224
	ds_read_b128 v[210:213], v161 offset:53248
	ds_read_b128 v[214:217], v161 offset:54272
	ds_read_b128 v[218:221], v161 offset:55296
	ds_read_b128 v[222:225], v161 offset:56320
	global_load_lds_dwordx4 v[156:157], off
	s_add_i32 m0, s62, 0x2000
	s_add_u32 s48, s48, 0x20080
	v_lshl_add_u64 v[156:157], v[226:227], 0, s[18:19]
	s_addc_u32 s49, s49, 0
	s_add_i32 s62, s84, s64
	global_load_lds_dwordx4 v[156:157], off
	v_lshl_add_u64 v[156:157], s[48:49], 0, v[134:135]
	s_mov_b32 m0, s62
	s_nop 0
	global_load_lds_dwordx4 v[156:157], off
	v_lshl_add_u64 v[156:157], s[48:49], 0, v[138:139]
	s_add_i32 m0, s62, 0x2000
	s_nop 0
	global_load_lds_dwordx4 v[156:157], off
	v_lshl_add_u64 v[156:157], v[228:229], 0, s[18:19]
	s_mov_b32 m0, s70
	s_nop 0
	global_load_lds_dwordx4 v[156:157], off
	v_lshl_add_u64 v[156:157], v[230:231], 0, s[18:19]
	s_mov_b32 m0, s71
	s_nop 0
	global_load_lds_dwordx4 v[156:157], off
	s_nop 0
	s_waitcnt vmcnt(8)
	s_waitcnt lgkmcnt(0)
	s_barrier
	v_mfma_f32_16x16x32_bf16 v[62:65], v[152:155], v[190:193], v[62:65]
	v_mfma_f32_16x16x32_bf16 v[58:61], v[166:169], v[190:193], v[58:61]
	v_mfma_f32_16x16x32_bf16 v[46:49], v[152:155], v[200:203], v[46:49]
	v_mfma_f32_16x16x32_bf16 v[42:45], v[166:169], v[200:203], v[42:45]
	v_mfma_f32_16x16x32_bf16 v[30:33], v[152:155], v[210:213], v[30:33]
	v_mfma_f32_16x16x32_bf16 v[26:29], v[166:169], v[210:213], v[26:29]
	v_mfma_f32_16x16x32_bf16 v[14:17], v[152:155], v[218:221], v[14:17]
	v_mfma_f32_16x16x32_bf16 v[10:13], v[166:169], v[218:221], v[10:13]
	v_mfma_f32_16x16x32_bf16 v[62:65], v[162:165], v[196:199], v[62:65]
	v_mfma_f32_16x16x32_bf16 v[58:61], v[170:173], v[196:199], v[58:61]
	v_mfma_f32_16x16x32_bf16 v[46:49], v[162:165], v[206:209], v[46:49]
	v_mfma_f32_16x16x32_bf16 v[42:45], v[170:173], v[206:209], v[42:45]
	v_mfma_f32_16x16x32_bf16 v[30:33], v[162:165], v[214:217], v[30:33]
	v_mfma_f32_16x16x32_bf16 v[26:29], v[170:173], v[214:217], v[26:29]
	v_mfma_f32_16x16x32_bf16 v[14:17], v[162:165], v[222:225], v[14:17]
	v_mfma_f32_16x16x32_bf16 v[10:13], v[170:173], v[222:225], v[10:13]
	v_mfma_f32_16x16x32_bf16 v[54:57], v[174:177], v[190:193], v[54:57]
	v_mfma_f32_16x16x32_bf16 v[50:53], v[182:185], v[190:193], v[50:53]
	v_mfma_f32_16x16x32_bf16 v[38:41], v[174:177], v[200:203], v[38:41]
	v_mfma_f32_16x16x32_bf16 v[34:37], v[182:185], v[200:203], v[34:37]
	v_mfma_f32_16x16x32_bf16 v[22:25], v[174:177], v[210:213], v[22:25]
	v_mfma_f32_16x16x32_bf16 v[18:21], v[182:185], v[210:213], v[18:21]
	v_mfma_f32_16x16x32_bf16 v[6:9], v[174:177], v[218:221], v[6:9]
	v_mfma_f32_16x16x32_bf16 v[2:5], v[182:185], v[218:221], v[2:5]
	v_mfma_f32_16x16x32_bf16 v[54:57], v[178:181], v[196:199], v[54:57]
	v_mfma_f32_16x16x32_bf16 v[50:53], v[186:189], v[196:199], v[50:53]
	v_mfma_f32_16x16x32_bf16 v[38:41], v[178:181], v[206:209], v[38:41]
	v_mfma_f32_16x16x32_bf16 v[34:37], v[186:189], v[206:209], v[34:37]
	v_mfma_f32_16x16x32_bf16 v[22:25], v[178:181], v[214:217], v[22:25]
	v_mfma_f32_16x16x32_bf16 v[18:21], v[186:189], v[214:217], v[18:21]
	v_mfma_f32_16x16x32_bf16 v[6:9], v[178:181], v[222:225], v[6:9]
	v_mfma_f32_16x16x32_bf16 v[2:5], v[186:189], v[222:225], v[2:5]
	s_barrier
	s_add_u32 s60, s60, 0x100
	s_addc_u32 s61, s61, 0
	s_add_u32 s51, s51, 0x100
	s_addc_u32 s53, s53, 0
	s_cmp_ge_i32 s82, s81
	s_mov_b32 s48, s82
	s_cbranch_scc0 .LBB0_1391
	s_and_b64 vcc, exec, s[20:21]
	s_cbranch_vccz .LBB0_1394
	s_barrier

.LBB0_1553:
	ds_read_b128 v[156:159], v161
	ds_read_b128 v[164:167], v161 offset:1024
	ds_read_b128 v[168:171], v161 offset:2048
	ds_read_b128 v[172:175], v161 offset:3072
	ds_read_b128 v[176:179], v162
	ds_read_b128 v[180:183], v162 offset:1024
	ds_read_b128 v[184:187], v162 offset:2048
	ds_read_b128 v[188:191], v162 offset:3072
	s_add_i32 s76, s48, 2
	s_add_u32 s49, s46, 0xfff00080
	s_addc_u32 s50, s47, -1
	s_cmp_eq_u32 s73, s48
	s_cselect_b32 s48, s29, s74
	s_cselect_b32 s51, s9, s50
	s_cselect_b32 s50, s27, s49
	s_cselect_b32 s49, s25, s75
	v_lshl_add_u64 v[192:193], s[46:47], 0, v[148:149]
	s_add_i32 m0, s43, 0xc000
	ds_read_b128 v[196:199], v163
	ds_read_b128 v[200:203], v163 offset:1024
	ds_read_b128 v[206:209], v163 offset:2048
	ds_read_b128 v[210:213], v163 offset:3072
	ds_read_b128 v[214:217], v163 offset:4096
	ds_read_b128 v[218:221], v163 offset:5120
	ds_read_b128 v[222:225], v163 offset:6144
	ds_read_b128 v[226:229], v163 offset:7168
	global_load_lds_dwordx4 v[192:193], off
	v_lshl_add_u64 v[192:193], s[46:47], 0, v[150:151]
	s_add_i32 m0, s43, 0xe000
	s_nop 0
	global_load_lds_dwordx4 v[192:193], off
	s_nop 0
	s_waitcnt vmcnt(8)
	s_waitcnt lgkmcnt(0)
	s_barrier
	v_mfma_f32_16x16x32_bf16 v[78:81], v[156:159], v[196:199], v[78:81]
	v_mfma_f32_16x16x32_bf16 v[74:77], v[168:171], v[196:199], v[74:77]
	v_mfma_f32_16x16x32_bf16 v[70:73], v[156:159], v[206:209], v[70:73]
	v_mfma_f32_16x16x32_bf16 v[62:65], v[168:171], v[206:209], v[62:65]
	v_mfma_f32_16x16x32_bf16 v[58:61], v[156:159], v[214:217], v[58:61]
	v_mfma_f32_16x16x32_bf16 v[54:57], v[168:171], v[214:217], v[54:57]
	v_mfma_f32_16x16x32_bf16 v[46:49], v[156:159], v[222:225], v[46:49]
	v_mfma_f32_16x16x32_bf16 v[38:41], v[168:171], v[222:225], v[38:41]
	v_mfma_f32_16x16x32_bf16 v[78:81], v[164:167], v[200:203], v[78:81]
	v_mfma_f32_16x16x32_bf16 v[74:77], v[172:175], v[200:203], v[74:77]
	v_mfma_f32_16x16x32_bf16 v[70:73], v[164:167], v[210:213], v[70:73]
	v_mfma_f32_16x16x32_bf16 v[62:65], v[172:175], v[210:213], v[62:65]
	v_mfma_f32_16x16x32_bf16 v[58:61], v[164:167], v[218:221], v[58:61]
	v_mfma_f32_16x16x32_bf16 v[54:57], v[172:175], v[218:221], v[54:57]
	v_mfma_f32_16x16x32_bf16 v[46:49], v[164:167], v[226:229], v[46:49]
	v_mfma_f32_16x16x32_bf16 v[38:41], v[172:175], v[226:229], v[38:41]
	v_mfma_f32_16x16x32_bf16 v[50:53], v[176:179], v[196:199], v[50:53]
	v_mfma_f32_16x16x32_bf16 v[42:45], v[184:187], v[196:199], v[42:45]
	v_mfma_f32_16x16x32_bf16 v[34:37], v[176:179], v[206:209], v[34:37]
	v_mfma_f32_16x16x32_bf16 v[26:29], v[184:187], v[206:209], v[26:29]
	v_mfma_f32_16x16x32_bf16 v[18:21], v[176:179], v[214:217], v[18:21]
	v_mfma_f32_16x16x32_bf16 v[14:17], v[184:187], v[214:217], v[14:17]
	v_mfma_f32_16x16x32_bf16 v[10:13], v[176:179], v[222:225], v[10:13]
	v_mfma_f32_16x16x32_bf16 v[6:9], v[184:187], v[222:225], v[6:9]
	v_mfma_f32_16x16x32_bf16 v[50:53], v[180:183], v[200:203], v[50:53]
	v_mfma_f32_16x16x32_bf16 v[42:45], v[188:191], v[200:203], v[42:45]
	v_mfma_f32_16x16x32_bf16 v[34:37], v[180:183], v[210:213], v[34:37]
	v_mfma_f32_16x16x32_bf16 v[26:29], v[188:191], v[210:213], v[26:29]
	v_mfma_f32_16x16x32_bf16 v[18:21], v[180:183], v[218:221], v[18:21]
	v_mfma_f32_16x16x32_bf16 v[14:17], v[188:191], v[218:221], v[14:17]
	v_mfma_f32_16x16x32_bf16 v[10:13], v[180:183], v[226:229], v[10:13]
	v_mfma_f32_16x16x32_bf16 v[6:9], v[188:191], v[226:229], v[6:9]
	s_barrier
	s_add_i32 s77, s66, s53
	v_lshl_add_u64 v[192:193], s[48:49], 0, v[134:135]
	s_mov_b32 m0, s77
	ds_read_b128 v[196:199], v163 offset:16384
	ds_read_b128 v[200:203], v163 offset:17408
	ds_read_b128 v[206:209], v163 offset:18432
	ds_read_b128 v[210:213], v163 offset:19456
	ds_read_b128 v[214:217], v163 offset:20480
	ds_read_b128 v[218:221], v163 offset:21504
	ds_read_b128 v[222:225], v163 offset:22528
	ds_read_b128 v[226:229], v163 offset:23552
	global_load_lds_dwordx4 v[192:193], off
	s_add_i32 m0, s77, 0x2000
	s_add_u32 s78, s48, 0x100000
	v_lshl_add_u64 v[230:231], s[48:49], 0, v[138:139]
	s_addc_u32 s79, s49, 0
	s_add_i32 s77, s67, s53
	global_load_lds_dwordx4 v[230:231], off
	v_lshl_add_u64 v[232:233], s[78:79], 0, v[134:135]
	s_mov_b32 m0, s77
	v_lshl_add_u64 v[234:235], s[50:51], 0, v[136:137]
	global_load_lds_dwordx4 v[232:233], off
	v_lshl_add_u64 v[232:233], s[78:79], 0, v[138:139]
	s_add_i32 m0, s77, 0x2000
	s_nop 0
	global_load_lds_dwordx4 v[232:233], off
	v_lshl_add_u64 v[232:233], s[50:51], 0, v[132:133]
	s_mov_b32 m0, s43
	s_nop 0
	global_load_lds_dwordx4 v[232:233], off
	s_mov_b32 m0, s54
	s_nop 0
	global_load_lds_dwordx4 v[234:235], off
	s_waitcnt vmcnt(8)
	s_waitcnt lgkmcnt(0)
	s_barrier
	v_mfma_f32_16x16x32_bf16 v[126:129], v[156:159], v[196:199], v[126:129]
	v_mfma_f32_16x16x32_bf16 v[118:121], v[168:171], v[196:199], v[118:121]
	v_mfma_f32_16x16x32_bf16 v[110:113], v[156:159], v[206:209], v[110:113]
	v_mfma_f32_16x16x32_bf16 v[102:105], v[168:171], v[206:209], v[102:105]
	v_mfma_f32_16x16x32_bf16 v[94:97], v[156:159], v[214:217], v[94:97]
	v_mfma_f32_16x16x32_bf16 v[86:89], v[168:171], v[214:217], v[86:89]
	v_mfma_f32_16x16x32_bf16 v[66:69], v[156:159], v[222:225], v[66:69]
	v_mfma_f32_16x16x32_bf16 v[22:25], v[168:171], v[222:225], v[22:25]
	v_mfma_f32_16x16x32_bf16 v[126:129], v[164:167], v[200:203], v[126:129]
	v_mfma_f32_16x16x32_bf16 v[118:121], v[172:175], v[200:203], v[118:121]
	v_mfma_f32_16x16x32_bf16 v[110:113], v[164:167], v[210:213], v[110:113]
	v_mfma_f32_16x16x32_bf16 v[102:105], v[172:175], v[210:213], v[102:105]
	v_mfma_f32_16x16x32_bf16 v[94:97], v[164:167], v[218:221], v[94:97]
	v_mfma_f32_16x16x32_bf16 v[86:89], v[172:175], v[218:221], v[86:89]
	v_mfma_f32_16x16x32_bf16 v[66:69], v[164:167], v[226:229], v[66:69]
	v_mfma_f32_16x16x32_bf16 v[22:25], v[172:175], v[226:229], v[22:25]
	v_mfma_f32_16x16x32_bf16 v[122:125], v[176:179], v[196:199], v[122:125]
	v_mfma_f32_16x16x32_bf16 v[114:117], v[184:187], v[196:199], v[114:117]
	v_mfma_f32_16x16x32_bf16 v[106:109], v[176:179], v[206:209], v[106:109]
	v_mfma_f32_16x16x32_bf16 v[98:101], v[184:187], v[206:209], v[98:101]
	v_mfma_f32_16x16x32_bf16 v[90:93], v[176:179], v[214:217], v[90:93]
	v_mfma_f32_16x16x32_bf16 v[82:85], v[184:187], v[214:217], v[82:85]
	v_mfma_f32_16x16x32_bf16 v[30:33], v[176:179], v[222:225], v[30:33]
	v_mfma_f32_16x16x32_bf16 v[2:5], v[184:187], v[222:225], v[2:5]
	v_mfma_f32_16x16x32_bf16 v[122:125], v[180:183], v[200:203], v[122:125]
	v_mfma_f32_16x16x32_bf16 v[114:117], v[188:191], v[200:203], v[114:117]
	v_mfma_f32_16x16x32_bf16 v[106:109], v[180:183], v[210:213], v[106:109]
	v_mfma_f32_16x16x32_bf16 v[98:101], v[188:191], v[210:213], v[98:101]
	v_mfma_f32_16x16x32_bf16 v[90:93], v[180:183], v[218:221], v[90:93]
	v_mfma_f32_16x16x32_bf16 v[82:85], v[188:191], v[218:221], v[82:85]
	v_mfma_f32_16x16x32_bf16 v[30:33], v[180:183], v[226:229], v[30:33]
	v_mfma_f32_16x16x32_bf16 v[2:5], v[188:191], v[226:229], v[2:5]
	s_barrier
	s_add_i32 s77, 0, 0x18000
	s_add_i32 s78, 0, 0x1c000
	v_add_u32_e32 v172, s77, v131
	v_add_u32_e32 v188, s78, v131
	ds_read_b128 v[156:159], v172
	ds_read_b128 v[164:167], v172 offset:1024
	ds_read_b128 v[168:171], v172 offset:2048
	ds_read_b128 v[172:175], v172 offset:3072
	ds_read_b128 v[176:179], v188
	ds_read_b128 v[180:183], v188 offset:1024
	ds_read_b128 v[184:187], v188 offset:2048
	ds_read_b128 v[188:191], v188 offset:3072
	s_add_u32 s50, s50, 0x100000
	s_addc_u32 s51, s51, 0
	s_mov_b32 m0, s55
	v_lshl_add_u64 v[236:237], s[50:51], 0, v[132:133]
	ds_read_b128 v[196:199], v163 offset:32768
	ds_read_b128 v[200:203], v163 offset:33792
	ds_read_b128 v[206:209], v163 offset:34816
	ds_read_b128 v[210:213], v163 offset:35840
	ds_read_b128 v[214:217], v163 offset:36864
	ds_read_b128 v[218:221], v163 offset:37888
	ds_read_b128 v[222:225], v163 offset:38912
	ds_read_b128 v[226:229], v163 offset:39936
	global_load_lds_dwordx4 v[236:237], off
	v_lshl_add_u64 v[236:237], s[50:51], 0, v[136:137]
	s_mov_b32 m0, s56
	s_nop 0
	global_load_lds_dwordx4 v[236:237], off
	s_waitcnt vmcnt(8)
	s_waitcnt lgkmcnt(0)
	s_barrier
	v_mfma_f32_16x16x32_bf16 v[78:81], v[156:159], v[196:199], v[78:81]
	v_mfma_f32_16x16x32_bf16 v[74:77], v[168:171], v[196:199], v[74:77]
	v_mfma_f32_16x16x32_bf16 v[70:73], v[156:159], v[206:209], v[70:73]
	v_mfma_f32_16x16x32_bf16 v[62:65], v[168:171], v[206:209], v[62:65]
	v_mfma_f32_16x16x32_bf16 v[58:61], v[156:159], v[214:217], v[58:61]
	v_mfma_f32_16x16x32_bf16 v[54:57], v[168:171], v[214:217], v[54:57]
	v_mfma_f32_16x16x32_bf16 v[46:49], v[156:159], v[222:225], v[46:49]
	v_mfma_f32_16x16x32_bf16 v[38:41], v[168:171], v[222:225], v[38:41]
	v_mfma_f32_16x16x32_bf16 v[78:81], v[164:167], v[200:203], v[78:81]
	v_mfma_f32_16x16x32_bf16 v[74:77], v[172:175], v[200:203], v[74:77]
	v_mfma_f32_16x16x32_bf16 v[70:73], v[164:167], v[210:213], v[70:73]
	v_mfma_f32_16x16x32_bf16 v[62:65], v[172:175], v[210:213], v[62:65]
	v_mfma_f32_16x16x32_bf16 v[58:61], v[164:167], v[218:221], v[58:61]
	v_mfma_f32_16x16x32_bf16 v[54:57], v[172:175], v[218:221], v[54:57]
	v_mfma_f32_16x16x32_bf16 v[46:49], v[164:167], v[226:229], v[46:49]
	v_mfma_f32_16x16x32_bf16 v[38:41], v[172:175], v[226:229], v[38:41]
	v_mfma_f32_16x16x32_bf16 v[50:53], v[176:179], v[196:199], v[50:53]
	v_mfma_f32_16x16x32_bf16 v[42:45], v[184:187], v[196:199], v[42:45]
	v_mfma_f32_16x16x32_bf16 v[34:37], v[176:179], v[206:209], v[34:37]
	v_mfma_f32_16x16x32_bf16 v[26:29], v[184:187], v[206:209], v[26:29]
	v_mfma_f32_16x16x32_bf16 v[18:21], v[176:179], v[214:217], v[18:21]
	v_mfma_f32_16x16x32_bf16 v[14:17], v[184:187], v[214:217], v[14:17]
	v_mfma_f32_16x16x32_bf16 v[10:13], v[176:179], v[222:225], v[10:13]
	v_mfma_f32_16x16x32_bf16 v[6:9], v[184:187], v[222:225], v[6:9]
	v_mfma_f32_16x16x32_bf16 v[50:53], v[180:183], v[200:203], v[50:53]
	v_mfma_f32_16x16x32_bf16 v[42:45], v[188:191], v[200:203], v[42:45]
	v_mfma_f32_16x16x32_bf16 v[34:37], v[180:183], v[210:213], v[34:37]
	v_mfma_f32_16x16x32_bf16 v[26:29], v[188:191], v[210:213], v[26:29]
	v_mfma_f32_16x16x32_bf16 v[18:21], v[180:183], v[218:221], v[18:21]
	v_mfma_f32_16x16x32_bf16 v[14:17], v[188:191], v[218:221], v[14:17]
	v_mfma_f32_16x16x32_bf16 v[10:13], v[180:183], v[226:229], v[10:13]
	v_mfma_f32_16x16x32_bf16 v[6:9], v[188:191], v[226:229], v[6:9]
	s_barrier
	s_add_i32 s50, s77, s53
	v_lshl_add_u64 v[192:193], v[192:193], 0, s[14:15]
	s_mov_b32 m0, s50
	ds_read_b128 v[196:199], v163 offset:49152
	ds_read_b128 v[200:203], v163 offset:50176
	ds_read_b128 v[206:209], v163 offset:51200
	ds_read_b128 v[210:213], v163 offset:52224
	ds_read_b128 v[214:217], v163 offset:53248
	ds_read_b128 v[218:221], v163 offset:54272
	ds_read_b128 v[222:225], v163 offset:55296
	ds_read_b128 v[226:229], v163 offset:56320
	global_load_lds_dwordx4 v[192:193], off
	s_add_i32 m0, s50, 0x2000
	s_add_u32 s48, s48, 0x100080
	v_lshl_add_u64 v[192:193], v[230:231], 0, s[14:15]
	s_addc_u32 s49, s49, 0
	s_add_i32 s50, s78, s53
	global_load_lds_dwordx4 v[192:193], off
	v_lshl_add_u64 v[192:193], s[48:49], 0, v[134:135]
	s_mov_b32 m0, s50
	s_nop 0
	global_load_lds_dwordx4 v[192:193], off
	v_lshl_add_u64 v[192:193], s[48:49], 0, v[138:139]
	s_add_i32 m0, s50, 0x2000
	s_nop 0
	global_load_lds_dwordx4 v[192:193], off
	v_lshl_add_u64 v[192:193], v[232:233], 0, s[14:15]
	s_mov_b32 m0, s59
	s_nop 0
	global_load_lds_dwordx4 v[192:193], off
	v_lshl_add_u64 v[192:193], v[234:235], 0, s[14:15]
	s_mov_b32 m0, s60
	s_nop 0
	global_load_lds_dwordx4 v[192:193], off
	s_nop 0
	s_waitcnt vmcnt(8)
	s_waitcnt lgkmcnt(0)
	s_barrier
	v_mfma_f32_16x16x32_bf16 v[126:129], v[156:159], v[196:199], v[126:129]
	v_mfma_f32_16x16x32_bf16 v[118:121], v[168:171], v[196:199], v[118:121]
	v_mfma_f32_16x16x32_bf16 v[110:113], v[156:159], v[206:209], v[110:113]
	v_mfma_f32_16x16x32_bf16 v[102:105], v[168:171], v[206:209], v[102:105]
	v_mfma_f32_16x16x32_bf16 v[94:97], v[156:159], v[214:217], v[94:97]
	v_mfma_f32_16x16x32_bf16 v[86:89], v[168:171], v[214:217], v[86:89]
	v_mfma_f32_16x16x32_bf16 v[66:69], v[156:159], v[222:225], v[66:69]
	v_mfma_f32_16x16x32_bf16 v[22:25], v[168:171], v[222:225], v[22:25]
	v_mfma_f32_16x16x32_bf16 v[126:129], v[164:167], v[200:203], v[126:129]
	v_mfma_f32_16x16x32_bf16 v[118:121], v[172:175], v[200:203], v[118:121]
	v_mfma_f32_16x16x32_bf16 v[110:113], v[164:167], v[210:213], v[110:113]
	v_mfma_f32_16x16x32_bf16 v[102:105], v[172:175], v[210:213], v[102:105]
	v_mfma_f32_16x16x32_bf16 v[94:97], v[164:167], v[218:221], v[94:97]
	v_mfma_f32_16x16x32_bf16 v[86:89], v[172:175], v[218:221], v[86:89]
	v_mfma_f32_16x16x32_bf16 v[66:69], v[164:167], v[226:229], v[66:69]
	v_mfma_f32_16x16x32_bf16 v[22:25], v[172:175], v[226:229], v[22:25]
	v_mfma_f32_16x16x32_bf16 v[122:125], v[176:179], v[196:199], v[122:125]
	v_mfma_f32_16x16x32_bf16 v[114:117], v[184:187], v[196:199], v[114:117]
	v_mfma_f32_16x16x32_bf16 v[106:109], v[176:179], v[206:209], v[106:109]
	v_mfma_f32_16x16x32_bf16 v[98:101], v[184:187], v[206:209], v[98:101]
	v_mfma_f32_16x16x32_bf16 v[90:93], v[176:179], v[214:217], v[90:93]
	v_mfma_f32_16x16x32_bf16 v[82:85], v[184:187], v[214:217], v[82:85]
	v_mfma_f32_16x16x32_bf16 v[30:33], v[176:179], v[222:225], v[30:33]
	v_mfma_f32_16x16x32_bf16 v[2:5], v[184:187], v[222:225], v[2:5]
	v_mfma_f32_16x16x32_bf16 v[122:125], v[180:183], v[200:203], v[122:125]
	v_mfma_f32_16x16x32_bf16 v[114:117], v[188:191], v[200:203], v[114:117]
	v_mfma_f32_16x16x32_bf16 v[106:109], v[180:183], v[210:213], v[106:109]
	v_mfma_f32_16x16x32_bf16 v[98:101], v[188:191], v[210:213], v[98:101]
	v_mfma_f32_16x16x32_bf16 v[90:93], v[180:183], v[218:221], v[90:93]
	v_mfma_f32_16x16x32_bf16 v[82:85], v[188:191], v[218:221], v[82:85]
	v_mfma_f32_16x16x32_bf16 v[30:33], v[180:183], v[226:229], v[30:33]
	v_mfma_f32_16x16x32_bf16 v[2:5], v[188:191], v[226:229], v[2:5]
	s_barrier
	s_add_u32 s46, s46, 0x100
	s_addc_u32 s47, s47, 0
	s_add_u32 s74, s74, 0x100
	s_addc_u32 s75, s75, 0
	s_cmp_ge_i32 s76, s72
	s_mov_b32 s48, s76
	s_cbranch_scc0 .LBB0_1553
	s_and_b64 vcc, exec, s[16:17]
	s_cbranch_vccz .LBB0_1558
	s_barrier
	s_cmp_lt_i32 s52, 0
	s_mov_b64 s[46:47], -1
	s_cbranch_scc1 .LBB0_1559

.LBB0_1712:
	ds_read_b128 v[152:155], v160
	ds_read_b128 v[164:167], v160 offset:1024
	ds_read_b128 v[168:171], v160 offset:2048
	ds_read_b128 v[172:175], v160 offset:3072
	ds_read_b128 v[176:179], v161
	ds_read_b128 v[180:183], v161 offset:1024
	ds_read_b128 v[184:187], v161 offset:2048
	ds_read_b128 v[188:191], v161 offset:3072
	s_add_i32 s82, s48, 2
	s_add_u32 s49, s52, 0xffd50080
	s_addc_u32 s54, s53, -1
	s_cmp_eq_u32 s47, s48
	s_cselect_b32 s48, s50, s80
	s_cselect_b32 s55, s9, s54
	s_cselect_b32 s54, s8, s49
	s_cselect_b32 s49, s51, s81
	v_lshl_add_u64 v[156:157], s[52:53], 0, v[140:141]
	s_add_i32 m0, s57, 0xc000
	ds_read_b128 v[196:199], v162
	ds_read_b128 v[200:203], v162 offset:1024
	ds_read_b128 v[206:209], v162 offset:2048
	ds_read_b128 v[210:213], v162 offset:3072
	ds_read_b128 v[214:217], v162 offset:4096
	ds_read_b128 v[218:221], v162 offset:5120
	ds_read_b128 v[222:225], v162 offset:6144
	ds_read_b128 v[226:229], v162 offset:7168
	global_load_lds_dwordx4 v[156:157], off
	v_lshl_add_u64 v[156:157], s[52:53], 0, v[142:143]
	s_add_i32 m0, s57, 0xe000
	s_nop 0
	global_load_lds_dwordx4 v[156:157], off
	s_waitcnt vmcnt(8)
	s_waitcnt lgkmcnt(0)
	s_barrier
	v_mfma_f32_16x16x32_bf16 v[126:129], v[152:155], v[196:199], v[126:129]
	v_mfma_f32_16x16x32_bf16 v[122:125], v[168:171], v[196:199], v[122:125]
	v_mfma_f32_16x16x32_bf16 v[110:113], v[152:155], v[206:209], v[110:113]
	v_mfma_f32_16x16x32_bf16 v[106:109], v[168:171], v[206:209], v[106:109]
	v_mfma_f32_16x16x32_bf16 v[94:97], v[152:155], v[214:217], v[94:97]
	v_mfma_f32_16x16x32_bf16 v[90:93], v[168:171], v[214:217], v[90:93]
	v_mfma_f32_16x16x32_bf16 v[78:81], v[152:155], v[222:225], v[78:81]
	v_mfma_f32_16x16x32_bf16 v[74:77], v[168:171], v[222:225], v[74:77]
	v_mfma_f32_16x16x32_bf16 v[126:129], v[164:167], v[200:203], v[126:129]
	v_mfma_f32_16x16x32_bf16 v[122:125], v[172:175], v[200:203], v[122:125]
	v_mfma_f32_16x16x32_bf16 v[110:113], v[164:167], v[210:213], v[110:113]
	v_mfma_f32_16x16x32_bf16 v[106:109], v[172:175], v[210:213], v[106:109]
	v_mfma_f32_16x16x32_bf16 v[94:97], v[164:167], v[218:221], v[94:97]
	v_mfma_f32_16x16x32_bf16 v[90:93], v[172:175], v[218:221], v[90:93]
	v_mfma_f32_16x16x32_bf16 v[78:81], v[164:167], v[226:229], v[78:81]
	v_mfma_f32_16x16x32_bf16 v[74:77], v[172:175], v[226:229], v[74:77]
	v_mfma_f32_16x16x32_bf16 v[118:121], v[176:179], v[196:199], v[118:121]
	v_mfma_f32_16x16x32_bf16 v[114:117], v[184:187], v[196:199], v[114:117]
	v_mfma_f32_16x16x32_bf16 v[102:105], v[176:179], v[206:209], v[102:105]
	v_mfma_f32_16x16x32_bf16 v[98:101], v[184:187], v[206:209], v[98:101]
	v_mfma_f32_16x16x32_bf16 v[86:89], v[176:179], v[214:217], v[86:89]
	v_mfma_f32_16x16x32_bf16 v[82:85], v[184:187], v[214:217], v[82:85]
	v_mfma_f32_16x16x32_bf16 v[70:73], v[176:179], v[222:225], v[70:73]
	v_mfma_f32_16x16x32_bf16 v[66:69], v[184:187], v[222:225], v[66:69]
	v_mfma_f32_16x16x32_bf16 v[118:121], v[180:183], v[200:203], v[118:121]
	v_mfma_f32_16x16x32_bf16 v[114:117], v[188:191], v[200:203], v[114:117]
	v_mfma_f32_16x16x32_bf16 v[102:105], v[180:183], v[210:213], v[102:105]
	v_mfma_f32_16x16x32_bf16 v[98:101], v[188:191], v[210:213], v[98:101]
	v_mfma_f32_16x16x32_bf16 v[86:89], v[180:183], v[218:221], v[86:89]
	v_mfma_f32_16x16x32_bf16 v[82:85], v[188:191], v[218:221], v[82:85]
	v_mfma_f32_16x16x32_bf16 v[70:73], v[180:183], v[226:229], v[70:73]
	v_mfma_f32_16x16x32_bf16 v[66:69], v[188:191], v[226:229], v[66:69]
	s_barrier
	s_add_i32 s83, s67, s56
	v_lshl_add_u64 v[156:157], s[48:49], 0, v[134:135]
	s_mov_b32 m0, s83
	ds_read_b128 v[196:199], v162 offset:16384
	ds_read_b128 v[200:203], v162 offset:17408
	ds_read_b128 v[206:209], v162 offset:18432
	ds_read_b128 v[210:213], v162 offset:19456
	ds_read_b128 v[214:217], v162 offset:20480
	ds_read_b128 v[218:221], v162 offset:21504
	ds_read_b128 v[222:225], v162 offset:22528
	ds_read_b128 v[226:229], v162 offset:23552
	global_load_lds_dwordx4 v[156:157], off
	s_add_i32 m0, s83, 0x2000
	s_add_u32 s84, s48, 0x2b0000
	v_lshl_add_u64 v[192:193], s[48:49], 0, v[138:139]
	s_addc_u32 s85, s49, 0
	s_add_i32 s83, s68, s56
	global_load_lds_dwordx4 v[192:193], off
	v_lshl_add_u64 v[230:231], s[84:85], 0, v[134:135]
	s_mov_b32 m0, s83
	v_lshl_add_u64 v[232:233], s[54:55], 0, v[136:137]
	global_load_lds_dwordx4 v[230:231], off
	v_lshl_add_u64 v[230:231], s[84:85], 0, v[138:139]
	s_add_i32 m0, s83, 0x2000
	s_nop 0
	global_load_lds_dwordx4 v[230:231], off
	v_lshl_add_u64 v[230:231], s[54:55], 0, v[132:133]
	s_mov_b32 m0, s57
	s_nop 0
	global_load_lds_dwordx4 v[230:231], off
	s_mov_b32 m0, s58
	s_nop 0
	global_load_lds_dwordx4 v[232:233], off
	s_waitcnt vmcnt(8)
	s_waitcnt lgkmcnt(0)
	s_barrier
	v_mfma_f32_16x16x32_bf16 v[62:65], v[152:155], v[196:199], v[62:65]
	v_mfma_f32_16x16x32_bf16 v[58:61], v[168:171], v[196:199], v[58:61]
	v_mfma_f32_16x16x32_bf16 v[46:49], v[152:155], v[206:209], v[46:49]
	v_mfma_f32_16x16x32_bf16 v[42:45], v[168:171], v[206:209], v[42:45]
	v_mfma_f32_16x16x32_bf16 v[30:33], v[152:155], v[214:217], v[30:33]
	v_mfma_f32_16x16x32_bf16 v[26:29], v[168:171], v[214:217], v[26:29]
	v_mfma_f32_16x16x32_bf16 v[14:17], v[152:155], v[222:225], v[14:17]
	v_mfma_f32_16x16x32_bf16 v[10:13], v[168:171], v[222:225], v[10:13]
	v_mfma_f32_16x16x32_bf16 v[62:65], v[164:167], v[200:203], v[62:65]
	v_mfma_f32_16x16x32_bf16 v[58:61], v[172:175], v[200:203], v[58:61]
	v_mfma_f32_16x16x32_bf16 v[46:49], v[164:167], v[210:213], v[46:49]
	v_mfma_f32_16x16x32_bf16 v[42:45], v[172:175], v[210:213], v[42:45]
	v_mfma_f32_16x16x32_bf16 v[30:33], v[164:167], v[218:221], v[30:33]
	v_mfma_f32_16x16x32_bf16 v[26:29], v[172:175], v[218:221], v[26:29]
	v_mfma_f32_16x16x32_bf16 v[14:17], v[164:167], v[226:229], v[14:17]
	v_mfma_f32_16x16x32_bf16 v[10:13], v[172:175], v[226:229], v[10:13]
	v_mfma_f32_16x16x32_bf16 v[54:57], v[176:179], v[196:199], v[54:57]
	v_mfma_f32_16x16x32_bf16 v[50:53], v[184:187], v[196:199], v[50:53]
	v_mfma_f32_16x16x32_bf16 v[38:41], v[176:179], v[206:209], v[38:41]
	v_mfma_f32_16x16x32_bf16 v[34:37], v[184:187], v[206:209], v[34:37]
	v_mfma_f32_16x16x32_bf16 v[22:25], v[176:179], v[214:217], v[22:25]
	v_mfma_f32_16x16x32_bf16 v[18:21], v[184:187], v[214:217], v[18:21]
	v_mfma_f32_16x16x32_bf16 v[6:9], v[176:179], v[222:225], v[6:9]
	v_mfma_f32_16x16x32_bf16 v[2:5], v[184:187], v[222:225], v[2:5]
	v_mfma_f32_16x16x32_bf16 v[54:57], v[180:183], v[200:203], v[54:57]
	v_mfma_f32_16x16x32_bf16 v[50:53], v[188:191], v[200:203], v[50:53]
	v_mfma_f32_16x16x32_bf16 v[38:41], v[180:183], v[210:213], v[38:41]
	v_mfma_f32_16x16x32_bf16 v[34:37], v[188:191], v[210:213], v[34:37]
	v_mfma_f32_16x16x32_bf16 v[22:25], v[180:183], v[218:221], v[22:25]
	v_mfma_f32_16x16x32_bf16 v[18:21], v[188:191], v[218:221], v[18:21]
	v_mfma_f32_16x16x32_bf16 v[6:9], v[180:183], v[226:229], v[6:9]
	v_mfma_f32_16x16x32_bf16 v[2:5], v[188:191], v[226:229], v[2:5]
	s_barrier
	s_add_i32 s83, 0, 0x18000
	v_add_u32_e32 v163, s83, v158
	s_add_i32 s84, 0, 0x1c000
	ds_read_b128 v[152:155], v163
	ds_read_b128 v[164:167], v163 offset:1024
	ds_read_b128 v[168:171], v163 offset:2048
	ds_read_b128 v[172:175], v163 offset:3072
	v_add_u32_e32 v163, s84, v158
	ds_read_b128 v[176:179], v163
	ds_read_b128 v[180:183], v163 offset:1024
	ds_read_b128 v[184:187], v163 offset:2048
	ds_read_b128 v[188:191], v163 offset:3072
	s_add_u32 s54, s54, 0x2b0000
	s_addc_u32 s55, s55, 0
	s_mov_b32 m0, s59
	v_lshl_add_u64 v[234:235], s[54:55], 0, v[132:133]
	ds_read_b128 v[196:199], v162 offset:32768
	ds_read_b128 v[200:203], v162 offset:33792
	ds_read_b128 v[206:209], v162 offset:34816
	ds_read_b128 v[210:213], v162 offset:35840
	ds_read_b128 v[214:217], v162 offset:36864
	ds_read_b128 v[218:221], v162 offset:37888
	ds_read_b128 v[222:225], v162 offset:38912
	ds_read_b128 v[226:229], v162 offset:39936
	global_load_lds_dwordx4 v[234:235], off
	v_lshl_add_u64 v[234:235], s[54:55], 0, v[136:137]
	s_mov_b32 m0, s60
	s_nop 0
	global_load_lds_dwordx4 v[234:235], off
	s_waitcnt vmcnt(8)
	s_waitcnt lgkmcnt(0)
	s_barrier
	v_mfma_f32_16x16x32_bf16 v[126:129], v[152:155], v[196:199], v[126:129]
	v_mfma_f32_16x16x32_bf16 v[122:125], v[168:171], v[196:199], v[122:125]
	v_mfma_f32_16x16x32_bf16 v[110:113], v[152:155], v[206:209], v[110:113]
	v_mfma_f32_16x16x32_bf16 v[106:109], v[168:171], v[206:209], v[106:109]
	v_mfma_f32_16x16x32_bf16 v[94:97], v[152:155], v[214:217], v[94:97]
	v_mfma_f32_16x16x32_bf16 v[90:93], v[168:171], v[214:217], v[90:93]
	v_mfma_f32_16x16x32_bf16 v[78:81], v[152:155], v[222:225], v[78:81]
	v_mfma_f32_16x16x32_bf16 v[74:77], v[168:171], v[222:225], v[74:77]
	v_mfma_f32_16x16x32_bf16 v[126:129], v[164:167], v[200:203], v[126:129]
	v_mfma_f32_16x16x32_bf16 v[122:125], v[172:175], v[200:203], v[122:125]
	v_mfma_f32_16x16x32_bf16 v[110:113], v[164:167], v[210:213], v[110:113]
	v_mfma_f32_16x16x32_bf16 v[106:109], v[172:175], v[210:213], v[106:109]
	v_mfma_f32_16x16x32_bf16 v[94:97], v[164:167], v[218:221], v[94:97]
	v_mfma_f32_16x16x32_bf16 v[90:93], v[172:175], v[218:221], v[90:93]
	v_mfma_f32_16x16x32_bf16 v[78:81], v[164:167], v[226:229], v[78:81]
	v_mfma_f32_16x16x32_bf16 v[74:77], v[172:175], v[226:229], v[74:77]
	v_mfma_f32_16x16x32_bf16 v[118:121], v[176:179], v[196:199], v[118:121]
	v_mfma_f32_16x16x32_bf16 v[114:117], v[184:187], v[196:199], v[114:117]
	v_mfma_f32_16x16x32_bf16 v[102:105], v[176:179], v[206:209], v[102:105]
	v_mfma_f32_16x16x32_bf16 v[98:101], v[184:187], v[206:209], v[98:101]
	v_mfma_f32_16x16x32_bf16 v[86:89], v[176:179], v[214:217], v[86:89]
	v_mfma_f32_16x16x32_bf16 v[82:85], v[184:187], v[214:217], v[82:85]
	v_mfma_f32_16x16x32_bf16 v[70:73], v[176:179], v[222:225], v[70:73]
	v_mfma_f32_16x16x32_bf16 v[66:69], v[184:187], v[222:225], v[66:69]
	v_mfma_f32_16x16x32_bf16 v[118:121], v[180:183], v[200:203], v[118:121]
	v_mfma_f32_16x16x32_bf16 v[114:117], v[188:191], v[200:203], v[114:117]
	v_mfma_f32_16x16x32_bf16 v[102:105], v[180:183], v[210:213], v[102:105]
	v_mfma_f32_16x16x32_bf16 v[98:101], v[188:191], v[210:213], v[98:101]
	v_mfma_f32_16x16x32_bf16 v[86:89], v[180:183], v[218:221], v[86:89]
	v_mfma_f32_16x16x32_bf16 v[82:85], v[188:191], v[218:221], v[82:85]
	v_mfma_f32_16x16x32_bf16 v[70:73], v[180:183], v[226:229], v[70:73]
	v_mfma_f32_16x16x32_bf16 v[66:69], v[188:191], v[226:229], v[66:69]
	s_barrier
	s_add_i32 s54, s83, s56
	v_lshl_add_u64 v[156:157], v[156:157], 0, s[18:19]
	s_mov_b32 m0, s54
	ds_read_b128 v[196:199], v162 offset:49152
	ds_read_b128 v[200:203], v162 offset:50176
	ds_read_b128 v[206:209], v162 offset:51200
	ds_read_b128 v[210:213], v162 offset:52224
	ds_read_b128 v[214:217], v162 offset:53248
	ds_read_b128 v[218:221], v162 offset:54272
	ds_read_b128 v[222:225], v162 offset:55296
	ds_read_b128 v[226:229], v162 offset:56320
	global_load_lds_dwordx4 v[156:157], off
	s_add_i32 m0, s54, 0x2000
	s_add_u32 s48, s48, 0x2b0080
	v_lshl_add_u64 v[156:157], v[192:193], 0, s[18:19]
	s_addc_u32 s49, s49, 0
	s_add_i32 s54, s84, s56
	global_load_lds_dwordx4 v[156:157], off
	v_lshl_add_u64 v[156:157], s[48:49], 0, v[134:135]
	s_mov_b32 m0, s54
	s_nop 0
	global_load_lds_dwordx4 v[156:157], off
	v_lshl_add_u64 v[156:157], s[48:49], 0, v[138:139]
	s_add_i32 m0, s54, 0x2000
	s_nop 0
	global_load_lds_dwordx4 v[156:157], off
	v_lshl_add_u64 v[156:157], v[230:231], 0, s[18:19]
	s_mov_b32 m0, s64
	s_nop 0
	global_load_lds_dwordx4 v[156:157], off
	v_lshl_add_u64 v[156:157], v[232:233], 0, s[18:19]
	s_mov_b32 m0, s65
	s_nop 0
	global_load_lds_dwordx4 v[156:157], off
	s_nop 0
	s_waitcnt vmcnt(8)
	s_waitcnt lgkmcnt(0)
	s_barrier
	v_mfma_f32_16x16x32_bf16 v[62:65], v[152:155], v[196:199], v[62:65]
	v_mfma_f32_16x16x32_bf16 v[58:61], v[168:171], v[196:199], v[58:61]
	v_mfma_f32_16x16x32_bf16 v[46:49], v[152:155], v[206:209], v[46:49]
	v_mfma_f32_16x16x32_bf16 v[42:45], v[168:171], v[206:209], v[42:45]
	v_mfma_f32_16x16x32_bf16 v[30:33], v[152:155], v[214:217], v[30:33]
	v_mfma_f32_16x16x32_bf16 v[26:29], v[168:171], v[214:217], v[26:29]
	v_mfma_f32_16x16x32_bf16 v[14:17], v[152:155], v[222:225], v[14:17]
	v_mfma_f32_16x16x32_bf16 v[10:13], v[168:171], v[222:225], v[10:13]
	v_mfma_f32_16x16x32_bf16 v[62:65], v[164:167], v[200:203], v[62:65]
	v_mfma_f32_16x16x32_bf16 v[58:61], v[172:175], v[200:203], v[58:61]
	v_mfma_f32_16x16x32_bf16 v[46:49], v[164:167], v[210:213], v[46:49]
	v_mfma_f32_16x16x32_bf16 v[42:45], v[172:175], v[210:213], v[42:45]
	v_mfma_f32_16x16x32_bf16 v[30:33], v[164:167], v[218:221], v[30:33]
	v_mfma_f32_16x16x32_bf16 v[26:29], v[172:175], v[218:221], v[26:29]
	v_mfma_f32_16x16x32_bf16 v[14:17], v[164:167], v[226:229], v[14:17]
	v_mfma_f32_16x16x32_bf16 v[10:13], v[172:175], v[226:229], v[10:13]
	v_mfma_f32_16x16x32_bf16 v[54:57], v[176:179], v[196:199], v[54:57]
	v_mfma_f32_16x16x32_bf16 v[50:53], v[184:187], v[196:199], v[50:53]
	v_mfma_f32_16x16x32_bf16 v[38:41], v[176:179], v[206:209], v[38:41]
	v_mfma_f32_16x16x32_bf16 v[34:37], v[184:187], v[206:209], v[34:37]
	v_mfma_f32_16x16x32_bf16 v[22:25], v[176:179], v[214:217], v[22:25]
	v_mfma_f32_16x16x32_bf16 v[18:21], v[184:187], v[214:217], v[18:21]
	v_mfma_f32_16x16x32_bf16 v[6:9], v[176:179], v[222:225], v[6:9]
	v_mfma_f32_16x16x32_bf16 v[2:5], v[184:187], v[222:225], v[2:5]
	v_mfma_f32_16x16x32_bf16 v[54:57], v[180:183], v[200:203], v[54:57]
	v_mfma_f32_16x16x32_bf16 v[50:53], v[188:191], v[200:203], v[50:53]
	v_mfma_f32_16x16x32_bf16 v[38:41], v[180:183], v[210:213], v[38:41]
	v_mfma_f32_16x16x32_bf16 v[34:37], v[188:191], v[210:213], v[34:37]
	v_mfma_f32_16x16x32_bf16 v[22:25], v[180:183], v[218:221], v[22:25]
	v_mfma_f32_16x16x32_bf16 v[18:21], v[188:191], v[218:221], v[18:21]
	v_mfma_f32_16x16x32_bf16 v[6:9], v[180:183], v[226:229], v[6:9]
	v_mfma_f32_16x16x32_bf16 v[2:5], v[188:191], v[226:229], v[2:5]
	s_barrier
	s_add_u32 s52, s52, 0x100
	s_addc_u32 s53, s53, 0
	s_add_u32 s80, s80, 0x100
	s_addc_u32 s81, s81, 0
	s_cmp_ge_i32 s82, s78
	s_mov_b32 s48, s82
	s_cbranch_scc0 .LBB0_1712
	s_and_b64 vcc, exec, s[20:21]
	s_cbranch_vccz .LBB0_1715
	s_barrier

.LBB0_1869:
	ds_read_b128 v[162:165], v168
	s_waitcnt vmcnt(0)
	ds_read_b128 v[172:175], v168 offset:1024
	ds_read_b128 v[176:179], v168 offset:2048
	ds_read_b128 v[180:183], v168 offset:3072
	ds_read_b128 v[184:187], v169
	ds_read_b128 v[188:191], v169 offset:1024
	ds_read_b128 v[196:199], v169 offset:2048
	ds_read_b128 v[200:203], v169 offset:3072
	s_add_i32 s55, s42, 2
	s_add_u32 s43, s8, 0xfff00080
	s_addc_u32 s46, s9, -1
	s_cmp_eq_u32 s48, s42
	s_cselect_b32 s42, s41, s49
	s_cselect_b32 s47, s31, s46
	s_cselect_b32 s46, s33, s43
	s_cselect_b32 s43, s35, s53
	v_lshl_add_u64 v[166:167], s[8:9], 0, v[150:151]
	s_add_i32 m0, s62, 0xc000
	ds_read_b128 v[206:209], v170
	ds_read_b128 v[210:213], v170 offset:1024
	ds_read_b128 v[214:217], v170 offset:2048
	ds_read_b128 v[218:221], v170 offset:3072
	ds_read_b128 v[222:225], v170 offset:4096
	ds_read_b128 v[226:229], v170 offset:5120
	ds_read_b128 v[230:233], v170 offset:6144
	ds_read_b128 v[234:237], v170 offset:7168
	global_load_lds_dwordx4 v[166:167], off
	v_lshl_add_u64 v[166:167], s[8:9], 0, v[152:153]
	s_add_i32 m0, s62, 0xe000
	s_nop 0
	global_load_lds_dwordx4 v[166:167], off
	s_waitcnt vmcnt(8)
	s_waitcnt lgkmcnt(0)
	s_barrier
	v_mfma_f32_16x16x32_bf16 v[66:69], v[162:165], v[206:209], v[66:69]
	v_mfma_f32_16x16x32_bf16 v[62:65], v[176:179], v[206:209], v[62:65]
	v_mfma_f32_16x16x32_bf16 v[58:61], v[162:165], v[214:217], v[58:61]
	v_mfma_f32_16x16x32_bf16 v[54:57], v[176:179], v[214:217], v[54:57]
	v_mfma_f32_16x16x32_bf16 v[50:53], v[162:165], v[222:225], v[50:53]
	v_mfma_f32_16x16x32_bf16 v[46:49], v[176:179], v[222:225], v[46:49]
	v_mfma_f32_16x16x32_bf16 v[38:41], v[162:165], v[230:233], v[38:41]
	v_mfma_f32_16x16x32_bf16 v[30:33], v[176:179], v[230:233], v[30:33]
	v_mfma_f32_16x16x32_bf16 v[66:69], v[172:175], v[210:213], v[66:69]
	v_mfma_f32_16x16x32_bf16 v[62:65], v[180:183], v[210:213], v[62:65]
	v_mfma_f32_16x16x32_bf16 v[58:61], v[172:175], v[218:221], v[58:61]
	v_mfma_f32_16x16x32_bf16 v[54:57], v[180:183], v[218:221], v[54:57]
	v_mfma_f32_16x16x32_bf16 v[50:53], v[172:175], v[226:229], v[50:53]
	v_mfma_f32_16x16x32_bf16 v[46:49], v[180:183], v[226:229], v[46:49]
	v_mfma_f32_16x16x32_bf16 v[38:41], v[172:175], v[234:237], v[38:41]
	v_mfma_f32_16x16x32_bf16 v[30:33], v[180:183], v[234:237], v[30:33]
	v_mfma_f32_16x16x32_bf16 v[42:45], v[184:187], v[206:209], v[42:45]
	v_mfma_f32_16x16x32_bf16 v[34:37], v[196:199], v[206:209], v[34:37]
	v_mfma_f32_16x16x32_bf16 v[26:29], v[184:187], v[214:217], v[26:29]
	v_mfma_f32_16x16x32_bf16 v[22:25], v[196:199], v[214:217], v[22:25]
	v_mfma_f32_16x16x32_bf16 v[18:21], v[184:187], v[222:225], v[18:21]
	v_mfma_f32_16x16x32_bf16 v[14:17], v[196:199], v[222:225], v[14:17]
	v_mfma_f32_16x16x32_bf16 v[10:13], v[184:187], v[230:233], v[10:13]
	v_mfma_f32_16x16x32_bf16 v[6:9], v[196:199], v[230:233], v[6:9]
	v_mfma_f32_16x16x32_bf16 v[42:45], v[188:191], v[210:213], v[42:45]
	v_mfma_f32_16x16x32_bf16 v[34:37], v[200:203], v[210:213], v[34:37]
	v_mfma_f32_16x16x32_bf16 v[26:29], v[188:191], v[218:221], v[26:29]
	v_mfma_f32_16x16x32_bf16 v[22:25], v[200:203], v[218:221], v[22:25]
	v_mfma_f32_16x16x32_bf16 v[18:21], v[188:191], v[226:229], v[18:21]
	v_mfma_f32_16x16x32_bf16 v[14:17], v[200:203], v[226:229], v[14:17]
	v_mfma_f32_16x16x32_bf16 v[10:13], v[188:191], v[234:237], v[10:13]
	v_mfma_f32_16x16x32_bf16 v[6:9], v[200:203], v[234:237], v[6:9]
	s_barrier
	s_add_i32 s80, s72, s61
	v_lshl_add_u64 v[166:167], s[42:43], 0, v[134:135]
	s_mov_b32 m0, s80
	ds_read_b128 v[206:209], v170 offset:16384
	ds_read_b128 v[210:213], v170 offset:17408
	ds_read_b128 v[214:217], v170 offset:18432
	ds_read_b128 v[218:221], v170 offset:19456
	ds_read_b128 v[222:225], v170 offset:20480
	ds_read_b128 v[226:229], v170 offset:21504
	ds_read_b128 v[230:233], v170 offset:22528
	ds_read_b128 v[234:237], v170 offset:23552
	global_load_lds_dwordx4 v[166:167], off
	s_add_i32 m0, s80, 0x2000
	s_add_u32 s80, s42, 0x100000
	v_lshl_add_u64 v[192:193], s[42:43], 0, v[138:139]
	s_addc_u32 s81, s43, 0
	s_add_i32 s82, s73, s61
	global_load_lds_dwordx4 v[192:193], off
	v_lshl_add_u64 v[238:239], s[80:81], 0, v[134:135]
	s_mov_b32 m0, s82
	v_lshl_add_u64 v[240:241], s[46:47], 0, v[136:137]
	global_load_lds_dwordx4 v[238:239], off
	v_lshl_add_u64 v[238:239], s[80:81], 0, v[138:139]
	s_add_i32 m0, s82, 0x2000
	s_nop 0
	global_load_lds_dwordx4 v[238:239], off
	v_lshl_add_u64 v[238:239], s[46:47], 0, v[132:133]
	s_mov_b32 m0, s62
	s_nop 0
	global_load_lds_dwordx4 v[238:239], off
	s_mov_b32 m0, s63
	s_nop 0
	global_load_lds_dwordx4 v[240:241], off
	s_waitcnt vmcnt(8)
	s_waitcnt lgkmcnt(0)
	s_barrier
	v_mfma_f32_16x16x32_bf16 v[126:129], v[162:165], v[206:209], v[126:129]
	v_mfma_f32_16x16x32_bf16 v[122:125], v[176:179], v[206:209], v[122:125]
	v_mfma_f32_16x16x32_bf16 v[110:113], v[162:165], v[214:217], v[110:113]
	v_mfma_f32_16x16x32_bf16 v[106:109], v[176:179], v[214:217], v[106:109]
	v_mfma_f32_16x16x32_bf16 v[94:97], v[162:165], v[222:225], v[94:97]
	v_mfma_f32_16x16x32_bf16 v[90:93], v[176:179], v[222:225], v[90:93]
	v_mfma_f32_16x16x32_bf16 v[78:81], v[162:165], v[230:233], v[78:81]
	v_mfma_f32_16x16x32_bf16 v[74:77], v[176:179], v[230:233], v[74:77]
	v_mfma_f32_16x16x32_bf16 v[126:129], v[172:175], v[210:213], v[126:129]
	v_mfma_f32_16x16x32_bf16 v[122:125], v[180:183], v[210:213], v[122:125]
	v_mfma_f32_16x16x32_bf16 v[110:113], v[172:175], v[218:221], v[110:113]
	v_mfma_f32_16x16x32_bf16 v[106:109], v[180:183], v[218:221], v[106:109]
	v_mfma_f32_16x16x32_bf16 v[94:97], v[172:175], v[226:229], v[94:97]
	v_mfma_f32_16x16x32_bf16 v[90:93], v[180:183], v[226:229], v[90:93]
	v_mfma_f32_16x16x32_bf16 v[78:81], v[172:175], v[234:237], v[78:81]
	v_mfma_f32_16x16x32_bf16 v[74:77], v[180:183], v[234:237], v[74:77]
	v_mfma_f32_16x16x32_bf16 v[118:121], v[184:187], v[206:209], v[118:121]
	v_mfma_f32_16x16x32_bf16 v[114:117], v[196:199], v[206:209], v[114:117]
	v_mfma_f32_16x16x32_bf16 v[102:105], v[184:187], v[214:217], v[102:105]
	v_mfma_f32_16x16x32_bf16 v[98:101], v[196:199], v[214:217], v[98:101]
	v_mfma_f32_16x16x32_bf16 v[86:89], v[184:187], v[222:225], v[86:89]
	v_mfma_f32_16x16x32_bf16 v[82:85], v[196:199], v[222:225], v[82:85]
	v_mfma_f32_16x16x32_bf16 v[70:73], v[184:187], v[230:233], v[70:73]
	v_mfma_f32_16x16x32_bf16 v[2:5], v[196:199], v[230:233], v[2:5]
	v_mfma_f32_16x16x32_bf16 v[118:121], v[188:191], v[210:213], v[118:121]
	v_mfma_f32_16x16x32_bf16 v[114:117], v[200:203], v[210:213], v[114:117]
	v_mfma_f32_16x16x32_bf16 v[102:105], v[188:191], v[218:221], v[102:105]
	v_mfma_f32_16x16x32_bf16 v[98:101], v[200:203], v[218:221], v[98:101]
	v_mfma_f32_16x16x32_bf16 v[86:89], v[188:191], v[226:229], v[86:89]
	v_mfma_f32_16x16x32_bf16 v[82:85], v[200:203], v[226:229], v[82:85]
	v_mfma_f32_16x16x32_bf16 v[70:73], v[188:191], v[234:237], v[70:73]
	v_mfma_f32_16x16x32_bf16 v[2:5], v[200:203], v[234:237], v[2:5]
	s_barrier
	s_add_i32 s80, 0, 0x18000
	s_add_i32 s81, 0, 0x1c000
	v_add_u32_e32 v180, s80, v131
	v_add_u32_e32 v200, s81, v131
	ds_read_b128 v[162:165], v180
	ds_read_b128 v[172:175], v180 offset:1024
	ds_read_b128 v[176:179], v180 offset:2048
	ds_read_b128 v[180:183], v180 offset:3072
	ds_read_b128 v[184:187], v200
	ds_read_b128 v[188:191], v200 offset:1024
	ds_read_b128 v[196:199], v200 offset:2048
	ds_read_b128 v[200:203], v200 offset:3072
	s_add_u32 s46, s46, 0x100000
	s_addc_u32 s47, s47, 0
	s_mov_b32 m0, s64
	v_lshl_add_u64 v[242:243], s[46:47], 0, v[132:133]
	ds_read_b128 v[206:209], v170 offset:32768
	ds_read_b128 v[210:213], v170 offset:33792
	ds_read_b128 v[214:217], v170 offset:34816
	ds_read_b128 v[218:221], v170 offset:35840
	ds_read_b128 v[222:225], v170 offset:36864
	ds_read_b128 v[226:229], v170 offset:37888
	ds_read_b128 v[230:233], v170 offset:38912
	ds_read_b128 v[234:237], v170 offset:39936
	global_load_lds_dwordx4 v[242:243], off
	v_lshl_add_u64 v[242:243], s[46:47], 0, v[136:137]
	s_mov_b32 m0, s65
	s_nop 0
	global_load_lds_dwordx4 v[242:243], off
	s_waitcnt vmcnt(8)
	s_waitcnt lgkmcnt(0)
	s_barrier
	v_mfma_f32_16x16x32_bf16 v[66:69], v[162:165], v[206:209], v[66:69]
	v_mfma_f32_16x16x32_bf16 v[62:65], v[176:179], v[206:209], v[62:65]
	v_mfma_f32_16x16x32_bf16 v[58:61], v[162:165], v[214:217], v[58:61]
	v_mfma_f32_16x16x32_bf16 v[54:57], v[176:179], v[214:217], v[54:57]
	v_mfma_f32_16x16x32_bf16 v[50:53], v[162:165], v[222:225], v[50:53]
	v_mfma_f32_16x16x32_bf16 v[46:49], v[176:179], v[222:225], v[46:49]
	v_mfma_f32_16x16x32_bf16 v[38:41], v[162:165], v[230:233], v[38:41]
	v_mfma_f32_16x16x32_bf16 v[30:33], v[176:179], v[230:233], v[30:33]
	v_mfma_f32_16x16x32_bf16 v[66:69], v[172:175], v[210:213], v[66:69]
	v_mfma_f32_16x16x32_bf16 v[62:65], v[180:183], v[210:213], v[62:65]
	v_mfma_f32_16x16x32_bf16 v[58:61], v[172:175], v[218:221], v[58:61]
	v_mfma_f32_16x16x32_bf16 v[54:57], v[180:183], v[218:221], v[54:57]
	v_mfma_f32_16x16x32_bf16 v[50:53], v[172:175], v[226:229], v[50:53]
	v_mfma_f32_16x16x32_bf16 v[46:49], v[180:183], v[226:229], v[46:49]
	v_mfma_f32_16x16x32_bf16 v[38:41], v[172:175], v[234:237], v[38:41]
	v_mfma_f32_16x16x32_bf16 v[30:33], v[180:183], v[234:237], v[30:33]
	v_mfma_f32_16x16x32_bf16 v[42:45], v[184:187], v[206:209], v[42:45]
	v_mfma_f32_16x16x32_bf16 v[34:37], v[196:199], v[206:209], v[34:37]
	v_mfma_f32_16x16x32_bf16 v[26:29], v[184:187], v[214:217], v[26:29]
	v_mfma_f32_16x16x32_bf16 v[22:25], v[196:199], v[214:217], v[22:25]
	v_mfma_f32_16x16x32_bf16 v[18:21], v[184:187], v[222:225], v[18:21]
	v_mfma_f32_16x16x32_bf16 v[14:17], v[196:199], v[222:225], v[14:17]
	v_mfma_f32_16x16x32_bf16 v[10:13], v[184:187], v[230:233], v[10:13]
	v_mfma_f32_16x16x32_bf16 v[6:9], v[196:199], v[230:233], v[6:9]
	v_mfma_f32_16x16x32_bf16 v[42:45], v[188:191], v[210:213], v[42:45]
	v_mfma_f32_16x16x32_bf16 v[34:37], v[200:203], v[210:213], v[34:37]
	v_mfma_f32_16x16x32_bf16 v[26:29], v[188:191], v[218:221], v[26:29]
	v_mfma_f32_16x16x32_bf16 v[22:25], v[200:203], v[218:221], v[22:25]
	v_mfma_f32_16x16x32_bf16 v[18:21], v[188:191], v[226:229], v[18:21]
	v_mfma_f32_16x16x32_bf16 v[14:17], v[200:203], v[226:229], v[14:17]
	v_mfma_f32_16x16x32_bf16 v[10:13], v[188:191], v[234:237], v[10:13]
	v_mfma_f32_16x16x32_bf16 v[6:9], v[200:203], v[234:237], v[6:9]
	s_barrier
	s_add_i32 s46, s80, s61
	v_lshl_add_u64 v[166:167], v[166:167], 0, s[18:19]
	s_mov_b32 m0, s46
	ds_read_b128 v[206:209], v170 offset:49152
	ds_read_b128 v[210:213], v170 offset:50176
	ds_read_b128 v[214:217], v170 offset:51200
	ds_read_b128 v[218:221], v170 offset:52224
	ds_read_b128 v[222:225], v170 offset:53248
	ds_read_b128 v[226:229], v170 offset:54272
	ds_read_b128 v[230:233], v170 offset:55296
	ds_read_b128 v[234:237], v170 offset:56320
	global_load_lds_dwordx4 v[166:167], off
	s_add_i32 m0, s46, 0x2000
	s_add_u32 s42, s42, 0x100080
	v_lshl_add_u64 v[166:167], v[192:193], 0, s[18:19]
	s_addc_u32 s43, s43, 0
	s_add_i32 s46, s81, s61
	global_load_lds_dwordx4 v[166:167], off
	v_lshl_add_u64 v[166:167], s[42:43], 0, v[134:135]
	s_mov_b32 m0, s46
	s_nop 0
	global_load_lds_dwordx4 v[166:167], off
	v_lshl_add_u64 v[166:167], s[42:43], 0, v[138:139]
	s_add_i32 m0, s46, 0x2000
	s_nop 0
	global_load_lds_dwordx4 v[166:167], off
	v_lshl_add_u64 v[166:167], v[238:239], 0, s[18:19]
	s_mov_b32 m0, s69
	s_nop 0
	global_load_lds_dwordx4 v[166:167], off
	v_lshl_add_u64 v[166:167], v[240:241], 0, s[18:19]
	s_mov_b32 m0, s70
	s_nop 0
	global_load_lds_dwordx4 v[166:167], off
	s_nop 0
	s_waitcnt vmcnt(8)
	s_waitcnt lgkmcnt(0)
	s_barrier
	v_mfma_f32_16x16x32_bf16 v[126:129], v[162:165], v[206:209], v[126:129]
	v_mfma_f32_16x16x32_bf16 v[122:125], v[176:179], v[206:209], v[122:125]
	v_mfma_f32_16x16x32_bf16 v[110:113], v[162:165], v[214:217], v[110:113]
	v_mfma_f32_16x16x32_bf16 v[106:109], v[176:179], v[214:217], v[106:109]
	v_mfma_f32_16x16x32_bf16 v[94:97], v[162:165], v[222:225], v[94:97]
	v_mfma_f32_16x16x32_bf16 v[90:93], v[176:179], v[222:225], v[90:93]
	v_mfma_f32_16x16x32_bf16 v[78:81], v[162:165], v[230:233], v[78:81]
	v_mfma_f32_16x16x32_bf16 v[74:77], v[176:179], v[230:233], v[74:77]
	v_mfma_f32_16x16x32_bf16 v[126:129], v[172:175], v[210:213], v[126:129]
	v_mfma_f32_16x16x32_bf16 v[122:125], v[180:183], v[210:213], v[122:125]
	v_mfma_f32_16x16x32_bf16 v[110:113], v[172:175], v[218:221], v[110:113]
	v_mfma_f32_16x16x32_bf16 v[106:109], v[180:183], v[218:221], v[106:109]
	v_mfma_f32_16x16x32_bf16 v[94:97], v[172:175], v[226:229], v[94:97]
	v_mfma_f32_16x16x32_bf16 v[90:93], v[180:183], v[226:229], v[90:93]
	v_mfma_f32_16x16x32_bf16 v[78:81], v[172:175], v[234:237], v[78:81]
	v_mfma_f32_16x16x32_bf16 v[74:77], v[180:183], v[234:237], v[74:77]
	v_mfma_f32_16x16x32_bf16 v[118:121], v[184:187], v[206:209], v[118:121]
	v_mfma_f32_16x16x32_bf16 v[114:117], v[196:199], v[206:209], v[114:117]
	v_mfma_f32_16x16x32_bf16 v[102:105], v[184:187], v[214:217], v[102:105]
	v_mfma_f32_16x16x32_bf16 v[98:101], v[196:199], v[214:217], v[98:101]
	v_mfma_f32_16x16x32_bf16 v[86:89], v[184:187], v[222:225], v[86:89]
	v_mfma_f32_16x16x32_bf16 v[82:85], v[196:199], v[222:225], v[82:85]
	v_mfma_f32_16x16x32_bf16 v[70:73], v[184:187], v[230:233], v[70:73]
	v_mfma_f32_16x16x32_bf16 v[2:5], v[196:199], v[230:233], v[2:5]
	v_mfma_f32_16x16x32_bf16 v[118:121], v[188:191], v[210:213], v[118:121]
	v_mfma_f32_16x16x32_bf16 v[114:117], v[200:203], v[210:213], v[114:117]
	v_mfma_f32_16x16x32_bf16 v[102:105], v[188:191], v[218:221], v[102:105]
	v_mfma_f32_16x16x32_bf16 v[98:101], v[200:203], v[218:221], v[98:101]
	v_mfma_f32_16x16x32_bf16 v[86:89], v[188:191], v[226:229], v[86:89]
	v_mfma_f32_16x16x32_bf16 v[82:85], v[200:203], v[226:229], v[82:85]
	v_mfma_f32_16x16x32_bf16 v[70:73], v[188:191], v[234:237], v[70:73]
	v_mfma_f32_16x16x32_bf16 v[2:5], v[200:203], v[234:237], v[2:5]
	s_barrier
	s_add_u32 s8, s8, 0x100
	s_addc_u32 s9, s9, 0
	s_add_u32 s49, s49, 0x100
	s_addc_u32 s53, s53, 0
	s_cmp_ge_i32 s55, s3
	s_mov_b32 s42, s55
	s_cbranch_scc0 .LBB0_1869
	s_and_b64 vcc, exec, s[20:21]
	s_cbranch_vccz .LBB0_1874
	s_barrier
	v_lshl_or_b32 v162, s40, 8, v141
	s_cmp_lt_i32 s10, 0
	s_mov_b64 s[8:9], -1
	s_cbranch_scc1 .LBB0_1875

.LBB0_3649:
	ds_read_b128 v[152:155], v162
	ds_read_b128 v[156:159], v162 offset:1024
	ds_read_b128 v[168:171], v162 offset:2048
	ds_read_b128 v[172:175], v162 offset:3072
	ds_read_b128 v[176:179], v163
	ds_read_b128 v[180:183], v163 offset:1024
	ds_read_b128 v[184:187], v163 offset:2048
	ds_read_b128 v[188:191], v163 offset:3072
	s_add_i32 s86, s48, 2
	s_add_u32 s49, s6, 0xfff00080
	s_addc_u32 s64, s7, -1
	s_cmp_eq_u32 s51, s48
	s_cselect_b32 s48, s58, s53
	s_cselect_b32 s65, s57, s64
	s_cselect_b32 s64, s56, s49
	s_cselect_b32 s49, s59, s55
	v_lshl_add_u64 v[192:193], s[6:7], 0, v[140:141]
	s_add_i32 m0, s61, 0xc000
	ds_read_b128 v[196:199], v164
	ds_read_b128 v[200:203], v164 offset:1024
	ds_read_b128 v[206:209], v164 offset:2048
	ds_read_b128 v[210:213], v164 offset:3072
	ds_read_b128 v[214:217], v164 offset:4096
	ds_read_b128 v[218:221], v164 offset:5120
	ds_read_b128 v[222:225], v164 offset:6144
	ds_read_b128 v[226:229], v164 offset:7168
	global_load_lds_dwordx4 v[192:193], off
	v_lshl_add_u64 v[192:193], s[6:7], 0, v[142:143]
	s_add_i32 m0, s61, 0xe000
	s_nop 0
	global_load_lds_dwordx4 v[192:193], off
	s_nop 0
	s_waitcnt vmcnt(8)
	s_waitcnt lgkmcnt(0)
	s_barrier
	v_mfma_f32_16x16x32_bf16 v[126:129], v[152:155], v[196:199], v[126:129]
	v_mfma_f32_16x16x32_bf16 v[122:125], v[168:171], v[196:199], v[122:125]
	v_mfma_f32_16x16x32_bf16 v[110:113], v[152:155], v[206:209], v[110:113]
	v_mfma_f32_16x16x32_bf16 v[106:109], v[168:171], v[206:209], v[106:109]
	v_mfma_f32_16x16x32_bf16 v[94:97], v[152:155], v[214:217], v[94:97]
	v_mfma_f32_16x16x32_bf16 v[90:93], v[168:171], v[214:217], v[90:93]
	v_mfma_f32_16x16x32_bf16 v[78:81], v[152:155], v[222:225], v[78:81]
	v_mfma_f32_16x16x32_bf16 v[74:77], v[168:171], v[222:225], v[74:77]
	v_mfma_f32_16x16x32_bf16 v[126:129], v[156:159], v[200:203], v[126:129]
	v_mfma_f32_16x16x32_bf16 v[122:125], v[172:175], v[200:203], v[122:125]
	v_mfma_f32_16x16x32_bf16 v[110:113], v[156:159], v[210:213], v[110:113]
	v_mfma_f32_16x16x32_bf16 v[106:109], v[172:175], v[210:213], v[106:109]
	v_mfma_f32_16x16x32_bf16 v[94:97], v[156:159], v[218:221], v[94:97]
	v_mfma_f32_16x16x32_bf16 v[90:93], v[172:175], v[218:221], v[90:93]
	v_mfma_f32_16x16x32_bf16 v[78:81], v[156:159], v[226:229], v[78:81]
	v_mfma_f32_16x16x32_bf16 v[74:77], v[172:175], v[226:229], v[74:77]
	v_mfma_f32_16x16x32_bf16 v[118:121], v[176:179], v[196:199], v[118:121]
	v_mfma_f32_16x16x32_bf16 v[114:117], v[184:187], v[196:199], v[114:117]
	v_mfma_f32_16x16x32_bf16 v[102:105], v[176:179], v[206:209], v[102:105]
	v_mfma_f32_16x16x32_bf16 v[98:101], v[184:187], v[206:209], v[98:101]
	v_mfma_f32_16x16x32_bf16 v[86:89], v[176:179], v[214:217], v[86:89]
	v_mfma_f32_16x16x32_bf16 v[82:85], v[184:187], v[214:217], v[82:85]
	v_mfma_f32_16x16x32_bf16 v[70:73], v[176:179], v[222:225], v[70:73]
	v_mfma_f32_16x16x32_bf16 v[66:69], v[184:187], v[222:225], v[66:69]
	v_mfma_f32_16x16x32_bf16 v[118:121], v[180:183], v[200:203], v[118:121]
	v_mfma_f32_16x16x32_bf16 v[114:117], v[188:191], v[200:203], v[114:117]
	v_mfma_f32_16x16x32_bf16 v[102:105], v[180:183], v[210:213], v[102:105]
	v_mfma_f32_16x16x32_bf16 v[98:101], v[188:191], v[210:213], v[98:101]
	v_mfma_f32_16x16x32_bf16 v[86:89], v[180:183], v[218:221], v[86:89]
	v_mfma_f32_16x16x32_bf16 v[82:85], v[188:191], v[218:221], v[82:85]
	v_mfma_f32_16x16x32_bf16 v[70:73], v[180:183], v[226:229], v[70:73]
	v_mfma_f32_16x16x32_bf16 v[66:69], v[188:191], v[226:229], v[66:69]
	s_barrier
	s_add_i32 s87, s75, s66
	v_lshl_add_u64 v[192:193], s[48:49], 0, v[134:135]
	s_mov_b32 m0, s87
	ds_read_b128 v[196:199], v164 offset:16384
	ds_read_b128 v[200:203], v164 offset:17408
	ds_read_b128 v[206:209], v164 offset:18432
	ds_read_b128 v[210:213], v164 offset:19456
	ds_read_b128 v[214:217], v164 offset:20480
	ds_read_b128 v[218:221], v164 offset:21504
	ds_read_b128 v[222:225], v164 offset:22528
	ds_read_b128 v[226:229], v164 offset:23552
	global_load_lds_dwordx4 v[192:193], off
	s_add_i32 m0, s87, 0x2000
	s_add_u32 s88, s48, 0x100000
	v_lshl_add_u64 v[230:231], s[48:49], 0, v[138:139]
	s_addc_u32 s89, s49, 0
	s_add_i32 s87, s76, s66
	global_load_lds_dwordx4 v[230:231], off
	v_lshl_add_u64 v[232:233], s[88:89], 0, v[134:135]
	s_mov_b32 m0, s87
	v_lshl_add_u64 v[234:235], s[64:65], 0, v[136:137]
	global_load_lds_dwordx4 v[232:233], off
	v_lshl_add_u64 v[232:233], s[88:89], 0, v[138:139]
	s_add_i32 m0, s87, 0x2000
	s_nop 0
	global_load_lds_dwordx4 v[232:233], off
	v_lshl_add_u64 v[232:233], s[64:65], 0, v[132:133]
	s_mov_b32 m0, s61
	s_nop 0
	global_load_lds_dwordx4 v[232:233], off
	s_mov_b32 m0, s63
	s_nop 0
	global_load_lds_dwordx4 v[234:235], off
	s_waitcnt vmcnt(8)
	s_waitcnt lgkmcnt(0)
	s_barrier
	v_mfma_f32_16x16x32_bf16 v[62:65], v[152:155], v[196:199], v[62:65]
	v_mfma_f32_16x16x32_bf16 v[58:61], v[168:171], v[196:199], v[58:61]
	v_mfma_f32_16x16x32_bf16 v[46:49], v[152:155], v[206:209], v[46:49]
	v_mfma_f32_16x16x32_bf16 v[42:45], v[168:171], v[206:209], v[42:45]
	v_mfma_f32_16x16x32_bf16 v[30:33], v[152:155], v[214:217], v[30:33]
	v_mfma_f32_16x16x32_bf16 v[26:29], v[168:171], v[214:217], v[26:29]
	v_mfma_f32_16x16x32_bf16 v[14:17], v[152:155], v[222:225], v[14:17]
	v_mfma_f32_16x16x32_bf16 v[10:13], v[168:171], v[222:225], v[10:13]
	v_mfma_f32_16x16x32_bf16 v[62:65], v[156:159], v[200:203], v[62:65]
	v_mfma_f32_16x16x32_bf16 v[58:61], v[172:175], v[200:203], v[58:61]
	v_mfma_f32_16x16x32_bf16 v[46:49], v[156:159], v[210:213], v[46:49]
	v_mfma_f32_16x16x32_bf16 v[42:45], v[172:175], v[210:213], v[42:45]
	v_mfma_f32_16x16x32_bf16 v[30:33], v[156:159], v[218:221], v[30:33]
	v_mfma_f32_16x16x32_bf16 v[26:29], v[172:175], v[218:221], v[26:29]
	v_mfma_f32_16x16x32_bf16 v[14:17], v[156:159], v[226:229], v[14:17]
	v_mfma_f32_16x16x32_bf16 v[10:13], v[172:175], v[226:229], v[10:13]
	v_mfma_f32_16x16x32_bf16 v[54:57], v[176:179], v[196:199], v[54:57]
	v_mfma_f32_16x16x32_bf16 v[50:53], v[184:187], v[196:199], v[50:53]
	v_mfma_f32_16x16x32_bf16 v[38:41], v[176:179], v[206:209], v[38:41]
	v_mfma_f32_16x16x32_bf16 v[34:37], v[184:187], v[206:209], v[34:37]
	v_mfma_f32_16x16x32_bf16 v[22:25], v[176:179], v[214:217], v[22:25]
	v_mfma_f32_16x16x32_bf16 v[18:21], v[184:187], v[214:217], v[18:21]
	v_mfma_f32_16x16x32_bf16 v[6:9], v[176:179], v[222:225], v[6:9]
	v_mfma_f32_16x16x32_bf16 v[2:5], v[184:187], v[222:225], v[2:5]
	v_mfma_f32_16x16x32_bf16 v[54:57], v[180:183], v[200:203], v[54:57]
	v_mfma_f32_16x16x32_bf16 v[50:53], v[188:191], v[200:203], v[50:53]
	v_mfma_f32_16x16x32_bf16 v[38:41], v[180:183], v[210:213], v[38:41]
	v_mfma_f32_16x16x32_bf16 v[34:37], v[188:191], v[210:213], v[34:37]
	v_mfma_f32_16x16x32_bf16 v[22:25], v[180:183], v[218:221], v[22:25]
	v_mfma_f32_16x16x32_bf16 v[18:21], v[188:191], v[218:221], v[18:21]
	v_mfma_f32_16x16x32_bf16 v[6:9], v[180:183], v[226:229], v[6:9]
	v_mfma_f32_16x16x32_bf16 v[2:5], v[188:191], v[226:229], v[2:5]
	s_barrier
	s_add_i32 s87, 0, 0x18000
	v_add_u32_e32 v167, s87, v160
	s_add_i32 s88, 0, 0x1c000
	ds_read_b128 v[152:155], v167
	ds_read_b128 v[156:159], v167 offset:1024
	ds_read_b128 v[168:171], v167 offset:2048
	ds_read_b128 v[172:175], v167 offset:3072
	v_add_u32_e32 v167, s88, v160
	ds_read_b128 v[176:179], v167
	ds_read_b128 v[180:183], v167 offset:1024
	ds_read_b128 v[184:187], v167 offset:2048
	ds_read_b128 v[188:191], v167 offset:3072
	s_add_u32 s64, s64, 0x100000
	s_addc_u32 s65, s65, 0
	s_mov_b32 m0, s67
	v_lshl_add_u64 v[236:237], s[64:65], 0, v[132:133]
	ds_read_b128 v[196:199], v164 offset:32768
	ds_read_b128 v[200:203], v164 offset:33792
	ds_read_b128 v[206:209], v164 offset:34816
	ds_read_b128 v[210:213], v164 offset:35840
	ds_read_b128 v[214:217], v164 offset:36864
	ds_read_b128 v[218:221], v164 offset:37888
	ds_read_b128 v[222:225], v164 offset:38912
	ds_read_b128 v[226:229], v164 offset:39936
	global_load_lds_dwordx4 v[236:237], off
	v_lshl_add_u64 v[236:237], s[64:65], 0, v[136:137]
	s_mov_b32 m0, s68
	s_nop 0
	global_load_lds_dwordx4 v[236:237], off
	s_waitcnt vmcnt(8)
	s_waitcnt lgkmcnt(0)
	s_barrier
	v_mfma_f32_16x16x32_bf16 v[126:129], v[152:155], v[196:199], v[126:129]
	v_mfma_f32_16x16x32_bf16 v[122:125], v[168:171], v[196:199], v[122:125]
	v_mfma_f32_16x16x32_bf16 v[110:113], v[152:155], v[206:209], v[110:113]
	v_mfma_f32_16x16x32_bf16 v[106:109], v[168:171], v[206:209], v[106:109]
	v_mfma_f32_16x16x32_bf16 v[94:97], v[152:155], v[214:217], v[94:97]
	v_mfma_f32_16x16x32_bf16 v[90:93], v[168:171], v[214:217], v[90:93]
	v_mfma_f32_16x16x32_bf16 v[78:81], v[152:155], v[222:225], v[78:81]
	v_mfma_f32_16x16x32_bf16 v[74:77], v[168:171], v[222:225], v[74:77]
	v_mfma_f32_16x16x32_bf16 v[126:129], v[156:159], v[200:203], v[126:129]
	v_mfma_f32_16x16x32_bf16 v[122:125], v[172:175], v[200:203], v[122:125]
	v_mfma_f32_16x16x32_bf16 v[110:113], v[156:159], v[210:213], v[110:113]
	v_mfma_f32_16x16x32_bf16 v[106:109], v[172:175], v[210:213], v[106:109]
	v_mfma_f32_16x16x32_bf16 v[94:97], v[156:159], v[218:221], v[94:97]
	v_mfma_f32_16x16x32_bf16 v[90:93], v[172:175], v[218:221], v[90:93]
	v_mfma_f32_16x16x32_bf16 v[78:81], v[156:159], v[226:229], v[78:81]
	v_mfma_f32_16x16x32_bf16 v[74:77], v[172:175], v[226:229], v[74:77]
	v_mfma_f32_16x16x32_bf16 v[118:121], v[176:179], v[196:199], v[118:121]
	v_mfma_f32_16x16x32_bf16 v[114:117], v[184:187], v[196:199], v[114:117]
	v_mfma_f32_16x16x32_bf16 v[102:105], v[176:179], v[206:209], v[102:105]
	v_mfma_f32_16x16x32_bf16 v[98:101], v[184:187], v[206:209], v[98:101]
	v_mfma_f32_16x16x32_bf16 v[86:89], v[176:179], v[214:217], v[86:89]
	v_mfma_f32_16x16x32_bf16 v[82:85], v[184:187], v[214:217], v[82:85]
	v_mfma_f32_16x16x32_bf16 v[70:73], v[176:179], v[222:225], v[70:73]
	v_mfma_f32_16x16x32_bf16 v[66:69], v[184:187], v[222:225], v[66:69]
	v_mfma_f32_16x16x32_bf16 v[118:121], v[180:183], v[200:203], v[118:121]
	v_mfma_f32_16x16x32_bf16 v[114:117], v[188:191], v[200:203], v[114:117]
	v_mfma_f32_16x16x32_bf16 v[102:105], v[180:183], v[210:213], v[102:105]
	v_mfma_f32_16x16x32_bf16 v[98:101], v[188:191], v[210:213], v[98:101]
	v_mfma_f32_16x16x32_bf16 v[86:89], v[180:183], v[218:221], v[86:89]
	v_mfma_f32_16x16x32_bf16 v[82:85], v[188:191], v[218:221], v[82:85]
	v_mfma_f32_16x16x32_bf16 v[70:73], v[180:183], v[226:229], v[70:73]
	v_mfma_f32_16x16x32_bf16 v[66:69], v[188:191], v[226:229], v[66:69]
	s_barrier
	s_add_i32 s64, s87, s66
	v_lshl_add_u64 v[192:193], v[192:193], 0, s[20:21]
	s_mov_b32 m0, s64
	ds_read_b128 v[196:199], v164 offset:49152
	ds_read_b128 v[200:203], v164 offset:50176
	ds_read_b128 v[206:209], v164 offset:51200
	ds_read_b128 v[210:213], v164 offset:52224
	ds_read_b128 v[214:217], v164 offset:53248
	ds_read_b128 v[218:221], v164 offset:54272
	ds_read_b128 v[222:225], v164 offset:55296
	ds_read_b128 v[226:229], v164 offset:56320
	global_load_lds_dwordx4 v[192:193], off
	s_add_i32 m0, s64, 0x2000
	s_add_u32 s48, s48, 0x100080
	v_lshl_add_u64 v[192:193], v[230:231], 0, s[20:21]
	s_addc_u32 s49, s49, 0
	s_add_i32 s64, s88, s66
	global_load_lds_dwordx4 v[192:193], off
	v_lshl_add_u64 v[192:193], s[48:49], 0, v[134:135]
	s_mov_b32 m0, s64
	s_nop 0
	global_load_lds_dwordx4 v[192:193], off
	v_lshl_add_u64 v[192:193], s[48:49], 0, v[138:139]
	s_add_i32 m0, s64, 0x2000
	s_nop 0
	global_load_lds_dwordx4 v[192:193], off
	v_lshl_add_u64 v[192:193], v[232:233], 0, s[20:21]
	s_mov_b32 m0, s72
	s_nop 0
	global_load_lds_dwordx4 v[192:193], off
	v_lshl_add_u64 v[192:193], v[234:235], 0, s[20:21]
	s_mov_b32 m0, s73
	s_nop 0
	global_load_lds_dwordx4 v[192:193], off
	s_nop 0
	s_waitcnt vmcnt(8)
	s_waitcnt lgkmcnt(0)
	s_barrier
	v_mfma_f32_16x16x32_bf16 v[62:65], v[152:155], v[196:199], v[62:65]
	v_mfma_f32_16x16x32_bf16 v[58:61], v[168:171], v[196:199], v[58:61]
	v_mfma_f32_16x16x32_bf16 v[46:49], v[152:155], v[206:209], v[46:49]
	v_mfma_f32_16x16x32_bf16 v[42:45], v[168:171], v[206:209], v[42:45]
	v_mfma_f32_16x16x32_bf16 v[30:33], v[152:155], v[214:217], v[30:33]
	v_mfma_f32_16x16x32_bf16 v[26:29], v[168:171], v[214:217], v[26:29]
	v_mfma_f32_16x16x32_bf16 v[14:17], v[152:155], v[222:225], v[14:17]
	v_mfma_f32_16x16x32_bf16 v[10:13], v[168:171], v[222:225], v[10:13]
	v_mfma_f32_16x16x32_bf16 v[62:65], v[156:159], v[200:203], v[62:65]
	v_mfma_f32_16x16x32_bf16 v[58:61], v[172:175], v[200:203], v[58:61]
	v_mfma_f32_16x16x32_bf16 v[46:49], v[156:159], v[210:213], v[46:49]
	v_mfma_f32_16x16x32_bf16 v[42:45], v[172:175], v[210:213], v[42:45]
	v_mfma_f32_16x16x32_bf16 v[30:33], v[156:159], v[218:221], v[30:33]
	v_mfma_f32_16x16x32_bf16 v[26:29], v[172:175], v[218:221], v[26:29]
	v_mfma_f32_16x16x32_bf16 v[14:17], v[156:159], v[226:229], v[14:17]
	v_mfma_f32_16x16x32_bf16 v[10:13], v[172:175], v[226:229], v[10:13]
	v_mfma_f32_16x16x32_bf16 v[54:57], v[176:179], v[196:199], v[54:57]
	v_mfma_f32_16x16x32_bf16 v[50:53], v[184:187], v[196:199], v[50:53]
	v_mfma_f32_16x16x32_bf16 v[38:41], v[176:179], v[206:209], v[38:41]
	v_mfma_f32_16x16x32_bf16 v[34:37], v[184:187], v[206:209], v[34:37]
	v_mfma_f32_16x16x32_bf16 v[22:25], v[176:179], v[214:217], v[22:25]
	v_mfma_f32_16x16x32_bf16 v[18:21], v[184:187], v[214:217], v[18:21]
	v_mfma_f32_16x16x32_bf16 v[6:9], v[176:179], v[222:225], v[6:9]
	v_mfma_f32_16x16x32_bf16 v[2:5], v[184:187], v[222:225], v[2:5]
	v_mfma_f32_16x16x32_bf16 v[54:57], v[180:183], v[200:203], v[54:57]
	v_mfma_f32_16x16x32_bf16 v[50:53], v[188:191], v[200:203], v[50:53]
	v_mfma_f32_16x16x32_bf16 v[38:41], v[180:183], v[210:213], v[38:41]
	v_mfma_f32_16x16x32_bf16 v[34:37], v[188:191], v[210:213], v[34:37]
	v_mfma_f32_16x16x32_bf16 v[22:25], v[180:183], v[218:221], v[22:25]
	v_mfma_f32_16x16x32_bf16 v[18:21], v[188:191], v[218:221], v[18:21]
	v_mfma_f32_16x16x32_bf16 v[6:9], v[180:183], v[226:229], v[6:9]
	v_mfma_f32_16x16x32_bf16 v[2:5], v[188:191], v[226:229], v[2:5]
	s_barrier
	s_add_u32 s6, s6, 0x100
	s_addc_u32 s7, s7, 0
	s_add_u32 s53, s53, 0x100
	s_addc_u32 s55, s55, 0
	s_cmp_ge_i32 s86, s85
	s_mov_b32 s48, s86
	s_cbranch_scc0 .LBB0_3649
	s_and_b64 vcc, exec, s[22:23]
	s_cbranch_vccz .LBB0_3652
	s_barrier

.LBB0_3789:
	ds_read_b128 v[162:165], v145
	ds_read_b128 v[166:169], v145 offset:1024
	ds_read_b128 v[170:173], v145 offset:2048
	ds_read_b128 v[174:177], v145 offset:3072
	ds_read_b128 v[178:181], v160
	ds_read_b128 v[182:185], v160 offset:1024
	ds_read_b128 v[186:189], v160 offset:2048
	ds_read_b128 v[190:193], v160 offset:3072
	s_add_i32 s63, s30, 2
	s_add_u32 s31, s28, 0xfff00080
	s_addc_u32 s34, s29, -1
	s_cmp_eq_u32 s60, s30
	s_cselect_b32 s30, s59, s61
	s_cselect_b32 s35, s19, s34
	s_cselect_b32 s34, s23, s31
	s_cselect_b32 s31, s21, s62
	v_lshl_add_u64 v[158:159], s[28:29], 0, v[148:149]
	s_add_i32 m0, s6, 0xc000
	ds_read_b128 v[196:199], v161
	ds_read_b128 v[200:203], v161 offset:1024
	ds_read_b128 v[206:209], v161 offset:2048
	ds_read_b128 v[210:213], v161 offset:3072
	ds_read_b128 v[214:217], v161 offset:4096
	ds_read_b128 v[218:221], v161 offset:5120
	ds_read_b128 v[222:225], v161 offset:6144
	ds_read_b128 v[226:229], v161 offset:7168
	global_load_lds_dwordx4 v[158:159], off
	v_lshl_add_u64 v[158:159], s[28:29], 0, v[150:151]
	s_add_i32 m0, s6, 0xe000
	s_nop 0
	global_load_lds_dwordx4 v[158:159], off
	s_waitcnt vmcnt(8)
	s_waitcnt lgkmcnt(0)
	s_barrier
	v_mfma_f32_16x16x32_bf16 v[126:129], v[162:165], v[196:199], v[126:129]
	v_mfma_f32_16x16x32_bf16 v[122:125], v[170:173], v[196:199], v[122:125]
	v_mfma_f32_16x16x32_bf16 v[118:121], v[162:165], v[206:209], v[118:121]
	v_mfma_f32_16x16x32_bf16 v[114:117], v[170:173], v[206:209], v[114:117]
	v_mfma_f32_16x16x32_bf16 v[102:105], v[162:165], v[214:217], v[102:105]
	v_mfma_f32_16x16x32_bf16 v[98:101], v[170:173], v[214:217], v[98:101]
	v_mfma_f32_16x16x32_bf16 v[42:45], v[162:165], v[222:225], v[42:45]
	v_mfma_f32_16x16x32_bf16 v[34:37], v[170:173], v[222:225], v[34:37]
	v_mfma_f32_16x16x32_bf16 v[126:129], v[166:169], v[200:203], v[126:129]
	v_mfma_f32_16x16x32_bf16 v[122:125], v[174:177], v[200:203], v[122:125]
	v_mfma_f32_16x16x32_bf16 v[118:121], v[166:169], v[210:213], v[118:121]
	v_mfma_f32_16x16x32_bf16 v[114:117], v[174:177], v[210:213], v[114:117]
	v_mfma_f32_16x16x32_bf16 v[102:105], v[166:169], v[218:221], v[102:105]
	v_mfma_f32_16x16x32_bf16 v[98:101], v[174:177], v[218:221], v[98:101]
	v_mfma_f32_16x16x32_bf16 v[42:45], v[166:169], v[226:229], v[42:45]
	v_mfma_f32_16x16x32_bf16 v[34:37], v[174:177], v[226:229], v[34:37]
	v_mfma_f32_16x16x32_bf16 v[110:113], v[178:181], v[196:199], v[110:113]
	v_mfma_f32_16x16x32_bf16 v[106:109], v[186:189], v[196:199], v[106:109]
	v_mfma_f32_16x16x32_bf16 v[94:97], v[178:181], v[206:209], v[94:97]
	v_mfma_f32_16x16x32_bf16 v[90:93], v[186:189], v[206:209], v[90:93]
	v_mfma_f32_16x16x32_bf16 v[86:89], v[178:181], v[214:217], v[86:89]
	v_mfma_f32_16x16x32_bf16 v[82:85], v[186:189], v[214:217], v[82:85]
	v_mfma_f32_16x16x32_bf16 v[30:33], v[178:181], v[222:225], v[30:33]
	v_mfma_f32_16x16x32_bf16 v[26:29], v[186:189], v[222:225], v[26:29]
	v_mfma_f32_16x16x32_bf16 v[110:113], v[182:185], v[200:203], v[110:113]
	v_mfma_f32_16x16x32_bf16 v[106:109], v[190:193], v[200:203], v[106:109]
	v_mfma_f32_16x16x32_bf16 v[94:97], v[182:185], v[210:213], v[94:97]
	v_mfma_f32_16x16x32_bf16 v[90:93], v[190:193], v[210:213], v[90:93]
	v_mfma_f32_16x16x32_bf16 v[86:89], v[182:185], v[218:221], v[86:89]
	v_mfma_f32_16x16x32_bf16 v[82:85], v[190:193], v[218:221], v[82:85]
	v_mfma_f32_16x16x32_bf16 v[30:33], v[182:185], v[226:229], v[30:33]
	v_mfma_f32_16x16x32_bf16 v[26:29], v[190:193], v[226:229], v[26:29]
	s_barrier
	s_add_i32 s64, s54, s40
	v_lshl_add_u64 v[158:159], s[30:31], 0, v[134:135]
	s_mov_b32 m0, s64
	ds_read_b128 v[196:199], v161 offset:16384
	ds_read_b128 v[200:203], v161 offset:17408
	ds_read_b128 v[206:209], v161 offset:18432
	ds_read_b128 v[210:213], v161 offset:19456
	ds_read_b128 v[214:217], v161 offset:20480
	ds_read_b128 v[218:221], v161 offset:21504
	ds_read_b128 v[222:225], v161 offset:22528
	ds_read_b128 v[226:229], v161 offset:23552
	global_load_lds_dwordx4 v[158:159], off
	s_add_i32 m0, s64, 0x2000
	s_add_u32 s64, s30, 0x100000
	v_lshl_add_u64 v[230:231], s[30:31], 0, v[132:133]
	s_addc_u32 s65, s31, 0
	s_add_i32 s66, s55, s40
	global_load_lds_dwordx4 v[230:231], off
	v_lshl_add_u64 v[232:233], s[64:65], 0, v[134:135]
	s_mov_b32 m0, s66
	v_lshl_add_u64 v[234:235], s[34:35], 0, v[132:133]
	global_load_lds_dwordx4 v[232:233], off
	v_lshl_add_u64 v[232:233], s[64:65], 0, v[132:133]
	s_add_i32 m0, s66, 0x2000
	s_nop 0
	global_load_lds_dwordx4 v[232:233], off
	v_lshl_add_u64 v[232:233], s[34:35], 0, v[134:135]
	s_mov_b32 m0, s6
	s_nop 0
	global_load_lds_dwordx4 v[232:233], off
	s_mov_b32 m0, s13
	s_nop 0
	global_load_lds_dwordx4 v[234:235], off
	s_waitcnt vmcnt(8)
	s_waitcnt lgkmcnt(0)
	s_barrier
	v_mfma_f32_16x16x32_bf16 v[78:81], v[162:165], v[196:199], v[78:81]
	v_mfma_f32_16x16x32_bf16 v[74:77], v[170:173], v[196:199], v[74:77]
	v_mfma_f32_16x16x32_bf16 v[70:73], v[162:165], v[206:209], v[70:73]
	v_mfma_f32_16x16x32_bf16 v[66:69], v[170:173], v[206:209], v[66:69]
	v_mfma_f32_16x16x32_bf16 v[54:57], v[162:165], v[214:217], v[54:57]
	v_mfma_f32_16x16x32_bf16 v[50:53], v[170:173], v[214:217], v[50:53]
	v_mfma_f32_16x16x32_bf16 v[14:17], v[162:165], v[222:225], v[14:17]
	v_mfma_f32_16x16x32_bf16 v[10:13], v[170:173], v[222:225], v[10:13]
	v_mfma_f32_16x16x32_bf16 v[78:81], v[166:169], v[200:203], v[78:81]
	v_mfma_f32_16x16x32_bf16 v[74:77], v[174:177], v[200:203], v[74:77]
	v_mfma_f32_16x16x32_bf16 v[70:73], v[166:169], v[210:213], v[70:73]
	v_mfma_f32_16x16x32_bf16 v[66:69], v[174:177], v[210:213], v[66:69]
	v_mfma_f32_16x16x32_bf16 v[54:57], v[166:169], v[218:221], v[54:57]
	v_mfma_f32_16x16x32_bf16 v[50:53], v[174:177], v[218:221], v[50:53]
	v_mfma_f32_16x16x32_bf16 v[14:17], v[166:169], v[226:229], v[14:17]
	v_mfma_f32_16x16x32_bf16 v[10:13], v[174:177], v[226:229], v[10:13]
	v_mfma_f32_16x16x32_bf16 v[62:65], v[178:181], v[196:199], v[62:65]
	v_mfma_f32_16x16x32_bf16 v[58:61], v[186:189], v[196:199], v[58:61]
	v_mfma_f32_16x16x32_bf16 v[46:49], v[178:181], v[206:209], v[46:49]
	v_mfma_f32_16x16x32_bf16 v[38:41], v[186:189], v[206:209], v[38:41]
	v_mfma_f32_16x16x32_bf16 v[22:25], v[178:181], v[214:217], v[22:25]
	v_mfma_f32_16x16x32_bf16 v[18:21], v[186:189], v[214:217], v[18:21]
	v_mfma_f32_16x16x32_bf16 v[6:9], v[178:181], v[222:225], v[6:9]
	v_mfma_f32_16x16x32_bf16 v[2:5], v[186:189], v[222:225], v[2:5]
	v_mfma_f32_16x16x32_bf16 v[62:65], v[182:185], v[200:203], v[62:65]
	v_mfma_f32_16x16x32_bf16 v[58:61], v[190:193], v[200:203], v[58:61]
	v_mfma_f32_16x16x32_bf16 v[46:49], v[182:185], v[210:213], v[46:49]
	v_mfma_f32_16x16x32_bf16 v[38:41], v[190:193], v[210:213], v[38:41]
	v_mfma_f32_16x16x32_bf16 v[22:25], v[182:185], v[218:221], v[22:25]
	v_mfma_f32_16x16x32_bf16 v[18:21], v[190:193], v[218:221], v[18:21]
	v_mfma_f32_16x16x32_bf16 v[6:9], v[182:185], v[226:229], v[6:9]
	v_mfma_f32_16x16x32_bf16 v[2:5], v[190:193], v[226:229], v[2:5]
	s_barrier
	s_add_i32 s64, 0, 0x18000
	s_add_i32 s65, 0, 0x1c000
	v_add_u32_e32 v174, s64, v131
	v_add_u32_e32 v190, s65, v131
	ds_read_b128 v[162:165], v174
	ds_read_b128 v[166:169], v174 offset:1024
	ds_read_b128 v[170:173], v174 offset:2048
	ds_read_b128 v[174:177], v174 offset:3072
	ds_read_b128 v[178:181], v190
	ds_read_b128 v[182:185], v190 offset:1024
	ds_read_b128 v[186:189], v190 offset:2048
	ds_read_b128 v[190:193], v190 offset:3072
	s_add_u32 s34, s34, 0x100000
	s_addc_u32 s35, s35, 0
	s_mov_b32 m0, s43
	v_lshl_add_u64 v[236:237], s[34:35], 0, v[134:135]
	ds_read_b128 v[196:199], v161 offset:32768
	ds_read_b128 v[200:203], v161 offset:33792
	ds_read_b128 v[206:209], v161 offset:34816
	ds_read_b128 v[210:213], v161 offset:35840
	ds_read_b128 v[214:217], v161 offset:36864
	ds_read_b128 v[218:221], v161 offset:37888
	ds_read_b128 v[222:225], v161 offset:38912
	ds_read_b128 v[226:229], v161 offset:39936
	global_load_lds_dwordx4 v[236:237], off
	v_lshl_add_u64 v[236:237], s[34:35], 0, v[132:133]
	s_mov_b32 m0, s45
	s_nop 0
	global_load_lds_dwordx4 v[236:237], off
	s_waitcnt vmcnt(8)
	s_waitcnt lgkmcnt(0)
	s_barrier
	v_mfma_f32_16x16x32_bf16 v[126:129], v[162:165], v[196:199], v[126:129]
	v_mfma_f32_16x16x32_bf16 v[122:125], v[170:173], v[196:199], v[122:125]
	v_mfma_f32_16x16x32_bf16 v[118:121], v[162:165], v[206:209], v[118:121]
	v_mfma_f32_16x16x32_bf16 v[114:117], v[170:173], v[206:209], v[114:117]
	v_mfma_f32_16x16x32_bf16 v[102:105], v[162:165], v[214:217], v[102:105]
	v_mfma_f32_16x16x32_bf16 v[98:101], v[170:173], v[214:217], v[98:101]
	v_mfma_f32_16x16x32_bf16 v[42:45], v[162:165], v[222:225], v[42:45]
	v_mfma_f32_16x16x32_bf16 v[34:37], v[170:173], v[222:225], v[34:37]
	v_mfma_f32_16x16x32_bf16 v[126:129], v[166:169], v[200:203], v[126:129]
	v_mfma_f32_16x16x32_bf16 v[122:125], v[174:177], v[200:203], v[122:125]
	v_mfma_f32_16x16x32_bf16 v[118:121], v[166:169], v[210:213], v[118:121]
	v_mfma_f32_16x16x32_bf16 v[114:117], v[174:177], v[210:213], v[114:117]
	v_mfma_f32_16x16x32_bf16 v[102:105], v[166:169], v[218:221], v[102:105]
	v_mfma_f32_16x16x32_bf16 v[98:101], v[174:177], v[218:221], v[98:101]
	v_mfma_f32_16x16x32_bf16 v[42:45], v[166:169], v[226:229], v[42:45]
	v_mfma_f32_16x16x32_bf16 v[34:37], v[174:177], v[226:229], v[34:37]
	v_mfma_f32_16x16x32_bf16 v[110:113], v[178:181], v[196:199], v[110:113]
	v_mfma_f32_16x16x32_bf16 v[106:109], v[186:189], v[196:199], v[106:109]
	v_mfma_f32_16x16x32_bf16 v[94:97], v[178:181], v[206:209], v[94:97]
	v_mfma_f32_16x16x32_bf16 v[90:93], v[186:189], v[206:209], v[90:93]
	v_mfma_f32_16x16x32_bf16 v[86:89], v[178:181], v[214:217], v[86:89]
	v_mfma_f32_16x16x32_bf16 v[82:85], v[186:189], v[214:217], v[82:85]
	v_mfma_f32_16x16x32_bf16 v[30:33], v[178:181], v[222:225], v[30:33]
	v_mfma_f32_16x16x32_bf16 v[26:29], v[186:189], v[222:225], v[26:29]
	v_mfma_f32_16x16x32_bf16 v[110:113], v[182:185], v[200:203], v[110:113]
	v_mfma_f32_16x16x32_bf16 v[106:109], v[190:193], v[200:203], v[106:109]
	v_mfma_f32_16x16x32_bf16 v[94:97], v[182:185], v[210:213], v[94:97]
	v_mfma_f32_16x16x32_bf16 v[90:93], v[190:193], v[210:213], v[90:93]
	v_mfma_f32_16x16x32_bf16 v[86:89], v[182:185], v[218:221], v[86:89]
	v_mfma_f32_16x16x32_bf16 v[82:85], v[190:193], v[218:221], v[82:85]
	v_mfma_f32_16x16x32_bf16 v[30:33], v[182:185], v[226:229], v[30:33]
	v_mfma_f32_16x16x32_bf16 v[26:29], v[190:193], v[226:229], v[26:29]
	s_barrier
	s_add_i32 s34, s64, s40
	v_lshl_add_u64 v[158:159], v[158:159], 0, s[10:11]
	s_mov_b32 m0, s34
	ds_read_b128 v[196:199], v161 offset:49152
	ds_read_b128 v[200:203], v161 offset:50176
	ds_read_b128 v[206:209], v161 offset:51200
	ds_read_b128 v[210:213], v161 offset:52224
	ds_read_b128 v[214:217], v161 offset:53248
	ds_read_b128 v[218:221], v161 offset:54272
	ds_read_b128 v[222:225], v161 offset:55296
	ds_read_b128 v[226:229], v161 offset:56320
	global_load_lds_dwordx4 v[158:159], off
	s_add_i32 m0, s34, 0x2000
	s_add_u32 s30, s30, 0x100080
	v_lshl_add_u64 v[158:159], v[230:231], 0, s[10:11]
	s_addc_u32 s31, s31, 0
	s_add_i32 s34, s65, s40
	global_load_lds_dwordx4 v[158:159], off
	v_lshl_add_u64 v[158:159], s[30:31], 0, v[134:135]
	s_mov_b32 m0, s34
	s_nop 0
	global_load_lds_dwordx4 v[158:159], off
	v_lshl_add_u64 v[158:159], s[30:31], 0, v[132:133]
	s_add_i32 m0, s34, 0x2000
	s_nop 0
	global_load_lds_dwordx4 v[158:159], off
	v_lshl_add_u64 v[158:159], v[232:233], 0, s[10:11]
	s_mov_b32 m0, s50
	s_nop 0
	global_load_lds_dwordx4 v[158:159], off
	v_lshl_add_u64 v[158:159], v[234:235], 0, s[10:11]
	s_mov_b32 m0, s51
	s_nop 0
	global_load_lds_dwordx4 v[158:159], off
	s_nop 0
	s_waitcnt vmcnt(8)
	s_waitcnt lgkmcnt(0)
	s_barrier
	v_mfma_f32_16x16x32_bf16 v[78:81], v[162:165], v[196:199], v[78:81]
	v_mfma_f32_16x16x32_bf16 v[74:77], v[170:173], v[196:199], v[74:77]
	v_mfma_f32_16x16x32_bf16 v[70:73], v[162:165], v[206:209], v[70:73]
	v_mfma_f32_16x16x32_bf16 v[66:69], v[170:173], v[206:209], v[66:69]
	v_mfma_f32_16x16x32_bf16 v[54:57], v[162:165], v[214:217], v[54:57]
	v_mfma_f32_16x16x32_bf16 v[50:53], v[170:173], v[214:217], v[50:53]
	v_mfma_f32_16x16x32_bf16 v[14:17], v[162:165], v[222:225], v[14:17]
	v_mfma_f32_16x16x32_bf16 v[10:13], v[170:173], v[222:225], v[10:13]
	v_mfma_f32_16x16x32_bf16 v[78:81], v[166:169], v[200:203], v[78:81]
	v_mfma_f32_16x16x32_bf16 v[74:77], v[174:177], v[200:203], v[74:77]
	v_mfma_f32_16x16x32_bf16 v[70:73], v[166:169], v[210:213], v[70:73]
	v_mfma_f32_16x16x32_bf16 v[66:69], v[174:177], v[210:213], v[66:69]
	v_mfma_f32_16x16x32_bf16 v[54:57], v[166:169], v[218:221], v[54:57]
	v_mfma_f32_16x16x32_bf16 v[50:53], v[174:177], v[218:221], v[50:53]
	v_mfma_f32_16x16x32_bf16 v[14:17], v[166:169], v[226:229], v[14:17]
	v_mfma_f32_16x16x32_bf16 v[10:13], v[174:177], v[226:229], v[10:13]
	v_mfma_f32_16x16x32_bf16 v[62:65], v[178:181], v[196:199], v[62:65]
	v_mfma_f32_16x16x32_bf16 v[58:61], v[186:189], v[196:199], v[58:61]
	v_mfma_f32_16x16x32_bf16 v[46:49], v[178:181], v[206:209], v[46:49]
	v_mfma_f32_16x16x32_bf16 v[38:41], v[186:189], v[206:209], v[38:41]
	v_mfma_f32_16x16x32_bf16 v[22:25], v[178:181], v[214:217], v[22:25]
	v_mfma_f32_16x16x32_bf16 v[18:21], v[186:189], v[214:217], v[18:21]
	v_mfma_f32_16x16x32_bf16 v[6:9], v[178:181], v[222:225], v[6:9]
	v_mfma_f32_16x16x32_bf16 v[2:5], v[186:189], v[222:225], v[2:5]
	v_mfma_f32_16x16x32_bf16 v[62:65], v[182:185], v[200:203], v[62:65]
	v_mfma_f32_16x16x32_bf16 v[58:61], v[190:193], v[200:203], v[58:61]
	v_mfma_f32_16x16x32_bf16 v[46:49], v[182:185], v[210:213], v[46:49]
	v_mfma_f32_16x16x32_bf16 v[38:41], v[190:193], v[210:213], v[38:41]
	v_mfma_f32_16x16x32_bf16 v[22:25], v[182:185], v[218:221], v[22:25]
	v_mfma_f32_16x16x32_bf16 v[18:21], v[190:193], v[218:221], v[18:21]
	v_mfma_f32_16x16x32_bf16 v[6:9], v[182:185], v[226:229], v[6:9]
	v_mfma_f32_16x16x32_bf16 v[2:5], v[190:193], v[226:229], v[2:5]
	s_barrier
	s_add_u32 s28, s28, 0x100
	s_addc_u32 s29, s29, 0
	s_add_u32 s61, s61, 0x100
	s_addc_u32 s62, s62, 0
	s_cmp_ge_i32 s63, s58
	s_mov_b32 s30, s63
	s_cbranch_scc0 .LBB0_3789
	s_and_b64 vcc, exec, s[16:17]
	s_cbranch_vccz .LBB0_3792
	s_barrier

.LBB0_3983:
	ds_read_b128 v[152:155], v160
	ds_read_b128 v[164:167], v160 offset:1024
	ds_read_b128 v[168:171], v160 offset:2048
	ds_read_b128 v[172:175], v160 offset:3072
	ds_read_b128 v[176:179], v161
	ds_read_b128 v[180:183], v161 offset:1024
	ds_read_b128 v[184:187], v161 offset:2048
	ds_read_b128 v[188:191], v161 offset:3072
	s_add_i32 s80, s48, 2
	s_add_u32 s49, s58, 0xfffe0080
	s_addc_u32 s60, s59, -1
	s_cmp_eq_u32 s43, s48
	s_cselect_b32 s48, s52, s47
	s_cselect_b32 s61, s5, s60
	s_cselect_b32 s60, s4, s49
	s_cselect_b32 s49, s53, s51
	v_lshl_add_u64 v[156:157], s[58:59], 0, v[140:141]
	s_add_i32 m0, s55, 0xc000
	ds_read_b128 v[196:199], v162
	ds_read_b128 v[200:203], v162 offset:1024
	ds_read_b128 v[204:207], v162 offset:2048
	ds_read_b128 v[208:211], v162 offset:3072
	ds_read_b128 v[212:215], v162 offset:4096
	ds_read_b128 v[216:219], v162 offset:5120
	ds_read_b128 v[220:223], v162 offset:6144
	ds_read_b128 v[224:227], v162 offset:7168
	global_load_lds_dwordx4 v[156:157], off
	v_lshl_add_u64 v[156:157], s[58:59], 0, v[142:143]
	s_add_i32 m0, s55, 0xe000
	s_nop 0
	global_load_lds_dwordx4 v[156:157], off
	s_waitcnt vmcnt(8)
	s_waitcnt lgkmcnt(0)
	s_barrier
	v_mfma_f32_16x16x32_bf16 v[126:129], v[152:155], v[196:199], v[126:129]
	v_mfma_f32_16x16x32_bf16 v[122:125], v[168:171], v[196:199], v[122:125]
	v_mfma_f32_16x16x32_bf16 v[110:113], v[152:155], v[204:207], v[110:113]
	v_mfma_f32_16x16x32_bf16 v[106:109], v[168:171], v[204:207], v[106:109]
	v_mfma_f32_16x16x32_bf16 v[94:97], v[152:155], v[212:215], v[94:97]
	v_mfma_f32_16x16x32_bf16 v[90:93], v[168:171], v[212:215], v[90:93]
	v_mfma_f32_16x16x32_bf16 v[78:81], v[152:155], v[220:223], v[78:81]
	v_mfma_f32_16x16x32_bf16 v[74:77], v[168:171], v[220:223], v[74:77]
	v_mfma_f32_16x16x32_bf16 v[126:129], v[164:167], v[200:203], v[126:129]
	v_mfma_f32_16x16x32_bf16 v[122:125], v[172:175], v[200:203], v[122:125]
	v_mfma_f32_16x16x32_bf16 v[110:113], v[164:167], v[208:211], v[110:113]
	v_mfma_f32_16x16x32_bf16 v[106:109], v[172:175], v[208:211], v[106:109]
	v_mfma_f32_16x16x32_bf16 v[94:97], v[164:167], v[216:219], v[94:97]
	v_mfma_f32_16x16x32_bf16 v[90:93], v[172:175], v[216:219], v[90:93]
	v_mfma_f32_16x16x32_bf16 v[78:81], v[164:167], v[224:227], v[78:81]
	v_mfma_f32_16x16x32_bf16 v[74:77], v[172:175], v[224:227], v[74:77]
	v_mfma_f32_16x16x32_bf16 v[118:121], v[176:179], v[196:199], v[118:121]
	v_mfma_f32_16x16x32_bf16 v[114:117], v[184:187], v[196:199], v[114:117]
	v_mfma_f32_16x16x32_bf16 v[102:105], v[176:179], v[204:207], v[102:105]
	v_mfma_f32_16x16x32_bf16 v[98:101], v[184:187], v[204:207], v[98:101]
	v_mfma_f32_16x16x32_bf16 v[86:89], v[176:179], v[212:215], v[86:89]
	v_mfma_f32_16x16x32_bf16 v[82:85], v[184:187], v[212:215], v[82:85]
	v_mfma_f32_16x16x32_bf16 v[70:73], v[176:179], v[220:223], v[70:73]
	v_mfma_f32_16x16x32_bf16 v[66:69], v[184:187], v[220:223], v[66:69]
	v_mfma_f32_16x16x32_bf16 v[118:121], v[180:183], v[200:203], v[118:121]
	v_mfma_f32_16x16x32_bf16 v[114:117], v[188:191], v[200:203], v[114:117]
	v_mfma_f32_16x16x32_bf16 v[102:105], v[180:183], v[208:211], v[102:105]
	v_mfma_f32_16x16x32_bf16 v[98:101], v[188:191], v[208:211], v[98:101]
	v_mfma_f32_16x16x32_bf16 v[86:89], v[180:183], v[216:219], v[86:89]
	v_mfma_f32_16x16x32_bf16 v[82:85], v[188:191], v[216:219], v[82:85]
	v_mfma_f32_16x16x32_bf16 v[70:73], v[180:183], v[224:227], v[70:73]
	v_mfma_f32_16x16x32_bf16 v[66:69], v[188:191], v[224:227], v[66:69]
	s_barrier
	s_add_i32 s81, s71, s62
	v_lshl_add_u64 v[156:157], s[48:49], 0, v[134:135]
	s_mov_b32 m0, s81
	ds_read_b128 v[196:199], v162 offset:16384
	ds_read_b128 v[200:203], v162 offset:17408
	ds_read_b128 v[204:207], v162 offset:18432
	ds_read_b128 v[208:211], v162 offset:19456
	ds_read_b128 v[212:215], v162 offset:20480
	ds_read_b128 v[216:219], v162 offset:21504
	ds_read_b128 v[220:223], v162 offset:22528
	ds_read_b128 v[224:227], v162 offset:23552
	global_load_lds_dwordx4 v[156:157], off
	s_add_i32 m0, s81, 0x2000
	s_add_u32 s82, s48, 0x20000
	v_lshl_add_u64 v[192:193], s[48:49], 0, v[138:139]
	s_addc_u32 s83, s49, 0
	s_add_i32 s81, s72, s62
	global_load_lds_dwordx4 v[192:193], off
	v_lshl_add_u64 v[228:229], s[82:83], 0, v[134:135]
	s_mov_b32 m0, s81
	v_lshl_add_u64 v[230:231], s[60:61], 0, v[136:137]
	global_load_lds_dwordx4 v[228:229], off
	v_lshl_add_u64 v[228:229], s[82:83], 0, v[138:139]
	s_add_i32 m0, s81, 0x2000
	s_nop 0
	global_load_lds_dwordx4 v[228:229], off
	v_lshl_add_u64 v[228:229], s[60:61], 0, v[132:133]
	s_mov_b32 m0, s55
	s_nop 0
	global_load_lds_dwordx4 v[228:229], off
	s_mov_b32 m0, s57
	s_nop 0
	global_load_lds_dwordx4 v[230:231], off
	s_waitcnt vmcnt(8)
	s_waitcnt lgkmcnt(0)
	s_barrier
	v_mfma_f32_16x16x32_bf16 v[62:65], v[152:155], v[196:199], v[62:65]
	v_mfma_f32_16x16x32_bf16 v[58:61], v[168:171], v[196:199], v[58:61]
	v_mfma_f32_16x16x32_bf16 v[46:49], v[152:155], v[204:207], v[46:49]
	v_mfma_f32_16x16x32_bf16 v[42:45], v[168:171], v[204:207], v[42:45]
	v_mfma_f32_16x16x32_bf16 v[30:33], v[152:155], v[212:215], v[30:33]
	v_mfma_f32_16x16x32_bf16 v[26:29], v[168:171], v[212:215], v[26:29]
	v_mfma_f32_16x16x32_bf16 v[14:17], v[152:155], v[220:223], v[14:17]
	v_mfma_f32_16x16x32_bf16 v[10:13], v[168:171], v[220:223], v[10:13]
	v_mfma_f32_16x16x32_bf16 v[62:65], v[164:167], v[200:203], v[62:65]
	v_mfma_f32_16x16x32_bf16 v[58:61], v[172:175], v[200:203], v[58:61]
	v_mfma_f32_16x16x32_bf16 v[46:49], v[164:167], v[208:211], v[46:49]
	v_mfma_f32_16x16x32_bf16 v[42:45], v[172:175], v[208:211], v[42:45]
	v_mfma_f32_16x16x32_bf16 v[30:33], v[164:167], v[216:219], v[30:33]
	v_mfma_f32_16x16x32_bf16 v[26:29], v[172:175], v[216:219], v[26:29]
	v_mfma_f32_16x16x32_bf16 v[14:17], v[164:167], v[224:227], v[14:17]
	v_mfma_f32_16x16x32_bf16 v[10:13], v[172:175], v[224:227], v[10:13]
	v_mfma_f32_16x16x32_bf16 v[54:57], v[176:179], v[196:199], v[54:57]
	v_mfma_f32_16x16x32_bf16 v[50:53], v[184:187], v[196:199], v[50:53]
	v_mfma_f32_16x16x32_bf16 v[38:41], v[176:179], v[204:207], v[38:41]
	v_mfma_f32_16x16x32_bf16 v[34:37], v[184:187], v[204:207], v[34:37]
	v_mfma_f32_16x16x32_bf16 v[22:25], v[176:179], v[212:215], v[22:25]
	v_mfma_f32_16x16x32_bf16 v[18:21], v[184:187], v[212:215], v[18:21]
	v_mfma_f32_16x16x32_bf16 v[6:9], v[176:179], v[220:223], v[6:9]
	v_mfma_f32_16x16x32_bf16 v[2:5], v[184:187], v[220:223], v[2:5]
	v_mfma_f32_16x16x32_bf16 v[54:57], v[180:183], v[200:203], v[54:57]
	v_mfma_f32_16x16x32_bf16 v[50:53], v[188:191], v[200:203], v[50:53]
	v_mfma_f32_16x16x32_bf16 v[38:41], v[180:183], v[208:211], v[38:41]
	v_mfma_f32_16x16x32_bf16 v[34:37], v[188:191], v[208:211], v[34:37]
	v_mfma_f32_16x16x32_bf16 v[22:25], v[180:183], v[216:219], v[22:25]
	v_mfma_f32_16x16x32_bf16 v[18:21], v[188:191], v[216:219], v[18:21]
	v_mfma_f32_16x16x32_bf16 v[6:9], v[180:183], v[224:227], v[6:9]
	v_mfma_f32_16x16x32_bf16 v[2:5], v[188:191], v[224:227], v[2:5]
	s_barrier
	s_add_i32 s81, 0, 0x18000
	v_add_u32_e32 v163, s81, v158
	s_add_i32 s82, 0, 0x1c000
	ds_read_b128 v[152:155], v163
	ds_read_b128 v[164:167], v163 offset:1024
	ds_read_b128 v[168:171], v163 offset:2048
	ds_read_b128 v[172:175], v163 offset:3072
	v_add_u32_e32 v163, s82, v158
	ds_read_b128 v[176:179], v163
	ds_read_b128 v[180:183], v163 offset:1024
	ds_read_b128 v[184:187], v163 offset:2048
	ds_read_b128 v[188:191], v163 offset:3072
	s_add_u32 s60, s60, 0x20000
	s_addc_u32 s61, s61, 0
	s_mov_b32 m0, s63
	v_lshl_add_u64 v[232:233], s[60:61], 0, v[132:133]
	ds_read_b128 v[196:199], v162 offset:32768
	ds_read_b128 v[200:203], v162 offset:33792
	ds_read_b128 v[204:207], v162 offset:34816
	ds_read_b128 v[208:211], v162 offset:35840
	ds_read_b128 v[212:215], v162 offset:36864
	ds_read_b128 v[216:219], v162 offset:37888
	ds_read_b128 v[220:223], v162 offset:38912
	ds_read_b128 v[224:227], v162 offset:39936
	global_load_lds_dwordx4 v[232:233], off
	v_lshl_add_u64 v[232:233], s[60:61], 0, v[136:137]
	s_mov_b32 m0, s64
	s_nop 0
	global_load_lds_dwordx4 v[232:233], off
	s_waitcnt vmcnt(8)
	s_waitcnt lgkmcnt(0)
	s_barrier
	v_mfma_f32_16x16x32_bf16 v[126:129], v[152:155], v[196:199], v[126:129]
	v_mfma_f32_16x16x32_bf16 v[122:125], v[168:171], v[196:199], v[122:125]
	v_mfma_f32_16x16x32_bf16 v[110:113], v[152:155], v[204:207], v[110:113]
	v_mfma_f32_16x16x32_bf16 v[106:109], v[168:171], v[204:207], v[106:109]
	v_mfma_f32_16x16x32_bf16 v[94:97], v[152:155], v[212:215], v[94:97]
	v_mfma_f32_16x16x32_bf16 v[90:93], v[168:171], v[212:215], v[90:93]
	v_mfma_f32_16x16x32_bf16 v[78:81], v[152:155], v[220:223], v[78:81]
	v_mfma_f32_16x16x32_bf16 v[74:77], v[168:171], v[220:223], v[74:77]
	v_mfma_f32_16x16x32_bf16 v[126:129], v[164:167], v[200:203], v[126:129]
	v_mfma_f32_16x16x32_bf16 v[122:125], v[172:175], v[200:203], v[122:125]
	v_mfma_f32_16x16x32_bf16 v[110:113], v[164:167], v[208:211], v[110:113]
	v_mfma_f32_16x16x32_bf16 v[106:109], v[172:175], v[208:211], v[106:109]
	v_mfma_f32_16x16x32_bf16 v[94:97], v[164:167], v[216:219], v[94:97]
	v_mfma_f32_16x16x32_bf16 v[90:93], v[172:175], v[216:219], v[90:93]
	v_mfma_f32_16x16x32_bf16 v[78:81], v[164:167], v[224:227], v[78:81]
	v_mfma_f32_16x16x32_bf16 v[74:77], v[172:175], v[224:227], v[74:77]
	v_mfma_f32_16x16x32_bf16 v[118:121], v[176:179], v[196:199], v[118:121]
	v_mfma_f32_16x16x32_bf16 v[114:117], v[184:187], v[196:199], v[114:117]
	v_mfma_f32_16x16x32_bf16 v[102:105], v[176:179], v[204:207], v[102:105]
	v_mfma_f32_16x16x32_bf16 v[98:101], v[184:187], v[204:207], v[98:101]
	v_mfma_f32_16x16x32_bf16 v[86:89], v[176:179], v[212:215], v[86:89]
	v_mfma_f32_16x16x32_bf16 v[82:85], v[184:187], v[212:215], v[82:85]
	v_mfma_f32_16x16x32_bf16 v[70:73], v[176:179], v[220:223], v[70:73]
	v_mfma_f32_16x16x32_bf16 v[66:69], v[184:187], v[220:223], v[66:69]
	v_mfma_f32_16x16x32_bf16 v[118:121], v[180:183], v[200:203], v[118:121]
	v_mfma_f32_16x16x32_bf16 v[114:117], v[188:191], v[200:203], v[114:117]
	v_mfma_f32_16x16x32_bf16 v[102:105], v[180:183], v[208:211], v[102:105]
	v_mfma_f32_16x16x32_bf16 v[98:101], v[188:191], v[208:211], v[98:101]
	v_mfma_f32_16x16x32_bf16 v[86:89], v[180:183], v[216:219], v[86:89]
	v_mfma_f32_16x16x32_bf16 v[82:85], v[188:191], v[216:219], v[82:85]
	v_mfma_f32_16x16x32_bf16 v[70:73], v[180:183], v[224:227], v[70:73]
	v_mfma_f32_16x16x32_bf16 v[66:69], v[188:191], v[224:227], v[66:69]
	s_barrier
	s_add_i32 s60, s81, s62
	v_lshl_add_u64 v[156:157], v[156:157], 0, s[14:15]
	s_mov_b32 m0, s60
	ds_read_b128 v[196:199], v162 offset:49152
	ds_read_b128 v[200:203], v162 offset:50176
	ds_read_b128 v[204:207], v162 offset:51200
	ds_read_b128 v[208:211], v162 offset:52224
	ds_read_b128 v[212:215], v162 offset:53248
	ds_read_b128 v[216:219], v162 offset:54272
	ds_read_b128 v[220:223], v162 offset:55296
	ds_read_b128 v[224:227], v162 offset:56320
	global_load_lds_dwordx4 v[156:157], off
	s_add_i32 m0, s60, 0x2000
	s_add_u32 s48, s48, 0x20080
	v_lshl_add_u64 v[156:157], v[192:193], 0, s[14:15]
	s_addc_u32 s49, s49, 0
	s_add_i32 s60, s82, s62
	global_load_lds_dwordx4 v[156:157], off
	v_lshl_add_u64 v[156:157], s[48:49], 0, v[134:135]
	s_mov_b32 m0, s60
	s_nop 0
	global_load_lds_dwordx4 v[156:157], off
	v_lshl_add_u64 v[156:157], s[48:49], 0, v[138:139]
	s_add_i32 m0, s60, 0x2000
	s_nop 0
	global_load_lds_dwordx4 v[156:157], off
	v_lshl_add_u64 v[156:157], v[228:229], 0, s[14:15]
	s_mov_b32 m0, s68
	s_nop 0
	global_load_lds_dwordx4 v[156:157], off
	v_lshl_add_u64 v[156:157], v[230:231], 0, s[14:15]
	s_mov_b32 m0, s69
	s_nop 0
	global_load_lds_dwordx4 v[156:157], off
	s_nop 0
	s_waitcnt vmcnt(8)
	s_waitcnt lgkmcnt(0)
	s_barrier
	v_mfma_f32_16x16x32_bf16 v[62:65], v[152:155], v[196:199], v[62:65]
	v_mfma_f32_16x16x32_bf16 v[58:61], v[168:171], v[196:199], v[58:61]
	v_mfma_f32_16x16x32_bf16 v[46:49], v[152:155], v[204:207], v[46:49]
	v_mfma_f32_16x16x32_bf16 v[42:45], v[168:171], v[204:207], v[42:45]
	v_mfma_f32_16x16x32_bf16 v[30:33], v[152:155], v[212:215], v[30:33]
	v_mfma_f32_16x16x32_bf16 v[26:29], v[168:171], v[212:215], v[26:29]
	v_mfma_f32_16x16x32_bf16 v[14:17], v[152:155], v[220:223], v[14:17]
	v_mfma_f32_16x16x32_bf16 v[10:13], v[168:171], v[220:223], v[10:13]
	v_mfma_f32_16x16x32_bf16 v[62:65], v[164:167], v[200:203], v[62:65]
	v_mfma_f32_16x16x32_bf16 v[58:61], v[172:175], v[200:203], v[58:61]
	v_mfma_f32_16x16x32_bf16 v[46:49], v[164:167], v[208:211], v[46:49]
	v_mfma_f32_16x16x32_bf16 v[42:45], v[172:175], v[208:211], v[42:45]
	v_mfma_f32_16x16x32_bf16 v[30:33], v[164:167], v[216:219], v[30:33]
	v_mfma_f32_16x16x32_bf16 v[26:29], v[172:175], v[216:219], v[26:29]
	v_mfma_f32_16x16x32_bf16 v[14:17], v[164:167], v[224:227], v[14:17]
	v_mfma_f32_16x16x32_bf16 v[10:13], v[172:175], v[224:227], v[10:13]
	v_mfma_f32_16x16x32_bf16 v[54:57], v[176:179], v[196:199], v[54:57]
	v_mfma_f32_16x16x32_bf16 v[50:53], v[184:187], v[196:199], v[50:53]
	v_mfma_f32_16x16x32_bf16 v[38:41], v[176:179], v[204:207], v[38:41]
	v_mfma_f32_16x16x32_bf16 v[34:37], v[184:187], v[204:207], v[34:37]
	v_mfma_f32_16x16x32_bf16 v[22:25], v[176:179], v[212:215], v[22:25]
	v_mfma_f32_16x16x32_bf16 v[18:21], v[184:187], v[212:215], v[18:21]
	v_mfma_f32_16x16x32_bf16 v[6:9], v[176:179], v[220:223], v[6:9]
	v_mfma_f32_16x16x32_bf16 v[2:5], v[184:187], v[220:223], v[2:5]
	v_mfma_f32_16x16x32_bf16 v[54:57], v[180:183], v[200:203], v[54:57]
	v_mfma_f32_16x16x32_bf16 v[50:53], v[188:191], v[200:203], v[50:53]
	v_mfma_f32_16x16x32_bf16 v[38:41], v[180:183], v[208:211], v[38:41]
	v_mfma_f32_16x16x32_bf16 v[34:37], v[188:191], v[208:211], v[34:37]
	v_mfma_f32_16x16x32_bf16 v[22:25], v[180:183], v[216:219], v[22:25]
	v_mfma_f32_16x16x32_bf16 v[18:21], v[188:191], v[216:219], v[18:21]
	v_mfma_f32_16x16x32_bf16 v[6:9], v[180:183], v[224:227], v[6:9]
	v_mfma_f32_16x16x32_bf16 v[2:5], v[188:191], v[224:227], v[2:5]
	s_barrier
	s_add_u32 s58, s58, 0x100
	s_addc_u32 s59, s59, 0
	s_add_u32 s47, s47, 0x100
	s_addc_u32 s51, s51, 0
	s_cmp_ge_i32 s80, s79
	s_mov_b32 s48, s80
	s_cbranch_scc0 .LBB0_3983
	s_and_b64 vcc, exec, s[16:17]
	s_cbranch_vccz .LBB0_3986
	s_barrier

.LBB0_4145:
	ds_read_b128 v[156:159], v162
	ds_read_b128 v[166:169], v162 offset:1024
	ds_read_b128 v[170:173], v162 offset:2048
	ds_read_b128 v[174:177], v162 offset:3072
	ds_read_b128 v[178:181], v163
	ds_read_b128 v[182:185], v163 offset:1024
	ds_read_b128 v[186:189], v163 offset:2048
	ds_read_b128 v[190:193], v163 offset:3072
	s_add_i32 s72, s42, 2
	s_add_u32 s43, s40, 0xfff00080
	s_addc_u32 s46, s41, -1
	s_cmp_eq_u32 s69, s42
	s_cselect_b32 s42, s25, s70
	s_cselect_b32 s47, s5, s46
	s_cselect_b32 s46, s23, s43
	s_cselect_b32 s43, s21, s71
	v_lshl_add_u64 v[228:229], s[40:41], 0, v[148:149]
	s_add_i32 m0, s35, 0xc000
	ds_read_b128 v[196:199], v164
	ds_read_b128 v[200:203], v164 offset:1024
	ds_read_b128 v[204:207], v164 offset:2048
	ds_read_b128 v[208:211], v164 offset:3072
	ds_read_b128 v[212:215], v164 offset:4096
	ds_read_b128 v[216:219], v164 offset:5120
	ds_read_b128 v[220:223], v164 offset:6144
	ds_read_b128 v[224:227], v164 offset:7168
	global_load_lds_dwordx4 v[228:229], off
	v_lshl_add_u64 v[228:229], s[40:41], 0, v[150:151]
	s_add_i32 m0, s35, 0xe000
	s_nop 0
	global_load_lds_dwordx4 v[228:229], off
	s_nop 0
	s_waitcnt vmcnt(8)
	s_waitcnt lgkmcnt(0)
	s_barrier
	v_mfma_f32_16x16x32_bf16 v[78:81], v[156:159], v[196:199], v[78:81]
	v_mfma_f32_16x16x32_bf16 v[74:77], v[170:173], v[196:199], v[74:77]
	v_mfma_f32_16x16x32_bf16 v[70:73], v[156:159], v[204:207], v[70:73]
	v_mfma_f32_16x16x32_bf16 v[62:65], v[170:173], v[204:207], v[62:65]
	v_mfma_f32_16x16x32_bf16 v[58:61], v[156:159], v[212:215], v[58:61]
	v_mfma_f32_16x16x32_bf16 v[54:57], v[170:173], v[212:215], v[54:57]
	v_mfma_f32_16x16x32_bf16 v[46:49], v[156:159], v[220:223], v[46:49]
	v_mfma_f32_16x16x32_bf16 v[38:41], v[170:173], v[220:223], v[38:41]
	v_mfma_f32_16x16x32_bf16 v[78:81], v[166:169], v[200:203], v[78:81]
	v_mfma_f32_16x16x32_bf16 v[74:77], v[174:177], v[200:203], v[74:77]
	v_mfma_f32_16x16x32_bf16 v[70:73], v[166:169], v[208:211], v[70:73]
	v_mfma_f32_16x16x32_bf16 v[62:65], v[174:177], v[208:211], v[62:65]
	v_mfma_f32_16x16x32_bf16 v[58:61], v[166:169], v[216:219], v[58:61]
	v_mfma_f32_16x16x32_bf16 v[54:57], v[174:177], v[216:219], v[54:57]
	v_mfma_f32_16x16x32_bf16 v[46:49], v[166:169], v[224:227], v[46:49]
	v_mfma_f32_16x16x32_bf16 v[38:41], v[174:177], v[224:227], v[38:41]
	v_mfma_f32_16x16x32_bf16 v[50:53], v[178:181], v[196:199], v[50:53]
	v_mfma_f32_16x16x32_bf16 v[42:45], v[186:189], v[196:199], v[42:45]
	v_mfma_f32_16x16x32_bf16 v[34:37], v[178:181], v[204:207], v[34:37]
	v_mfma_f32_16x16x32_bf16 v[26:29], v[186:189], v[204:207], v[26:29]
	v_mfma_f32_16x16x32_bf16 v[18:21], v[178:181], v[212:215], v[18:21]
	v_mfma_f32_16x16x32_bf16 v[14:17], v[186:189], v[212:215], v[14:17]
	v_mfma_f32_16x16x32_bf16 v[10:13], v[178:181], v[220:223], v[10:13]
	v_mfma_f32_16x16x32_bf16 v[6:9], v[186:189], v[220:223], v[6:9]
	v_mfma_f32_16x16x32_bf16 v[50:53], v[182:185], v[200:203], v[50:53]
	v_mfma_f32_16x16x32_bf16 v[42:45], v[190:193], v[200:203], v[42:45]
	v_mfma_f32_16x16x32_bf16 v[34:37], v[182:185], v[208:211], v[34:37]
	v_mfma_f32_16x16x32_bf16 v[26:29], v[190:193], v[208:211], v[26:29]
	v_mfma_f32_16x16x32_bf16 v[18:21], v[182:185], v[216:219], v[18:21]
	v_mfma_f32_16x16x32_bf16 v[14:17], v[190:193], v[216:219], v[14:17]
	v_mfma_f32_16x16x32_bf16 v[10:13], v[182:185], v[224:227], v[10:13]
	v_mfma_f32_16x16x32_bf16 v[6:9], v[190:193], v[224:227], v[6:9]
	s_barrier
	s_add_i32 s73, s62, s49
	v_lshl_add_u64 v[228:229], s[42:43], 0, v[134:135]
	s_mov_b32 m0, s73
	ds_read_b128 v[196:199], v164 offset:16384
	ds_read_b128 v[200:203], v164 offset:17408
	ds_read_b128 v[204:207], v164 offset:18432
	ds_read_b128 v[208:211], v164 offset:19456
	ds_read_b128 v[212:215], v164 offset:20480
	ds_read_b128 v[216:219], v164 offset:21504
	ds_read_b128 v[220:223], v164 offset:22528
	ds_read_b128 v[224:227], v164 offset:23552
	global_load_lds_dwordx4 v[228:229], off
	s_add_i32 m0, s73, 0x2000
	s_add_u32 s74, s42, 0x100000
	v_lshl_add_u64 v[230:231], s[42:43], 0, v[138:139]
	s_addc_u32 s75, s43, 0
	s_add_i32 s73, s63, s49
	global_load_lds_dwordx4 v[230:231], off
	v_lshl_add_u64 v[232:233], s[74:75], 0, v[134:135]
	s_mov_b32 m0, s73
	v_lshl_add_u64 v[234:235], s[46:47], 0, v[136:137]
	global_load_lds_dwordx4 v[232:233], off
	v_lshl_add_u64 v[232:233], s[74:75], 0, v[138:139]
	s_add_i32 m0, s73, 0x2000
	s_nop 0
	global_load_lds_dwordx4 v[232:233], off
	v_lshl_add_u64 v[232:233], s[46:47], 0, v[132:133]
	s_mov_b32 m0, s35
	s_nop 0
	global_load_lds_dwordx4 v[232:233], off
	s_mov_b32 m0, s50
	s_nop 0
	global_load_lds_dwordx4 v[234:235], off
	s_waitcnt vmcnt(8)
	s_waitcnt lgkmcnt(0)
	s_barrier
	v_mfma_f32_16x16x32_bf16 v[126:129], v[156:159], v[196:199], v[126:129]
	v_mfma_f32_16x16x32_bf16 v[118:121], v[170:173], v[196:199], v[118:121]
	v_mfma_f32_16x16x32_bf16 v[110:113], v[156:159], v[204:207], v[110:113]
	v_mfma_f32_16x16x32_bf16 v[102:105], v[170:173], v[204:207], v[102:105]
	v_mfma_f32_16x16x32_bf16 v[94:97], v[156:159], v[212:215], v[94:97]
	v_mfma_f32_16x16x32_bf16 v[86:89], v[170:173], v[212:215], v[86:89]
	v_mfma_f32_16x16x32_bf16 v[66:69], v[156:159], v[220:223], v[66:69]
	v_mfma_f32_16x16x32_bf16 v[22:25], v[170:173], v[220:223], v[22:25]
	v_mfma_f32_16x16x32_bf16 v[126:129], v[166:169], v[200:203], v[126:129]
	v_mfma_f32_16x16x32_bf16 v[118:121], v[174:177], v[200:203], v[118:121]
	v_mfma_f32_16x16x32_bf16 v[110:113], v[166:169], v[208:211], v[110:113]
	v_mfma_f32_16x16x32_bf16 v[102:105], v[174:177], v[208:211], v[102:105]
	v_mfma_f32_16x16x32_bf16 v[94:97], v[166:169], v[216:219], v[94:97]
	v_mfma_f32_16x16x32_bf16 v[86:89], v[174:177], v[216:219], v[86:89]
	v_mfma_f32_16x16x32_bf16 v[66:69], v[166:169], v[224:227], v[66:69]
	v_mfma_f32_16x16x32_bf16 v[22:25], v[174:177], v[224:227], v[22:25]
	v_mfma_f32_16x16x32_bf16 v[122:125], v[178:181], v[196:199], v[122:125]
	v_mfma_f32_16x16x32_bf16 v[114:117], v[186:189], v[196:199], v[114:117]
	v_mfma_f32_16x16x32_bf16 v[106:109], v[178:181], v[204:207], v[106:109]
	v_mfma_f32_16x16x32_bf16 v[98:101], v[186:189], v[204:207], v[98:101]
	v_mfma_f32_16x16x32_bf16 v[90:93], v[178:181], v[212:215], v[90:93]
	v_mfma_f32_16x16x32_bf16 v[82:85], v[186:189], v[212:215], v[82:85]
	v_mfma_f32_16x16x32_bf16 v[30:33], v[178:181], v[220:223], v[30:33]
	v_mfma_f32_16x16x32_bf16 v[2:5], v[186:189], v[220:223], v[2:5]
	v_mfma_f32_16x16x32_bf16 v[122:125], v[182:185], v[200:203], v[122:125]
	v_mfma_f32_16x16x32_bf16 v[114:117], v[190:193], v[200:203], v[114:117]
	v_mfma_f32_16x16x32_bf16 v[106:109], v[182:185], v[208:211], v[106:109]
	v_mfma_f32_16x16x32_bf16 v[98:101], v[190:193], v[208:211], v[98:101]
	v_mfma_f32_16x16x32_bf16 v[90:93], v[182:185], v[216:219], v[90:93]
	v_mfma_f32_16x16x32_bf16 v[82:85], v[190:193], v[216:219], v[82:85]
	v_mfma_f32_16x16x32_bf16 v[30:33], v[182:185], v[224:227], v[30:33]
	v_mfma_f32_16x16x32_bf16 v[2:5], v[190:193], v[224:227], v[2:5]
	s_barrier
	s_add_i32 s73, 0, 0x18000
	v_add_u32_e32 v165, s73, v160
	s_add_i32 s74, 0, 0x1c000
	ds_read_b128 v[156:159], v165
	ds_read_b128 v[166:169], v165 offset:1024
	ds_read_b128 v[170:173], v165 offset:2048
	ds_read_b128 v[174:177], v165 offset:3072
	v_add_u32_e32 v165, s74, v160
	ds_read_b128 v[178:181], v165
	ds_read_b128 v[182:185], v165 offset:1024
	ds_read_b128 v[186:189], v165 offset:2048
	ds_read_b128 v[190:193], v165 offset:3072
	s_add_u32 s46, s46, 0x100000
	s_addc_u32 s47, s47, 0
	s_mov_b32 m0, s51
	v_lshl_add_u64 v[236:237], s[46:47], 0, v[132:133]
	ds_read_b128 v[196:199], v164 offset:32768
	ds_read_b128 v[200:203], v164 offset:33792
	ds_read_b128 v[204:207], v164 offset:34816
	ds_read_b128 v[208:211], v164 offset:35840
	ds_read_b128 v[212:215], v164 offset:36864
	ds_read_b128 v[216:219], v164 offset:37888
	ds_read_b128 v[220:223], v164 offset:38912
	ds_read_b128 v[224:227], v164 offset:39936
	global_load_lds_dwordx4 v[236:237], off
	v_lshl_add_u64 v[236:237], s[46:47], 0, v[136:137]
	s_mov_b32 m0, s52
	s_nop 0
	global_load_lds_dwordx4 v[236:237], off
	s_waitcnt vmcnt(8)
	s_waitcnt lgkmcnt(0)
	s_barrier
	v_mfma_f32_16x16x32_bf16 v[78:81], v[156:159], v[196:199], v[78:81]
	v_mfma_f32_16x16x32_bf16 v[74:77], v[170:173], v[196:199], v[74:77]
	v_mfma_f32_16x16x32_bf16 v[70:73], v[156:159], v[204:207], v[70:73]
	v_mfma_f32_16x16x32_bf16 v[62:65], v[170:173], v[204:207], v[62:65]
	v_mfma_f32_16x16x32_bf16 v[58:61], v[156:159], v[212:215], v[58:61]
	v_mfma_f32_16x16x32_bf16 v[54:57], v[170:173], v[212:215], v[54:57]
	v_mfma_f32_16x16x32_bf16 v[46:49], v[156:159], v[220:223], v[46:49]
	v_mfma_f32_16x16x32_bf16 v[38:41], v[170:173], v[220:223], v[38:41]
	v_mfma_f32_16x16x32_bf16 v[78:81], v[166:169], v[200:203], v[78:81]
	v_mfma_f32_16x16x32_bf16 v[74:77], v[174:177], v[200:203], v[74:77]
	v_mfma_f32_16x16x32_bf16 v[70:73], v[166:169], v[208:211], v[70:73]
	v_mfma_f32_16x16x32_bf16 v[62:65], v[174:177], v[208:211], v[62:65]
	v_mfma_f32_16x16x32_bf16 v[58:61], v[166:169], v[216:219], v[58:61]
	v_mfma_f32_16x16x32_bf16 v[54:57], v[174:177], v[216:219], v[54:57]
	v_mfma_f32_16x16x32_bf16 v[46:49], v[166:169], v[224:227], v[46:49]
	v_mfma_f32_16x16x32_bf16 v[38:41], v[174:177], v[224:227], v[38:41]
	v_mfma_f32_16x16x32_bf16 v[50:53], v[178:181], v[196:199], v[50:53]
	v_mfma_f32_16x16x32_bf16 v[42:45], v[186:189], v[196:199], v[42:45]
	v_mfma_f32_16x16x32_bf16 v[34:37], v[178:181], v[204:207], v[34:37]
	v_mfma_f32_16x16x32_bf16 v[26:29], v[186:189], v[204:207], v[26:29]
	v_mfma_f32_16x16x32_bf16 v[18:21], v[178:181], v[212:215], v[18:21]
	v_mfma_f32_16x16x32_bf16 v[14:17], v[186:189], v[212:215], v[14:17]
	v_mfma_f32_16x16x32_bf16 v[10:13], v[178:181], v[220:223], v[10:13]
	v_mfma_f32_16x16x32_bf16 v[6:9], v[186:189], v[220:223], v[6:9]
	v_mfma_f32_16x16x32_bf16 v[50:53], v[182:185], v[200:203], v[50:53]
	v_mfma_f32_16x16x32_bf16 v[42:45], v[190:193], v[200:203], v[42:45]
	v_mfma_f32_16x16x32_bf16 v[34:37], v[182:185], v[208:211], v[34:37]
	v_mfma_f32_16x16x32_bf16 v[26:29], v[190:193], v[208:211], v[26:29]
	v_mfma_f32_16x16x32_bf16 v[18:21], v[182:185], v[216:219], v[18:21]
	v_mfma_f32_16x16x32_bf16 v[14:17], v[190:193], v[216:219], v[14:17]
	v_mfma_f32_16x16x32_bf16 v[10:13], v[182:185], v[224:227], v[10:13]
	v_mfma_f32_16x16x32_bf16 v[6:9], v[190:193], v[224:227], v[6:9]
	s_barrier
	s_add_i32 s46, s73, s49
	v_lshl_add_u64 v[228:229], v[228:229], 0, s[10:11]
	s_mov_b32 m0, s46
	ds_read_b128 v[196:199], v164 offset:49152
	ds_read_b128 v[200:203], v164 offset:50176
	ds_read_b128 v[204:207], v164 offset:51200
	ds_read_b128 v[208:211], v164 offset:52224
	ds_read_b128 v[212:215], v164 offset:53248
	ds_read_b128 v[216:219], v164 offset:54272
	ds_read_b128 v[220:223], v164 offset:55296
	ds_read_b128 v[224:227], v164 offset:56320
	global_load_lds_dwordx4 v[228:229], off
	s_add_i32 m0, s46, 0x2000
	s_add_u32 s42, s42, 0x100080
	v_lshl_add_u64 v[228:229], v[230:231], 0, s[10:11]
	s_addc_u32 s43, s43, 0
	s_add_i32 s46, s74, s49
	global_load_lds_dwordx4 v[228:229], off
	v_lshl_add_u64 v[228:229], s[42:43], 0, v[134:135]
	s_mov_b32 m0, s46
	s_nop 0
	global_load_lds_dwordx4 v[228:229], off
	v_lshl_add_u64 v[228:229], s[42:43], 0, v[138:139]
	s_add_i32 m0, s46, 0x2000
	s_nop 0
	global_load_lds_dwordx4 v[228:229], off
	v_lshl_add_u64 v[228:229], v[232:233], 0, s[10:11]
	s_mov_b32 m0, s55
	s_nop 0
	global_load_lds_dwordx4 v[228:229], off
	v_lshl_add_u64 v[228:229], v[234:235], 0, s[10:11]
	s_mov_b32 m0, s56
	s_nop 0
	global_load_lds_dwordx4 v[228:229], off
	s_nop 0
	s_waitcnt vmcnt(8)
	s_waitcnt lgkmcnt(0)
	s_barrier
	v_mfma_f32_16x16x32_bf16 v[126:129], v[156:159], v[196:199], v[126:129]
	v_mfma_f32_16x16x32_bf16 v[118:121], v[170:173], v[196:199], v[118:121]
	v_mfma_f32_16x16x32_bf16 v[110:113], v[156:159], v[204:207], v[110:113]
	v_mfma_f32_16x16x32_bf16 v[102:105], v[170:173], v[204:207], v[102:105]
	v_mfma_f32_16x16x32_bf16 v[94:97], v[156:159], v[212:215], v[94:97]
	v_mfma_f32_16x16x32_bf16 v[86:89], v[170:173], v[212:215], v[86:89]
	v_mfma_f32_16x16x32_bf16 v[66:69], v[156:159], v[220:223], v[66:69]
	v_mfma_f32_16x16x32_bf16 v[22:25], v[170:173], v[220:223], v[22:25]
	v_mfma_f32_16x16x32_bf16 v[126:129], v[166:169], v[200:203], v[126:129]
	v_mfma_f32_16x16x32_bf16 v[118:121], v[174:177], v[200:203], v[118:121]
	v_mfma_f32_16x16x32_bf16 v[110:113], v[166:169], v[208:211], v[110:113]
	v_mfma_f32_16x16x32_bf16 v[102:105], v[174:177], v[208:211], v[102:105]
	v_mfma_f32_16x16x32_bf16 v[94:97], v[166:169], v[216:219], v[94:97]
	v_mfma_f32_16x16x32_bf16 v[86:89], v[174:177], v[216:219], v[86:89]
	v_mfma_f32_16x16x32_bf16 v[66:69], v[166:169], v[224:227], v[66:69]
	v_mfma_f32_16x16x32_bf16 v[22:25], v[174:177], v[224:227], v[22:25]
	v_mfma_f32_16x16x32_bf16 v[122:125], v[178:181], v[196:199], v[122:125]
	v_mfma_f32_16x16x32_bf16 v[114:117], v[186:189], v[196:199], v[114:117]
	v_mfma_f32_16x16x32_bf16 v[106:109], v[178:181], v[204:207], v[106:109]
	v_mfma_f32_16x16x32_bf16 v[98:101], v[186:189], v[204:207], v[98:101]
	v_mfma_f32_16x16x32_bf16 v[90:93], v[178:181], v[212:215], v[90:93]
	v_mfma_f32_16x16x32_bf16 v[82:85], v[186:189], v[212:215], v[82:85]
	v_mfma_f32_16x16x32_bf16 v[30:33], v[178:181], v[220:223], v[30:33]
	v_mfma_f32_16x16x32_bf16 v[2:5], v[186:189], v[220:223], v[2:5]
	v_mfma_f32_16x16x32_bf16 v[122:125], v[182:185], v[200:203], v[122:125]
	v_mfma_f32_16x16x32_bf16 v[114:117], v[190:193], v[200:203], v[114:117]
	v_mfma_f32_16x16x32_bf16 v[106:109], v[182:185], v[208:211], v[106:109]
	v_mfma_f32_16x16x32_bf16 v[98:101], v[190:193], v[208:211], v[98:101]
	v_mfma_f32_16x16x32_bf16 v[90:93], v[182:185], v[216:219], v[90:93]
	v_mfma_f32_16x16x32_bf16 v[82:85], v[190:193], v[216:219], v[82:85]
	v_mfma_f32_16x16x32_bf16 v[30:33], v[182:185], v[224:227], v[30:33]
	v_mfma_f32_16x16x32_bf16 v[2:5], v[190:193], v[224:227], v[2:5]
	s_barrier
	s_add_u32 s40, s40, 0x100
	s_addc_u32 s41, s41, 0
	s_add_u32 s70, s70, 0x100
	s_addc_u32 s71, s71, 0
	s_cmp_ge_i32 s72, s68
	s_mov_b32 s42, s72
	s_cbranch_scc0 .LBB0_4145
	s_and_b64 vcc, exec, s[12:13]
	s_cbranch_vccz .LBB0_4150
	s_barrier
	s_cmp_lt_i32 s48, 0
	s_mov_b64 s[40:41], -1
	s_cbranch_scc1 .LBB0_4151

.LBB0_4304:
	ds_read_b128 v[150:153], v158
	ds_read_b128 v[162:165], v158 offset:1024
	ds_read_b128 v[166:169], v158 offset:2048
	ds_read_b128 v[170:173], v158 offset:3072
	ds_read_b128 v[174:177], v159
	ds_read_b128 v[178:181], v159 offset:1024
	ds_read_b128 v[182:185], v159 offset:2048
	ds_read_b128 v[186:189], v159 offset:3072
	s_add_i32 s80, s48, 2
	s_add_u32 s49, s50, 0xffd50080
	s_addc_u32 s52, s51, -1
	s_cmp_eq_u32 s43, s48
	s_cselect_b32 s48, s46, s78
	s_cselect_b32 s53, s5, s52
	s_cselect_b32 s52, s4, s49
	s_cselect_b32 s49, s47, s79
	v_lshl_add_u64 v[154:155], s[50:51], 0, v[138:139]
	s_add_i32 m0, s55, 0xc000
	ds_read_b128 v[190:193], v160
	ds_read_b128 v[196:199], v160 offset:1024
	ds_read_b128 v[200:203], v160 offset:2048
	ds_read_b128 v[204:207], v160 offset:3072
	ds_read_b128 v[208:211], v160 offset:4096
	ds_read_b128 v[212:215], v160 offset:5120
	ds_read_b128 v[216:219], v160 offset:6144
	ds_read_b128 v[220:223], v160 offset:7168
	global_load_lds_dwordx4 v[154:155], off
	v_lshl_add_u64 v[154:155], s[50:51], 0, v[140:141]
	s_add_i32 m0, s55, 0xe000
	s_nop 0
	global_load_lds_dwordx4 v[154:155], off
	s_nop 0
	s_waitcnt vmcnt(8)
	s_waitcnt lgkmcnt(0)
	s_barrier
	v_mfma_f32_16x16x32_bf16 v[124:127], v[150:153], v[190:193], v[124:127]
	v_mfma_f32_16x16x32_bf16 v[120:123], v[166:169], v[190:193], v[120:123]
	v_mfma_f32_16x16x32_bf16 v[108:111], v[150:153], v[200:203], v[108:111]
	v_mfma_f32_16x16x32_bf16 v[104:107], v[166:169], v[200:203], v[104:107]
	v_mfma_f32_16x16x32_bf16 v[92:95], v[150:153], v[208:211], v[92:95]
	v_mfma_f32_16x16x32_bf16 v[88:91], v[166:169], v[208:211], v[88:91]
	v_mfma_f32_16x16x32_bf16 v[76:79], v[150:153], v[216:219], v[76:79]
	v_mfma_f32_16x16x32_bf16 v[72:75], v[166:169], v[216:219], v[72:75]
	v_mfma_f32_16x16x32_bf16 v[124:127], v[162:165], v[196:199], v[124:127]
	v_mfma_f32_16x16x32_bf16 v[120:123], v[170:173], v[196:199], v[120:123]
	v_mfma_f32_16x16x32_bf16 v[108:111], v[162:165], v[204:207], v[108:111]
	v_mfma_f32_16x16x32_bf16 v[104:107], v[170:173], v[204:207], v[104:107]
	v_mfma_f32_16x16x32_bf16 v[92:95], v[162:165], v[212:215], v[92:95]
	v_mfma_f32_16x16x32_bf16 v[88:91], v[170:173], v[212:215], v[88:91]
	v_mfma_f32_16x16x32_bf16 v[76:79], v[162:165], v[220:223], v[76:79]
	v_mfma_f32_16x16x32_bf16 v[72:75], v[170:173], v[220:223], v[72:75]
	v_mfma_f32_16x16x32_bf16 v[116:119], v[174:177], v[190:193], v[116:119]
	v_mfma_f32_16x16x32_bf16 v[112:115], v[182:185], v[190:193], v[112:115]
	v_mfma_f32_16x16x32_bf16 v[100:103], v[174:177], v[200:203], v[100:103]
	v_mfma_f32_16x16x32_bf16 v[96:99], v[182:185], v[200:203], v[96:99]
	v_mfma_f32_16x16x32_bf16 v[84:87], v[174:177], v[208:211], v[84:87]
	v_mfma_f32_16x16x32_bf16 v[80:83], v[182:185], v[208:211], v[80:83]
	v_mfma_f32_16x16x32_bf16 v[68:71], v[174:177], v[216:219], v[68:71]
	v_mfma_f32_16x16x32_bf16 v[64:67], v[182:185], v[216:219], v[64:67]
	v_mfma_f32_16x16x32_bf16 v[116:119], v[178:181], v[196:199], v[116:119]
	v_mfma_f32_16x16x32_bf16 v[112:115], v[186:189], v[196:199], v[112:115]
	v_mfma_f32_16x16x32_bf16 v[100:103], v[178:181], v[204:207], v[100:103]
	v_mfma_f32_16x16x32_bf16 v[96:99], v[186:189], v[204:207], v[96:99]
	v_mfma_f32_16x16x32_bf16 v[84:87], v[178:181], v[212:215], v[84:87]
	v_mfma_f32_16x16x32_bf16 v[80:83], v[186:189], v[212:215], v[80:83]
	v_mfma_f32_16x16x32_bf16 v[68:71], v[178:181], v[220:223], v[68:71]
	v_mfma_f32_16x16x32_bf16 v[64:67], v[186:189], v[220:223], v[64:67]
	s_barrier
	s_add_i32 s81, s65, s54
	v_lshl_add_u64 v[154:155], s[48:49], 0, v[132:133]
	s_mov_b32 m0, s81
	ds_read_b128 v[190:193], v160 offset:16384
	ds_read_b128 v[196:199], v160 offset:17408
	ds_read_b128 v[200:203], v160 offset:18432
	ds_read_b128 v[204:207], v160 offset:19456
	ds_read_b128 v[208:211], v160 offset:20480
	ds_read_b128 v[212:215], v160 offset:21504
	ds_read_b128 v[216:219], v160 offset:22528
	ds_read_b128 v[220:223], v160 offset:23552
	global_load_lds_dwordx4 v[154:155], off
	s_add_i32 m0, s81, 0x2000
	s_add_u32 s82, s48, 0x2b0000
	v_lshl_add_u64 v[224:225], s[48:49], 0, v[136:137]
	s_addc_u32 s83, s49, 0
	s_add_i32 s81, s66, s54
	global_load_lds_dwordx4 v[224:225], off
	v_lshl_add_u64 v[226:227], s[82:83], 0, v[132:133]
	s_mov_b32 m0, s81
	v_lshl_add_u64 v[228:229], s[52:53], 0, v[134:135]
	global_load_lds_dwordx4 v[226:227], off
	v_lshl_add_u64 v[226:227], s[82:83], 0, v[136:137]
	s_add_i32 m0, s81, 0x2000
	s_nop 0
	global_load_lds_dwordx4 v[226:227], off
	v_lshl_add_u64 v[226:227], s[52:53], 0, v[128:129]
	s_mov_b32 m0, s55
	s_nop 0
	global_load_lds_dwordx4 v[226:227], off
	s_mov_b32 m0, s56
	s_nop 0
	global_load_lds_dwordx4 v[228:229], off
	s_waitcnt vmcnt(8)
	s_waitcnt lgkmcnt(0)
	s_barrier
	v_mfma_f32_16x16x32_bf16 v[60:63], v[150:153], v[190:193], v[60:63]
	v_mfma_f32_16x16x32_bf16 v[56:59], v[166:169], v[190:193], v[56:59]
	v_mfma_f32_16x16x32_bf16 v[44:47], v[150:153], v[200:203], v[44:47]
	v_mfma_f32_16x16x32_bf16 v[40:43], v[166:169], v[200:203], v[40:43]
	v_mfma_f32_16x16x32_bf16 v[28:31], v[150:153], v[208:211], v[28:31]
	v_mfma_f32_16x16x32_bf16 v[24:27], v[166:169], v[208:211], v[24:27]
	v_mfma_f32_16x16x32_bf16 v[12:15], v[150:153], v[216:219], v[12:15]
	v_mfma_f32_16x16x32_bf16 v[8:11], v[166:169], v[216:219], v[8:11]
	v_mfma_f32_16x16x32_bf16 v[60:63], v[162:165], v[196:199], v[60:63]
	v_mfma_f32_16x16x32_bf16 v[56:59], v[170:173], v[196:199], v[56:59]
	v_mfma_f32_16x16x32_bf16 v[44:47], v[162:165], v[204:207], v[44:47]
	v_mfma_f32_16x16x32_bf16 v[40:43], v[170:173], v[204:207], v[40:43]
	v_mfma_f32_16x16x32_bf16 v[28:31], v[162:165], v[212:215], v[28:31]
	v_mfma_f32_16x16x32_bf16 v[24:27], v[170:173], v[212:215], v[24:27]
	v_mfma_f32_16x16x32_bf16 v[12:15], v[162:165], v[220:223], v[12:15]
	v_mfma_f32_16x16x32_bf16 v[8:11], v[170:173], v[220:223], v[8:11]
	v_mfma_f32_16x16x32_bf16 v[52:55], v[174:177], v[190:193], v[52:55]
	v_mfma_f32_16x16x32_bf16 v[48:51], v[182:185], v[190:193], v[48:51]
	v_mfma_f32_16x16x32_bf16 v[36:39], v[174:177], v[200:203], v[36:39]
	v_mfma_f32_16x16x32_bf16 v[32:35], v[182:185], v[200:203], v[32:35]
	v_mfma_f32_16x16x32_bf16 v[20:23], v[174:177], v[208:211], v[20:23]
	v_mfma_f32_16x16x32_bf16 v[16:19], v[182:185], v[208:211], v[16:19]
	v_mfma_f32_16x16x32_bf16 v[4:7], v[174:177], v[216:219], v[4:7]
	v_mfma_f32_16x16x32_bf16 v[0:3], v[182:185], v[216:219], v[0:3]
	v_mfma_f32_16x16x32_bf16 v[52:55], v[178:181], v[196:199], v[52:55]
	v_mfma_f32_16x16x32_bf16 v[48:51], v[186:189], v[196:199], v[48:51]
	v_mfma_f32_16x16x32_bf16 v[36:39], v[178:181], v[204:207], v[36:39]
	v_mfma_f32_16x16x32_bf16 v[32:35], v[186:189], v[204:207], v[32:35]
	v_mfma_f32_16x16x32_bf16 v[20:23], v[178:181], v[212:215], v[20:23]
	v_mfma_f32_16x16x32_bf16 v[16:19], v[186:189], v[212:215], v[16:19]
	v_mfma_f32_16x16x32_bf16 v[4:7], v[178:181], v[220:223], v[4:7]
	v_mfma_f32_16x16x32_bf16 v[0:3], v[186:189], v[220:223], v[0:3]
	s_barrier
	s_add_i32 s81, 0, 0x18000
	v_add_u32_e32 v161, s81, v156
	s_add_i32 s82, 0, 0x1c000
	ds_read_b128 v[150:153], v161
	ds_read_b128 v[162:165], v161 offset:1024
	ds_read_b128 v[166:169], v161 offset:2048
	ds_read_b128 v[170:173], v161 offset:3072
	v_add_u32_e32 v161, s82, v156
	ds_read_b128 v[174:177], v161
	ds_read_b128 v[178:181], v161 offset:1024
	ds_read_b128 v[182:185], v161 offset:2048
	ds_read_b128 v[186:189], v161 offset:3072
	s_add_u32 s52, s52, 0x2b0000
	s_addc_u32 s53, s53, 0
	s_mov_b32 m0, s57
	v_lshl_add_u64 v[230:231], s[52:53], 0, v[128:129]
	ds_read_b128 v[190:193], v160 offset:32768
	ds_read_b128 v[196:199], v160 offset:33792
	ds_read_b128 v[200:203], v160 offset:34816
	ds_read_b128 v[204:207], v160 offset:35840
	ds_read_b128 v[208:211], v160 offset:36864
	ds_read_b128 v[212:215], v160 offset:37888
	ds_read_b128 v[216:219], v160 offset:38912
	ds_read_b128 v[220:223], v160 offset:39936
	global_load_lds_dwordx4 v[230:231], off
	v_lshl_add_u64 v[230:231], s[52:53], 0, v[134:135]
	s_mov_b32 m0, s58
	s_nop 0
	global_load_lds_dwordx4 v[230:231], off
	s_waitcnt vmcnt(8)
	s_waitcnt lgkmcnt(0)
	s_barrier
	v_mfma_f32_16x16x32_bf16 v[124:127], v[150:153], v[190:193], v[124:127]
	v_mfma_f32_16x16x32_bf16 v[120:123], v[166:169], v[190:193], v[120:123]
	v_mfma_f32_16x16x32_bf16 v[108:111], v[150:153], v[200:203], v[108:111]
	v_mfma_f32_16x16x32_bf16 v[104:107], v[166:169], v[200:203], v[104:107]
	v_mfma_f32_16x16x32_bf16 v[92:95], v[150:153], v[208:211], v[92:95]
	v_mfma_f32_16x16x32_bf16 v[88:91], v[166:169], v[208:211], v[88:91]
	v_mfma_f32_16x16x32_bf16 v[76:79], v[150:153], v[216:219], v[76:79]
	v_mfma_f32_16x16x32_bf16 v[72:75], v[166:169], v[216:219], v[72:75]
	v_mfma_f32_16x16x32_bf16 v[124:127], v[162:165], v[196:199], v[124:127]
	v_mfma_f32_16x16x32_bf16 v[120:123], v[170:173], v[196:199], v[120:123]
	v_mfma_f32_16x16x32_bf16 v[108:111], v[162:165], v[204:207], v[108:111]
	v_mfma_f32_16x16x32_bf16 v[104:107], v[170:173], v[204:207], v[104:107]
	v_mfma_f32_16x16x32_bf16 v[92:95], v[162:165], v[212:215], v[92:95]
	v_mfma_f32_16x16x32_bf16 v[88:91], v[170:173], v[212:215], v[88:91]
	v_mfma_f32_16x16x32_bf16 v[76:79], v[162:165], v[220:223], v[76:79]
	v_mfma_f32_16x16x32_bf16 v[72:75], v[170:173], v[220:223], v[72:75]
	v_mfma_f32_16x16x32_bf16 v[116:119], v[174:177], v[190:193], v[116:119]
	v_mfma_f32_16x16x32_bf16 v[112:115], v[182:185], v[190:193], v[112:115]
	v_mfma_f32_16x16x32_bf16 v[100:103], v[174:177], v[200:203], v[100:103]
	v_mfma_f32_16x16x32_bf16 v[96:99], v[182:185], v[200:203], v[96:99]
	v_mfma_f32_16x16x32_bf16 v[84:87], v[174:177], v[208:211], v[84:87]
	v_mfma_f32_16x16x32_bf16 v[80:83], v[182:185], v[208:211], v[80:83]
	v_mfma_f32_16x16x32_bf16 v[68:71], v[174:177], v[216:219], v[68:71]
	v_mfma_f32_16x16x32_bf16 v[64:67], v[182:185], v[216:219], v[64:67]
	v_mfma_f32_16x16x32_bf16 v[116:119], v[178:181], v[196:199], v[116:119]
	v_mfma_f32_16x16x32_bf16 v[112:115], v[186:189], v[196:199], v[112:115]
	v_mfma_f32_16x16x32_bf16 v[100:103], v[178:181], v[204:207], v[100:103]
	v_mfma_f32_16x16x32_bf16 v[96:99], v[186:189], v[204:207], v[96:99]
	v_mfma_f32_16x16x32_bf16 v[84:87], v[178:181], v[212:215], v[84:87]
	v_mfma_f32_16x16x32_bf16 v[80:83], v[186:189], v[212:215], v[80:83]
	v_mfma_f32_16x16x32_bf16 v[68:71], v[178:181], v[220:223], v[68:71]
	v_mfma_f32_16x16x32_bf16 v[64:67], v[186:189], v[220:223], v[64:67]
	s_barrier
	s_add_i32 s52, s81, s54
	v_lshl_add_u64 v[154:155], v[154:155], 0, s[14:15]
	s_mov_b32 m0, s52
	ds_read_b128 v[190:193], v160 offset:49152
	ds_read_b128 v[196:199], v160 offset:50176
	ds_read_b128 v[200:203], v160 offset:51200
	ds_read_b128 v[204:207], v160 offset:52224
	ds_read_b128 v[208:211], v160 offset:53248
	ds_read_b128 v[212:215], v160 offset:54272
	ds_read_b128 v[216:219], v160 offset:55296
	ds_read_b128 v[220:223], v160 offset:56320
	global_load_lds_dwordx4 v[154:155], off
	s_add_i32 m0, s52, 0x2000
	s_add_u32 s48, s48, 0x2b0080
	v_lshl_add_u64 v[154:155], v[224:225], 0, s[14:15]
	s_addc_u32 s49, s49, 0
	s_add_i32 s52, s82, s54
	global_load_lds_dwordx4 v[154:155], off
	v_lshl_add_u64 v[154:155], s[48:49], 0, v[132:133]
	s_mov_b32 m0, s52
	s_nop 0
	global_load_lds_dwordx4 v[154:155], off
	v_lshl_add_u64 v[154:155], s[48:49], 0, v[136:137]
	s_add_i32 m0, s52, 0x2000
	s_nop 0
	global_load_lds_dwordx4 v[154:155], off
	v_lshl_add_u64 v[154:155], v[226:227], 0, s[14:15]
	s_mov_b32 m0, s62
	s_nop 0
	global_load_lds_dwordx4 v[154:155], off
	v_lshl_add_u64 v[154:155], v[228:229], 0, s[14:15]
	s_mov_b32 m0, s63
	s_nop 0
	global_load_lds_dwordx4 v[154:155], off
	s_nop 0
	s_waitcnt vmcnt(8)
	s_waitcnt lgkmcnt(0)
	s_barrier
	v_mfma_f32_16x16x32_bf16 v[60:63], v[150:153], v[190:193], v[60:63]
	v_mfma_f32_16x16x32_bf16 v[56:59], v[166:169], v[190:193], v[56:59]
	v_mfma_f32_16x16x32_bf16 v[44:47], v[150:153], v[200:203], v[44:47]
	v_mfma_f32_16x16x32_bf16 v[40:43], v[166:169], v[200:203], v[40:43]
	v_mfma_f32_16x16x32_bf16 v[28:31], v[150:153], v[208:211], v[28:31]
	v_mfma_f32_16x16x32_bf16 v[24:27], v[166:169], v[208:211], v[24:27]
	v_mfma_f32_16x16x32_bf16 v[12:15], v[150:153], v[216:219], v[12:15]
	v_mfma_f32_16x16x32_bf16 v[8:11], v[166:169], v[216:219], v[8:11]
	v_mfma_f32_16x16x32_bf16 v[60:63], v[162:165], v[196:199], v[60:63]
	v_mfma_f32_16x16x32_bf16 v[56:59], v[170:173], v[196:199], v[56:59]
	v_mfma_f32_16x16x32_bf16 v[44:47], v[162:165], v[204:207], v[44:47]
	v_mfma_f32_16x16x32_bf16 v[40:43], v[170:173], v[204:207], v[40:43]
	v_mfma_f32_16x16x32_bf16 v[28:31], v[162:165], v[212:215], v[28:31]
	v_mfma_f32_16x16x32_bf16 v[24:27], v[170:173], v[212:215], v[24:27]
	v_mfma_f32_16x16x32_bf16 v[12:15], v[162:165], v[220:223], v[12:15]
	v_mfma_f32_16x16x32_bf16 v[8:11], v[170:173], v[220:223], v[8:11]
	v_mfma_f32_16x16x32_bf16 v[52:55], v[174:177], v[190:193], v[52:55]
	v_mfma_f32_16x16x32_bf16 v[48:51], v[182:185], v[190:193], v[48:51]
	v_mfma_f32_16x16x32_bf16 v[36:39], v[174:177], v[200:203], v[36:39]
	v_mfma_f32_16x16x32_bf16 v[32:35], v[182:185], v[200:203], v[32:35]
	v_mfma_f32_16x16x32_bf16 v[20:23], v[174:177], v[208:211], v[20:23]
	v_mfma_f32_16x16x32_bf16 v[16:19], v[182:185], v[208:211], v[16:19]
	v_mfma_f32_16x16x32_bf16 v[4:7], v[174:177], v[216:219], v[4:7]
	v_mfma_f32_16x16x32_bf16 v[0:3], v[182:185], v[216:219], v[0:3]
	v_mfma_f32_16x16x32_bf16 v[52:55], v[178:181], v[196:199], v[52:55]
	v_mfma_f32_16x16x32_bf16 v[48:51], v[186:189], v[196:199], v[48:51]
	v_mfma_f32_16x16x32_bf16 v[36:39], v[178:181], v[204:207], v[36:39]
	v_mfma_f32_16x16x32_bf16 v[32:35], v[186:189], v[204:207], v[32:35]
	v_mfma_f32_16x16x32_bf16 v[20:23], v[178:181], v[212:215], v[20:23]
	v_mfma_f32_16x16x32_bf16 v[16:19], v[186:189], v[212:215], v[16:19]
	v_mfma_f32_16x16x32_bf16 v[4:7], v[178:181], v[220:223], v[4:7]
	v_mfma_f32_16x16x32_bf16 v[0:3], v[186:189], v[220:223], v[0:3]
	s_barrier
	s_add_u32 s50, s50, 0x100
	s_addc_u32 s51, s51, 0
	s_add_u32 s78, s78, 0x100
	s_addc_u32 s79, s79, 0
	s_cmp_ge_i32 s80, s76
	s_mov_b32 s48, s80
	s_cbranch_scc0 .LBB0_4304
	s_and_b64 vcc, exec, s[16:17]
	s_cbranch_vccz .LBB0_4307
	s_barrier
